# peer top-k: intermediate top-16 lists stored round-major in LDS (conflict-free lane-consecutive accesses)
# speedup vs baseline: 1.0375x; 1.0050x over previous
; #define MFMA(a, b, c) __builtin_amdgcn_mfma_f32_32x32x16_bf16((a), (b), (c), 0, 0, 0)
; DI int crow(int i, int h) { return (i & 3) + 8 * (i >> 2) + 4 * h; }
; DI f32x16 zero16() { f32x16 z; for (int i = 0; i < 16; ++i) z[i] = 0.f; return z; }
; DI void peer_topk_item(const Params& p, int tt128, int head, char* smem) {
;     ...
;   {
;     const int half = wave >> 2, kt = wave & 3;
;     bf16x8 af[8];
; #pragma unroll
;     for (int ks = 0; ks < 8; ++ks) af[ks] = ldg8(sk + (size_t)half * 16384 + (kt * 32 + lr) * 128 + ks * 16 + lh * 8);
; #pragma unroll 1
;     for (int tt = 0; tt < 4; ++tt) {
;       f32x16 acc = zero16();
;       const u16* brow = pq + (((((size_t)(tok0 >> 5) + tt) * 8 + head) * 2 + half) * 8) * 512 + lane * 8;
; #pragma unroll
;       for (int ks = 0; ks < 8; ++ks) acc = MFMA(af[ks], ldg8(brow + ks * 512), acc);
; #pragma unroll
;       for (int i = 0; i < 16; ++i) sc[(half * 128 + tt * 32 + lr) * 129 + kt * 32 + crow(i, lh)] = acc[i];
;     }
;   }
.LBB0_964:
	s_mov_b32 s4, 0x16800000
	s_mov_b32 s5, 0
	s_mov_b64 s[8:9], 0x20000
	v_lshl_add_u64 v[142:143], v[52:53], 0, s[4:5]
	s_movk_i32 s10, 0x1000
	s_mov_b32 s11, 0
	v_lshl_add_u64 v[144:145], v[142:143], 0, s[10:11]
	v_lshl_add_u64 v[146:147], v[142:143], 0, s[8:9]
	v_lshl_add_u64 v[148:149], v[144:145], 0, s[8:9]
	v_lshl_add_u64 v[150:151], v[146:147], 0, s[8:9]
	v_lshl_add_u64 v[152:153], v[148:149], 0, s[8:9]
	v_lshl_add_u64 v[154:155], v[150:151], 0, s[8:9]
	v_lshl_add_u64 v[156:157], v[152:153], 0, s[8:9]
	s_waitcnt vmcnt(7)
	v_mfma_f32_32x32x16_bf16 v[0:15], v[16:19], v[168:171], 0
	global_load_dwordx4 v[168:171], v[150:151], off
	s_waitcnt vmcnt(7)
	v_mfma_f32_32x32x16_bf16 v[0:15], v[20:23], v[172:175], v[0:15]
	global_load_dwordx4 v[172:175], v[150:151], off offset:1024
	s_waitcnt vmcnt(7)
	v_mfma_f32_32x32x16_bf16 v[0:15], v[24:27], v[176:179], v[0:15]
	global_load_dwordx4 v[176:179], v[150:151], off offset:2048
	s_waitcnt vmcnt(7)
	v_mfma_f32_32x32x16_bf16 v[0:15], v[28:31], v[180:183], v[0:15]
	global_load_dwordx4 v[180:183], v[150:151], off offset:3072
	s_waitcnt vmcnt(7)
	v_mfma_f32_32x32x16_bf16 v[0:15], v[32:35], v[184:187], v[0:15]
	global_load_dwordx4 v[184:187], v[152:153], off
	s_waitcnt vmcnt(7)
	v_mfma_f32_32x32x16_bf16 v[0:15], v[36:39], v[188:191], v[0:15]
	global_load_dwordx4 v[188:191], v[152:153], off offset:1024
	s_waitcnt vmcnt(7)
	v_mfma_f32_32x32x16_bf16 v[0:15], v[40:43], v[192:195], v[0:15]
	global_load_dwordx4 v[192:195], v[152:153], off offset:2048
	s_waitcnt vmcnt(7)
	v_mfma_f32_32x32x16_bf16 v[0:15], v[44:47], v[196:199], v[0:15]
	global_load_dwordx4 v[196:199], v[152:153], off offset:3072
	s_nop 11
	ds_write2_b32 v124, v0, v1 offset1:1
	ds_write2_b32 v124, v2, v3 offset0:2 offset1:3
	ds_write2_b32 v124, v4, v5 offset0:8 offset1:9
	ds_write2_b32 v124, v6, v7 offset0:10 offset1:11
	ds_write2_b32 v124, v8, v9 offset0:16 offset1:17
	ds_write2_b32 v124, v10, v11 offset0:18 offset1:19
	ds_write2_b32 v124, v12, v13 offset0:24 offset1:25
	ds_write2_b32 v124, v14, v15 offset0:26 offset1:27
	v_add_u32_e32 v124, 0x4080, v124
	s_waitcnt vmcnt(15)
	v_mfma_f32_32x32x16_bf16 v[0:15], v[16:19], v[200:203], 0
	global_load_dwordx4 v[200:203], v[154:155], off
	s_waitcnt vmcnt(15)
	v_mfma_f32_32x32x16_bf16 v[0:15], v[20:23], v[204:207], v[0:15]
	global_load_dwordx4 v[204:207], v[154:155], off offset:1024
	s_waitcnt vmcnt(15)
	v_mfma_f32_32x32x16_bf16 v[0:15], v[24:27], v[208:211], v[0:15]
	global_load_dwordx4 v[208:211], v[154:155], off offset:2048
	s_waitcnt vmcnt(15)
	v_mfma_f32_32x32x16_bf16 v[0:15], v[28:31], v[212:215], v[0:15]
	global_load_dwordx4 v[212:215], v[154:155], off offset:3072
	s_waitcnt vmcnt(15)
	v_mfma_f32_32x32x16_bf16 v[0:15], v[32:35], v[216:219], v[0:15]
	global_load_dwordx4 v[216:219], v[156:157], off
	s_waitcnt vmcnt(15)
	v_mfma_f32_32x32x16_bf16 v[0:15], v[36:39], v[220:223], v[0:15]
	global_load_dwordx4 v[220:223], v[156:157], off offset:1024
	s_waitcnt vmcnt(15)
	v_mfma_f32_32x32x16_bf16 v[0:15], v[40:43], v[224:227], v[0:15]
	global_load_dwordx4 v[224:227], v[156:157], off offset:2048
	s_waitcnt vmcnt(15)
	v_mfma_f32_32x32x16_bf16 v[0:15], v[44:47], v[228:231], v[0:15]
	global_load_dwordx4 v[228:231], v[156:157], off offset:3072
	s_nop 11
	ds_write2_b32 v124, v0, v1 offset1:1
	ds_write2_b32 v124, v2, v3 offset0:2 offset1:3
	ds_write2_b32 v124, v4, v5 offset0:8 offset1:9
	ds_write2_b32 v124, v6, v7 offset0:10 offset1:11
	ds_write2_b32 v124, v8, v9 offset0:16 offset1:17
	ds_write2_b32 v124, v10, v11 offset0:18 offset1:19
	ds_write2_b32 v124, v12, v13 offset0:24 offset1:25
	ds_write2_b32 v124, v14, v15 offset0:26 offset1:27
	v_add_u32_e32 v124, 0x4080, v124
	s_waitcnt vmcnt(15)
	v_mfma_f32_32x32x16_bf16 v[0:15], v[16:19], v[168:171], 0
	s_waitcnt vmcnt(14)
	v_mfma_f32_32x32x16_bf16 v[0:15], v[20:23], v[172:175], v[0:15]
	s_waitcnt vmcnt(13)
	v_mfma_f32_32x32x16_bf16 v[0:15], v[24:27], v[176:179], v[0:15]
	s_waitcnt vmcnt(12)
	v_mfma_f32_32x32x16_bf16 v[0:15], v[28:31], v[180:183], v[0:15]
	s_waitcnt vmcnt(11)
	v_mfma_f32_32x32x16_bf16 v[0:15], v[32:35], v[184:187], v[0:15]
	s_waitcnt vmcnt(10)
	v_mfma_f32_32x32x16_bf16 v[0:15], v[36:39], v[188:191], v[0:15]
	s_waitcnt vmcnt(9)
	v_mfma_f32_32x32x16_bf16 v[0:15], v[40:43], v[192:195], v[0:15]
	s_waitcnt vmcnt(8)
	v_mfma_f32_32x32x16_bf16 v[0:15], v[44:47], v[196:199], v[0:15]
	s_nop 11
	ds_write2_b32 v124, v0, v1 offset1:1
	ds_write2_b32 v124, v2, v3 offset0:2 offset1:3
	ds_write2_b32 v124, v4, v5 offset0:8 offset1:9
	ds_write2_b32 v124, v6, v7 offset0:10 offset1:11
	ds_write2_b32 v124, v8, v9 offset0:16 offset1:17
	ds_write2_b32 v124, v10, v11 offset0:18 offset1:19
	ds_write2_b32 v124, v12, v13 offset0:24 offset1:25
	ds_write2_b32 v124, v14, v15 offset0:26 offset1:27
	v_add_u32_e32 v124, 0x4080, v124
	s_waitcnt vmcnt(7)
	v_mfma_f32_32x32x16_bf16 v[0:15], v[16:19], v[200:203], 0
	s_waitcnt vmcnt(6)
	v_mfma_f32_32x32x16_bf16 v[0:15], v[20:23], v[204:207], v[0:15]
	s_waitcnt vmcnt(5)
	v_mfma_f32_32x32x16_bf16 v[0:15], v[24:27], v[208:211], v[0:15]
	s_waitcnt vmcnt(4)
	v_mfma_f32_32x32x16_bf16 v[0:15], v[28:31], v[212:215], v[0:15]
	s_waitcnt vmcnt(3)
	v_mfma_f32_32x32x16_bf16 v[0:15], v[32:35], v[216:219], v[0:15]
	s_waitcnt vmcnt(2)
	v_mfma_f32_32x32x16_bf16 v[0:15], v[36:39], v[220:223], v[0:15]
	s_waitcnt vmcnt(1)
	v_mfma_f32_32x32x16_bf16 v[0:15], v[40:43], v[224:227], v[0:15]
	s_waitcnt vmcnt(0)
; #define MFMA(a, b, c) __builtin_amdgcn_mfma_f32_32x32x16_bf16((a), (b), (c), 0, 0, 0)
; DI int crow(int i, int h) { return (i & 3) + 8 * (i >> 2) + 4 * h; }
; DI f32x16 zero16() { f32x16 z; for (int i = 0; i < 16; ++i) z[i] = 0.f; return z; }
; DI void peer_topk_item(const Params& p, int tt128, int head, char* smem) {
;     ...
;     for (int tt = 0; tt < 4; ++tt) {
;       f32x16 acc = zero16();
;       const u16* brow = pq + (((((size_t)(tok0 >> 5) + tt) * 8 + head) * 2 + half) * 8) * 512 + lane * 8;
; #pragma unroll
;       for (int ks = 0; ks < 8; ++ks) acc = MFMA(af[ks], ldg8(brow + ks * 512), acc);
; #pragma unroll
;       for (int i = 0; i < 16; ++i) sc[(half * 128 + tt * 32 + lr) * 129 + kt * 32 + crow(i, lh)] = acc[i];
;     }
;   }
;   __syncthreads();
;   if (tid < 256) {
;     float* row = sc + tid * 129;
;     float gm[8]; int gi[8];
; #pragma unroll
;     for (int g = 0; g < 8; ++g) {
;       float m = -INFINITY; int mi = g * 16;
; #pragma unroll
;       for (int j = 0; j < 16; ++j) { float v = row[g * 16 + j]; if (v > m) { m = v; mi = g * 16 + j; } }
;       gm[g] = m; gi[g] = mi;
	v_mfma_f32_32x32x16_bf16 v[0:15], v[44:47], v[228:231], v[0:15]
	s_nop 11
	ds_write2_b32 v124, v0, v1 offset1:1
	ds_write2_b32 v124, v2, v3 offset0:2 offset1:3
	ds_write2_b32 v124, v4, v5 offset0:8 offset1:9
	ds_write2_b32 v124, v6, v7 offset0:10 offset1:11
	ds_write2_b32 v124, v8, v9 offset0:16 offset1:17
	ds_write2_b32 v124, v10, v11 offset0:18 offset1:19
	ds_write2_b32 v124, v12, v13 offset0:24 offset1:25
	ds_write2_b32 v124, v14, v15 offset0:26 offset1:27
	v_add_u32_e32 v124, 0x4080, v124
	s_add_i32 s12, s2, s78
	s_add_i32 s13, s3, s78
	s_cmpk_gt_i32 s12, 0x7ff
	s_cselect_b32 s12, s2, s12
	s_cselect_b32 s13, s3, s13
	s_and_b32 s0, s13, 7
	s_ashr_i32 s10, s12, 3
	s_lshl_b32 s4, s0, 14
	s_lshl_b32 s0, s10, 2
	s_ashr_i32 s1, s0, 31
	s_lshl_b64 s[0:1], s[0:1], 17
	s_or_b32 s0, s0, s4
	v_lshl_add_u64 v[142:143], v[50:51], 0, s[0:1]
	s_mov_b32 s4, 0x16800000
	s_mov_b32 s5, 0
	s_mov_b64 s[8:9], 0x20000
	v_lshl_add_u64 v[142:143], v[142:143], 0, s[4:5]
	s_movk_i32 s10, 0x1000
	s_mov_b32 s11, 0
	v_lshl_add_u64 v[144:145], v[142:143], 0, s[10:11]
	v_lshl_add_u64 v[146:147], v[142:143], 0, s[8:9]
	v_lshl_add_u64 v[148:149], v[144:145], 0, s[8:9]
	global_load_dwordx4 v[168:171], v[142:143], off
	global_load_dwordx4 v[172:175], v[142:143], off offset:1024
	global_load_dwordx4 v[176:179], v[142:143], off offset:2048
	global_load_dwordx4 v[180:183], v[142:143], off offset:3072
	global_load_dwordx4 v[184:187], v[144:145], off
	global_load_dwordx4 v[188:191], v[144:145], off offset:1024
	global_load_dwordx4 v[192:195], v[144:145], off offset:2048
	global_load_dwordx4 v[196:199], v[144:145], off offset:3072
	global_load_dwordx4 v[200:203], v[146:147], off
	global_load_dwordx4 v[204:207], v[146:147], off offset:1024
	global_load_dwordx4 v[208:211], v[146:147], off offset:2048
	global_load_dwordx4 v[212:215], v[146:147], off offset:3072
	global_load_dwordx4 v[216:219], v[148:149], off
	global_load_dwordx4 v[220:223], v[148:149], off offset:1024
	global_load_dwordx4 v[224:227], v[148:149], off offset:2048
	global_load_dwordx4 v[228:231], v[148:149], off offset:3072
	s_mov_b64 s[0:1], 0x80000
	s_waitcnt lgkmcnt(0)
	s_barrier
	s_mov_b64 s[52:53], exec
	v_readlane_b32 s0, v255, 45
	v_readlane_b32 s1, v255, 46
	s_and_b64 s[0:1], s[52:53], s[0:1]
	s_mov_b64 exec, s[0:1]
	s_cbranch_execz .LBB0_968
	v_lshlrev_b32_e32 v149, 2, v166
	v_add_u32_e32 v150, 0x24400, v166
	v_add_u32_e32 v149, 0x20400, v149
	ds_read2_b32 v[16:17], v54 offset0:0 offset1:1
	ds_read2_b32 v[18:19], v54 offset0:2 offset1:3
	ds_read2_b32 v[20:21], v54 offset0:4 offset1:5
	ds_read2_b32 v[22:23], v54 offset0:6 offset1:7
	ds_read2_b32 v[24:25], v54 offset0:8 offset1:9
	ds_read2_b32 v[26:27], v54 offset0:10 offset1:11
	ds_read2_b32 v[28:29], v54 offset0:12 offset1:13
	ds_read2_b32 v[30:31], v54 offset0:14 offset1:15
	ds_read2_b32 v[124:125], v54 offset0:16 offset1:17
	ds_read2_b32 v[126:127], v54 offset0:18 offset1:19
	ds_read2_b32 v[128:129], v54 offset0:20 offset1:21
	ds_read2_b32 v[130:131], v54 offset0:22 offset1:23
	ds_read2_b32 v[132:133], v54 offset0:24 offset1:25
	ds_read2_b32 v[134:135], v54 offset0:26 offset1:27
	ds_read2_b32 v[136:137], v54 offset0:28 offset1:29
	ds_read2_b32 v[138:139], v54 offset0:30 offset1:31
	s_waitcnt lgkmcnt(8)
	v_cmp_gt_f32_e64 s[8:9], v17, v16
	v_cmp_gt_f32_e64 s[10:11], v19, v18
	v_cmp_gt_f32_e64 s[12:13], v21, v20
	v_cmp_gt_f32_e64 s[24:25], v23, v22
	v_cmp_gt_f32_e64 s[26:27], v25, v24
	v_cmp_gt_f32_e64 s[28:29], v27, v26
	v_cmp_gt_f32_e64 s[30:31], v29, v28
	v_cmp_gt_f32_e64 s[34:35], v31, v30
	v_cndmask_b32_e64 v16, v16, v17, s[8:9]
	v_cndmask_b32_e64 v32, 0, 1, s[8:9]
	v_cndmask_b32_e64 v18, v18, v19, s[10:11]
	v_cndmask_b32_e64 v33, 2, 3, s[10:11]
	v_cndmask_b32_e64 v20, v20, v21, s[12:13]
	v_cndmask_b32_e64 v34, 4, 5, s[12:13]
	v_cndmask_b32_e64 v22, v22, v23, s[24:25]
	v_cndmask_b32_e64 v35, 6, 7, s[24:25]
	v_cndmask_b32_e64 v24, v24, v25, s[26:27]
	v_cndmask_b32_e64 v36, 8, 9, s[26:27]
	v_cndmask_b32_e64 v26, v26, v27, s[28:29]
	v_cndmask_b32_e64 v37, 10, 11, s[28:29]
	v_cndmask_b32_e64 v28, v28, v29, s[30:31]
	v_cndmask_b32_e64 v38, 12, 13, s[30:31]
	v_cndmask_b32_e64 v30, v30, v31, s[34:35]
	v_cndmask_b32_e64 v39, 14, 15, s[34:35]
	v_cmp_gt_f32_e64 s[8:9], v18, v16
	v_cmp_gt_f32_e64 s[10:11], v22, v20
	v_cmp_gt_f32_e64 s[12:13], v26, v24
	v_cmp_gt_f32_e64 s[24:25], v30, v28
	v_cndmask_b32_e64 v16, v16, v18, s[8:9]
	v_cndmask_b32_e64 v32, v32, v33, s[8:9]
	v_cndmask_b32_e64 v20, v20, v22, s[10:11]
	v_cndmask_b32_e64 v34, v34, v35, s[10:11]
	v_cndmask_b32_e64 v24, v24, v26, s[12:13]
	v_cndmask_b32_e64 v36, v36, v37, s[12:13]
	v_cndmask_b32_e64 v28, v28, v30, s[24:25]
	v_cndmask_b32_e64 v38, v38, v39, s[24:25]
	v_cmp_gt_f32_e64 s[8:9], v20, v16
	v_cmp_gt_f32_e64 s[10:11], v28, v24
	s_nop 0
	v_cndmask_b32_e64 v16, v16, v20, s[8:9]
	v_cndmask_b32_e64 v32, v32, v34, s[8:9]
	v_cndmask_b32_e64 v24, v24, v28, s[10:11]
	v_cndmask_b32_e64 v36, v36, v38, s[10:11]
	v_cmp_gt_f32_e64 s[8:9], v24, v16
	s_nop 1
	v_cndmask_b32_e64 v16, v16, v24, s[8:9]
	v_cndmask_b32_e64 v32, v32, v36, s[8:9]
	v_mov_b32_e32 v0, v16
	v_mov_b32_e32 v8, v32
	ds_read2_b32 v[16:17], v54 offset0:32 offset1:33
	ds_read2_b32 v[18:19], v54 offset0:34 offset1:35
	ds_read2_b32 v[20:21], v54 offset0:36 offset1:37
	ds_read2_b32 v[22:23], v54 offset0:38 offset1:39
	ds_read2_b32 v[24:25], v54 offset0:40 offset1:41
	ds_read2_b32 v[26:27], v54 offset0:42 offset1:43
	ds_read2_b32 v[28:29], v54 offset0:44 offset1:45
	ds_read2_b32 v[30:31], v54 offset0:46 offset1:47
	s_waitcnt lgkmcnt(8)
; DI void peer_topk_item(const Params& p, int tt128, int head, char* smem) {
;     ...
; #pragma unroll
;     for (int g = 0; g < 8; ++g) {
;       float m = -INFINITY; int mi = g * 16;
; #pragma unroll
;       for (int j = 0; j < 16; ++j) { float v = row[g * 16 + j]; if (v > m) { m = v; mi = g * 16 + j; } }
;       gm[g] = m; gi[g] = mi;
	v_cmp_gt_f32_e64 s[8:9], v125, v124
	v_cmp_gt_f32_e64 s[10:11], v127, v126
	v_cmp_gt_f32_e64 s[12:13], v129, v128
	v_cmp_gt_f32_e64 s[24:25], v131, v130
	v_cmp_gt_f32_e64 s[26:27], v133, v132
	v_cmp_gt_f32_e64 s[28:29], v135, v134
	v_cmp_gt_f32_e64 s[30:31], v137, v136
	v_cmp_gt_f32_e64 s[34:35], v139, v138
	v_cndmask_b32_e64 v124, v124, v125, s[8:9]
	v_cndmask_b32_e64 v32, 0, 1, s[8:9]
	v_cndmask_b32_e64 v126, v126, v127, s[10:11]
	v_cndmask_b32_e64 v33, 2, 3, s[10:11]
	v_cndmask_b32_e64 v128, v128, v129, s[12:13]
	v_cndmask_b32_e64 v34, 4, 5, s[12:13]
	v_cndmask_b32_e64 v130, v130, v131, s[24:25]
	v_cndmask_b32_e64 v35, 6, 7, s[24:25]
	v_cndmask_b32_e64 v132, v132, v133, s[26:27]
	v_cndmask_b32_e64 v36, 8, 9, s[26:27]
	v_cndmask_b32_e64 v134, v134, v135, s[28:29]
	v_cndmask_b32_e64 v37, 10, 11, s[28:29]
	v_cndmask_b32_e64 v136, v136, v137, s[30:31]
	v_cndmask_b32_e64 v38, 12, 13, s[30:31]
	v_cndmask_b32_e64 v138, v138, v139, s[34:35]
	v_cndmask_b32_e64 v39, 14, 15, s[34:35]
	v_cmp_gt_f32_e64 s[8:9], v126, v124
	v_cmp_gt_f32_e64 s[10:11], v130, v128
	v_cmp_gt_f32_e64 s[12:13], v134, v132
	v_cmp_gt_f32_e64 s[24:25], v138, v136
	v_cndmask_b32_e64 v124, v124, v126, s[8:9]
	v_cndmask_b32_e64 v32, v32, v33, s[8:9]
	v_cndmask_b32_e64 v128, v128, v130, s[10:11]
	v_cndmask_b32_e64 v34, v34, v35, s[10:11]
	v_cndmask_b32_e64 v132, v132, v134, s[12:13]
	v_cndmask_b32_e64 v36, v36, v37, s[12:13]
	v_cndmask_b32_e64 v136, v136, v138, s[24:25]
	v_cndmask_b32_e64 v38, v38, v39, s[24:25]
	v_cmp_gt_f32_e64 s[8:9], v128, v124
	v_cmp_gt_f32_e64 s[10:11], v136, v132
	s_nop 0
	v_cndmask_b32_e64 v124, v124, v128, s[8:9]
	v_cndmask_b32_e64 v32, v32, v34, s[8:9]
	v_cndmask_b32_e64 v132, v132, v136, s[10:11]
	v_cndmask_b32_e64 v36, v36, v38, s[10:11]
	v_cmp_gt_f32_e64 s[8:9], v132, v124
	s_nop 1
	v_cndmask_b32_e64 v124, v124, v132, s[8:9]
	v_cndmask_b32_e64 v32, v32, v36, s[8:9]
	v_mov_b32_e32 v1, v124
	v_add_u32_e32 v9, 16, v32
	ds_read2_b32 v[124:125], v54 offset0:48 offset1:49
	ds_read2_b32 v[126:127], v54 offset0:50 offset1:51
	ds_read2_b32 v[128:129], v54 offset0:52 offset1:53
	ds_read2_b32 v[130:131], v54 offset0:54 offset1:55
	ds_read2_b32 v[132:133], v54 offset0:56 offset1:57
	ds_read2_b32 v[134:135], v54 offset0:58 offset1:59
	ds_read2_b32 v[136:137], v54 offset0:60 offset1:61
	ds_read2_b32 v[138:139], v54 offset0:62 offset1:63
	s_waitcnt lgkmcnt(8)
	v_cmp_gt_f32_e64 s[8:9], v17, v16
	v_cmp_gt_f32_e64 s[10:11], v19, v18
	v_cmp_gt_f32_e64 s[12:13], v21, v20
	v_cmp_gt_f32_e64 s[24:25], v23, v22
	v_cmp_gt_f32_e64 s[26:27], v25, v24
	v_cmp_gt_f32_e64 s[28:29], v27, v26
	v_cmp_gt_f32_e64 s[30:31], v29, v28
	v_cmp_gt_f32_e64 s[34:35], v31, v30
	v_cndmask_b32_e64 v16, v16, v17, s[8:9]
	v_cndmask_b32_e64 v32, 0, 1, s[8:9]
	v_cndmask_b32_e64 v18, v18, v19, s[10:11]
	v_cndmask_b32_e64 v33, 2, 3, s[10:11]
	v_cndmask_b32_e64 v20, v20, v21, s[12:13]
	v_cndmask_b32_e64 v34, 4, 5, s[12:13]
	v_cndmask_b32_e64 v22, v22, v23, s[24:25]
	v_cndmask_b32_e64 v35, 6, 7, s[24:25]
	v_cndmask_b32_e64 v24, v24, v25, s[26:27]
	v_cndmask_b32_e64 v36, 8, 9, s[26:27]
	v_cndmask_b32_e64 v26, v26, v27, s[28:29]
	v_cndmask_b32_e64 v37, 10, 11, s[28:29]
	v_cndmask_b32_e64 v28, v28, v29, s[30:31]
	v_cndmask_b32_e64 v38, 12, 13, s[30:31]
	v_cndmask_b32_e64 v30, v30, v31, s[34:35]
	v_cndmask_b32_e64 v39, 14, 15, s[34:35]
	v_cmp_gt_f32_e64 s[8:9], v18, v16
	v_cmp_gt_f32_e64 s[10:11], v22, v20
	v_cmp_gt_f32_e64 s[12:13], v26, v24
	v_cmp_gt_f32_e64 s[24:25], v30, v28
	v_cndmask_b32_e64 v16, v16, v18, s[8:9]
	v_cndmask_b32_e64 v32, v32, v33, s[8:9]
	v_cndmask_b32_e64 v20, v20, v22, s[10:11]
	v_cndmask_b32_e64 v34, v34, v35, s[10:11]
	v_cndmask_b32_e64 v24, v24, v26, s[12:13]
	v_cndmask_b32_e64 v36, v36, v37, s[12:13]
	v_cndmask_b32_e64 v28, v28, v30, s[24:25]
	v_cndmask_b32_e64 v38, v38, v39, s[24:25]
	v_cmp_gt_f32_e64 s[8:9], v20, v16
	v_cmp_gt_f32_e64 s[10:11], v28, v24
	s_nop 0
	v_cndmask_b32_e64 v16, v16, v20, s[8:9]
	v_cndmask_b32_e64 v32, v32, v34, s[8:9]
	v_cndmask_b32_e64 v24, v24, v28, s[10:11]
	v_cndmask_b32_e64 v36, v36, v38, s[10:11]
	v_cmp_gt_f32_e64 s[8:9], v24, v16
	s_nop 1
	v_cndmask_b32_e64 v16, v16, v24, s[8:9]
	v_cndmask_b32_e64 v32, v32, v36, s[8:9]
	v_mov_b32_e32 v2, v16
	v_add_u32_e32 v10, 32, v32
	ds_read2_b32 v[16:17], v54 offset0:64 offset1:65
	ds_read2_b32 v[18:19], v54 offset0:66 offset1:67
	ds_read2_b32 v[20:21], v54 offset0:68 offset1:69
	ds_read2_b32 v[22:23], v54 offset0:70 offset1:71
	ds_read2_b32 v[24:25], v54 offset0:72 offset1:73
	ds_read2_b32 v[26:27], v54 offset0:74 offset1:75
	ds_read2_b32 v[28:29], v54 offset0:76 offset1:77
	ds_read2_b32 v[30:31], v54 offset0:78 offset1:79
	s_waitcnt lgkmcnt(8)
; DI void peer_topk_item(const Params& p, int tt128, int head, char* smem) {
;     ...
; #pragma unroll
;     for (int g = 0; g < 8; ++g) {
;       float m = -INFINITY; int mi = g * 16;
; #pragma unroll
;       for (int j = 0; j < 16; ++j) { float v = row[g * 16 + j]; if (v > m) { m = v; mi = g * 16 + j; } }
;       gm[g] = m; gi[g] = mi;
	v_cmp_gt_f32_e64 s[8:9], v125, v124
	v_cmp_gt_f32_e64 s[10:11], v127, v126
	v_cmp_gt_f32_e64 s[12:13], v129, v128
	v_cmp_gt_f32_e64 s[24:25], v131, v130
	v_cmp_gt_f32_e64 s[26:27], v133, v132
	v_cmp_gt_f32_e64 s[28:29], v135, v134
	v_cmp_gt_f32_e64 s[30:31], v137, v136
	v_cmp_gt_f32_e64 s[34:35], v139, v138
	v_cndmask_b32_e64 v124, v124, v125, s[8:9]
	v_cndmask_b32_e64 v32, 0, 1, s[8:9]
	v_cndmask_b32_e64 v126, v126, v127, s[10:11]
	v_cndmask_b32_e64 v33, 2, 3, s[10:11]
	v_cndmask_b32_e64 v128, v128, v129, s[12:13]
	v_cndmask_b32_e64 v34, 4, 5, s[12:13]
	v_cndmask_b32_e64 v130, v130, v131, s[24:25]
	v_cndmask_b32_e64 v35, 6, 7, s[24:25]
	v_cndmask_b32_e64 v132, v132, v133, s[26:27]
	v_cndmask_b32_e64 v36, 8, 9, s[26:27]
	v_cndmask_b32_e64 v134, v134, v135, s[28:29]
	v_cndmask_b32_e64 v37, 10, 11, s[28:29]
	v_cndmask_b32_e64 v136, v136, v137, s[30:31]
	v_cndmask_b32_e64 v38, 12, 13, s[30:31]
	v_cndmask_b32_e64 v138, v138, v139, s[34:35]
	v_cndmask_b32_e64 v39, 14, 15, s[34:35]
	v_cmp_gt_f32_e64 s[8:9], v126, v124
	v_cmp_gt_f32_e64 s[10:11], v130, v128
	v_cmp_gt_f32_e64 s[12:13], v134, v132
	v_cmp_gt_f32_e64 s[24:25], v138, v136
	v_cndmask_b32_e64 v124, v124, v126, s[8:9]
	v_cndmask_b32_e64 v32, v32, v33, s[8:9]
	v_cndmask_b32_e64 v128, v128, v130, s[10:11]
	v_cndmask_b32_e64 v34, v34, v35, s[10:11]
	v_cndmask_b32_e64 v132, v132, v134, s[12:13]
	v_cndmask_b32_e64 v36, v36, v37, s[12:13]
	v_cndmask_b32_e64 v136, v136, v138, s[24:25]
	v_cndmask_b32_e64 v38, v38, v39, s[24:25]
	v_cmp_gt_f32_e64 s[8:9], v128, v124
	v_cmp_gt_f32_e64 s[10:11], v136, v132
	s_nop 0
	v_cndmask_b32_e64 v124, v124, v128, s[8:9]
	v_cndmask_b32_e64 v32, v32, v34, s[8:9]
	v_cndmask_b32_e64 v132, v132, v136, s[10:11]
	v_cndmask_b32_e64 v36, v36, v38, s[10:11]
	v_cmp_gt_f32_e64 s[8:9], v132, v124
	s_nop 1
	v_cndmask_b32_e64 v124, v124, v132, s[8:9]
	v_cndmask_b32_e64 v32, v32, v36, s[8:9]
	v_mov_b32_e32 v3, v124
	v_add_u32_e32 v11, 48, v32
	ds_read2_b32 v[124:125], v54 offset0:80 offset1:81
	ds_read2_b32 v[126:127], v54 offset0:82 offset1:83
	ds_read2_b32 v[128:129], v54 offset0:84 offset1:85
	ds_read2_b32 v[130:131], v54 offset0:86 offset1:87
	ds_read2_b32 v[132:133], v54 offset0:88 offset1:89
	ds_read2_b32 v[134:135], v54 offset0:90 offset1:91
	ds_read2_b32 v[136:137], v54 offset0:92 offset1:93
	ds_read2_b32 v[138:139], v54 offset0:94 offset1:95
	s_waitcnt lgkmcnt(8)
	v_cmp_gt_f32_e64 s[8:9], v17, v16
	v_cmp_gt_f32_e64 s[10:11], v19, v18
	v_cmp_gt_f32_e64 s[12:13], v21, v20
	v_cmp_gt_f32_e64 s[24:25], v23, v22
	v_cmp_gt_f32_e64 s[26:27], v25, v24
	v_cmp_gt_f32_e64 s[28:29], v27, v26
	v_cmp_gt_f32_e64 s[30:31], v29, v28
	v_cmp_gt_f32_e64 s[34:35], v31, v30
	v_cndmask_b32_e64 v16, v16, v17, s[8:9]
	v_cndmask_b32_e64 v32, 0, 1, s[8:9]
	v_cndmask_b32_e64 v18, v18, v19, s[10:11]
	v_cndmask_b32_e64 v33, 2, 3, s[10:11]
	v_cndmask_b32_e64 v20, v20, v21, s[12:13]
	v_cndmask_b32_e64 v34, 4, 5, s[12:13]
	v_cndmask_b32_e64 v22, v22, v23, s[24:25]
	v_cndmask_b32_e64 v35, 6, 7, s[24:25]
	v_cndmask_b32_e64 v24, v24, v25, s[26:27]
	v_cndmask_b32_e64 v36, 8, 9, s[26:27]
	v_cndmask_b32_e64 v26, v26, v27, s[28:29]
	v_cndmask_b32_e64 v37, 10, 11, s[28:29]
	v_cndmask_b32_e64 v28, v28, v29, s[30:31]
	v_cndmask_b32_e64 v38, 12, 13, s[30:31]
	v_cndmask_b32_e64 v30, v30, v31, s[34:35]
	v_cndmask_b32_e64 v39, 14, 15, s[34:35]
	v_cmp_gt_f32_e64 s[8:9], v18, v16
	v_cmp_gt_f32_e64 s[10:11], v22, v20
	v_cmp_gt_f32_e64 s[12:13], v26, v24
	v_cmp_gt_f32_e64 s[24:25], v30, v28
	v_cndmask_b32_e64 v16, v16, v18, s[8:9]
	v_cndmask_b32_e64 v32, v32, v33, s[8:9]
	v_cndmask_b32_e64 v20, v20, v22, s[10:11]
	v_cndmask_b32_e64 v34, v34, v35, s[10:11]
	v_cndmask_b32_e64 v24, v24, v26, s[12:13]
	v_cndmask_b32_e64 v36, v36, v37, s[12:13]
	v_cndmask_b32_e64 v28, v28, v30, s[24:25]
	v_cndmask_b32_e64 v38, v38, v39, s[24:25]
	v_cmp_gt_f32_e64 s[8:9], v20, v16
	v_cmp_gt_f32_e64 s[10:11], v28, v24
	s_nop 0
	v_cndmask_b32_e64 v16, v16, v20, s[8:9]
	v_cndmask_b32_e64 v32, v32, v34, s[8:9]
	v_cndmask_b32_e64 v24, v24, v28, s[10:11]
	v_cndmask_b32_e64 v36, v36, v38, s[10:11]
	v_cmp_gt_f32_e64 s[8:9], v24, v16
	s_nop 1
	v_cndmask_b32_e64 v16, v16, v24, s[8:9]
	v_cndmask_b32_e64 v32, v32, v36, s[8:9]
	v_mov_b32_e32 v4, v16
	v_add_u32_e32 v12, 64, v32
	ds_read2_b32 v[16:17], v54 offset0:96 offset1:97
	ds_read2_b32 v[18:19], v54 offset0:98 offset1:99
	ds_read2_b32 v[20:21], v54 offset0:100 offset1:101
	ds_read2_b32 v[22:23], v54 offset0:102 offset1:103
	ds_read2_b32 v[24:25], v54 offset0:104 offset1:105
	ds_read2_b32 v[26:27], v54 offset0:106 offset1:107
	ds_read2_b32 v[28:29], v54 offset0:108 offset1:109
	ds_read2_b32 v[30:31], v54 offset0:110 offset1:111
	s_waitcnt lgkmcnt(8)
; DI void peer_topk_item(const Params& p, int tt128, int head, char* smem) {
;     ...
; #pragma unroll
;     for (int g = 0; g < 8; ++g) {
;       float m = -INFINITY; int mi = g * 16;
; #pragma unroll
;       for (int j = 0; j < 16; ++j) { float v = row[g * 16 + j]; if (v > m) { m = v; mi = g * 16 + j; } }
;       gm[g] = m; gi[g] = mi;
	v_cmp_gt_f32_e64 s[8:9], v125, v124
	v_cmp_gt_f32_e64 s[10:11], v127, v126
	v_cmp_gt_f32_e64 s[12:13], v129, v128
	v_cmp_gt_f32_e64 s[24:25], v131, v130
	v_cmp_gt_f32_e64 s[26:27], v133, v132
	v_cmp_gt_f32_e64 s[28:29], v135, v134
	v_cmp_gt_f32_e64 s[30:31], v137, v136
	v_cmp_gt_f32_e64 s[34:35], v139, v138
	v_cndmask_b32_e64 v124, v124, v125, s[8:9]
	v_cndmask_b32_e64 v32, 0, 1, s[8:9]
	v_cndmask_b32_e64 v126, v126, v127, s[10:11]
	v_cndmask_b32_e64 v33, 2, 3, s[10:11]
	v_cndmask_b32_e64 v128, v128, v129, s[12:13]
	v_cndmask_b32_e64 v34, 4, 5, s[12:13]
	v_cndmask_b32_e64 v130, v130, v131, s[24:25]
	v_cndmask_b32_e64 v35, 6, 7, s[24:25]
	v_cndmask_b32_e64 v132, v132, v133, s[26:27]
	v_cndmask_b32_e64 v36, 8, 9, s[26:27]
	v_cndmask_b32_e64 v134, v134, v135, s[28:29]
	v_cndmask_b32_e64 v37, 10, 11, s[28:29]
	v_cndmask_b32_e64 v136, v136, v137, s[30:31]
	v_cndmask_b32_e64 v38, 12, 13, s[30:31]
	v_cndmask_b32_e64 v138, v138, v139, s[34:35]
	v_cndmask_b32_e64 v39, 14, 15, s[34:35]
	v_cmp_gt_f32_e64 s[8:9], v126, v124
	v_cmp_gt_f32_e64 s[10:11], v130, v128
	v_cmp_gt_f32_e64 s[12:13], v134, v132
	v_cmp_gt_f32_e64 s[24:25], v138, v136
	v_cndmask_b32_e64 v124, v124, v126, s[8:9]
	v_cndmask_b32_e64 v32, v32, v33, s[8:9]
	v_cndmask_b32_e64 v128, v128, v130, s[10:11]
	v_cndmask_b32_e64 v34, v34, v35, s[10:11]
	v_cndmask_b32_e64 v132, v132, v134, s[12:13]
	v_cndmask_b32_e64 v36, v36, v37, s[12:13]
	v_cndmask_b32_e64 v136, v136, v138, s[24:25]
	v_cndmask_b32_e64 v38, v38, v39, s[24:25]
	v_cmp_gt_f32_e64 s[8:9], v128, v124
	v_cmp_gt_f32_e64 s[10:11], v136, v132
	s_nop 0
	v_cndmask_b32_e64 v124, v124, v128, s[8:9]
	v_cndmask_b32_e64 v32, v32, v34, s[8:9]
	v_cndmask_b32_e64 v132, v132, v136, s[10:11]
	v_cndmask_b32_e64 v36, v36, v38, s[10:11]
	v_cmp_gt_f32_e64 s[8:9], v132, v124
	s_nop 1
	v_cndmask_b32_e64 v124, v124, v132, s[8:9]
	v_cndmask_b32_e64 v32, v32, v36, s[8:9]
	v_mov_b32_e32 v5, v124
	v_add_u32_e32 v13, 0x50, v32
	ds_read2_b32 v[124:125], v54 offset0:112 offset1:113
	ds_read2_b32 v[126:127], v54 offset0:114 offset1:115
	ds_read2_b32 v[128:129], v54 offset0:116 offset1:117
	ds_read2_b32 v[130:131], v54 offset0:118 offset1:119
	ds_read2_b32 v[132:133], v54 offset0:120 offset1:121
	ds_read2_b32 v[134:135], v54 offset0:122 offset1:123
	ds_read2_b32 v[136:137], v54 offset0:124 offset1:125
	ds_read2_b32 v[138:139], v54 offset0:126 offset1:127
	s_waitcnt lgkmcnt(8)
	v_cmp_gt_f32_e64 s[8:9], v17, v16
	v_cmp_gt_f32_e64 s[10:11], v19, v18
	v_cmp_gt_f32_e64 s[12:13], v21, v20
	v_cmp_gt_f32_e64 s[24:25], v23, v22
	v_cmp_gt_f32_e64 s[26:27], v25, v24
	v_cmp_gt_f32_e64 s[28:29], v27, v26
	v_cmp_gt_f32_e64 s[30:31], v29, v28
	v_cmp_gt_f32_e64 s[34:35], v31, v30
	v_cndmask_b32_e64 v16, v16, v17, s[8:9]
	v_cndmask_b32_e64 v32, 0, 1, s[8:9]
	v_cndmask_b32_e64 v18, v18, v19, s[10:11]
	v_cndmask_b32_e64 v33, 2, 3, s[10:11]
	v_cndmask_b32_e64 v20, v20, v21, s[12:13]
	v_cndmask_b32_e64 v34, 4, 5, s[12:13]
	v_cndmask_b32_e64 v22, v22, v23, s[24:25]
	v_cndmask_b32_e64 v35, 6, 7, s[24:25]
	v_cndmask_b32_e64 v24, v24, v25, s[26:27]
	v_cndmask_b32_e64 v36, 8, 9, s[26:27]
	v_cndmask_b32_e64 v26, v26, v27, s[28:29]
	v_cndmask_b32_e64 v37, 10, 11, s[28:29]
	v_cndmask_b32_e64 v28, v28, v29, s[30:31]
	v_cndmask_b32_e64 v38, 12, 13, s[30:31]
	v_cndmask_b32_e64 v30, v30, v31, s[34:35]
	v_cndmask_b32_e64 v39, 14, 15, s[34:35]
	v_cmp_gt_f32_e64 s[8:9], v18, v16
	v_cmp_gt_f32_e64 s[10:11], v22, v20
	v_cmp_gt_f32_e64 s[12:13], v26, v24
	v_cmp_gt_f32_e64 s[24:25], v30, v28
	v_cndmask_b32_e64 v16, v16, v18, s[8:9]
	v_cndmask_b32_e64 v32, v32, v33, s[8:9]
	v_cndmask_b32_e64 v20, v20, v22, s[10:11]
	v_cndmask_b32_e64 v34, v34, v35, s[10:11]
	v_cndmask_b32_e64 v24, v24, v26, s[12:13]
	v_cndmask_b32_e64 v36, v36, v37, s[12:13]
	v_cndmask_b32_e64 v28, v28, v30, s[24:25]
	v_cndmask_b32_e64 v38, v38, v39, s[24:25]
	v_cmp_gt_f32_e64 s[8:9], v20, v16
	v_cmp_gt_f32_e64 s[10:11], v28, v24
	s_nop 0
	v_cndmask_b32_e64 v16, v16, v20, s[8:9]
	v_cndmask_b32_e64 v32, v32, v34, s[8:9]
	v_cndmask_b32_e64 v24, v24, v28, s[10:11]
	v_cndmask_b32_e64 v36, v36, v38, s[10:11]
	v_cmp_gt_f32_e64 s[8:9], v24, v16
	s_nop 1
	v_cndmask_b32_e64 v16, v16, v24, s[8:9]
	v_cndmask_b32_e64 v32, v32, v36, s[8:9]
	v_mov_b32_e32 v6, v16
	v_add_u32_e32 v14, 0x60, v32
	s_waitcnt lgkmcnt(0)
; DI void peer_topk_item(const Params& p, int tt128, int head, char* smem) {
;     ...
; #pragma unroll
;     for (int g = 0; g < 8; ++g) {
;       float m = -INFINITY; int mi = g * 16;
; #pragma unroll
;       for (int j = 0; j < 16; ++j) { float v = row[g * 16 + j]; if (v > m) { m = v; mi = g * 16 + j; } }
;       gm[g] = m; gi[g] = mi;
;     }
; #pragma unroll 1
;     for (int r = 0; r < 16; ++r) {
;       float best = gm[0]; int bg = 0; int bi = gi[0];
; #pragma unroll
;       for (int g = 1; g < 8; ++g) if (gm[g] > best) { best = gm[g]; bg = g; bi = gi[g]; }
;       topv[tid * 16 + r] = best; topi[tid * 16 + r] = (unsigned char)bi;
;       row[bi] = -INFINITY;
;       float m = -INFINITY; int mi = bg * 16;
; #pragma unroll
;       for (int j = 0; j < 16; ++j) { float v = row[bg * 16 + j]; if (v > m) { m = v; mi = bg * 16 + j; } }
	v_cmp_gt_f32_e64 s[8:9], v125, v124
	v_cmp_gt_f32_e64 s[10:11], v127, v126
	v_cmp_gt_f32_e64 s[12:13], v129, v128
	v_cmp_gt_f32_e64 s[24:25], v131, v130
	v_cmp_gt_f32_e64 s[26:27], v133, v132
	v_cmp_gt_f32_e64 s[28:29], v135, v134
	v_cmp_gt_f32_e64 s[30:31], v137, v136
	v_cmp_gt_f32_e64 s[34:35], v139, v138
	v_cndmask_b32_e64 v124, v124, v125, s[8:9]
	v_cndmask_b32_e64 v32, 0, 1, s[8:9]
	v_cndmask_b32_e64 v126, v126, v127, s[10:11]
	v_cndmask_b32_e64 v33, 2, 3, s[10:11]
	v_cndmask_b32_e64 v128, v128, v129, s[12:13]
	v_cndmask_b32_e64 v34, 4, 5, s[12:13]
	v_cndmask_b32_e64 v130, v130, v131, s[24:25]
	v_cndmask_b32_e64 v35, 6, 7, s[24:25]
	v_cndmask_b32_e64 v132, v132, v133, s[26:27]
	v_cndmask_b32_e64 v36, 8, 9, s[26:27]
	v_cndmask_b32_e64 v134, v134, v135, s[28:29]
	v_cndmask_b32_e64 v37, 10, 11, s[28:29]
	v_cndmask_b32_e64 v136, v136, v137, s[30:31]
	v_cndmask_b32_e64 v38, 12, 13, s[30:31]
	v_cndmask_b32_e64 v138, v138, v139, s[34:35]
	v_cndmask_b32_e64 v39, 14, 15, s[34:35]
	v_cmp_gt_f32_e64 s[8:9], v126, v124
	v_cmp_gt_f32_e64 s[10:11], v130, v128
	v_cmp_gt_f32_e64 s[12:13], v134, v132
	v_cmp_gt_f32_e64 s[24:25], v138, v136
	v_cndmask_b32_e64 v124, v124, v126, s[8:9]
	v_cndmask_b32_e64 v32, v32, v33, s[8:9]
	v_cndmask_b32_e64 v128, v128, v130, s[10:11]
	v_cndmask_b32_e64 v34, v34, v35, s[10:11]
	v_cndmask_b32_e64 v132, v132, v134, s[12:13]
	v_cndmask_b32_e64 v36, v36, v37, s[12:13]
	v_cndmask_b32_e64 v136, v136, v138, s[24:25]
	v_cndmask_b32_e64 v38, v38, v39, s[24:25]
	v_cmp_gt_f32_e64 s[8:9], v128, v124
	v_cmp_gt_f32_e64 s[10:11], v136, v132
	s_nop 0
	v_cndmask_b32_e64 v124, v124, v128, s[8:9]
	v_cndmask_b32_e64 v32, v32, v34, s[8:9]
	v_cndmask_b32_e64 v132, v132, v136, s[10:11]
	v_cndmask_b32_e64 v36, v36, v38, s[10:11]
	v_cmp_gt_f32_e64 s[8:9], v132, v124
	s_nop 1
	v_cndmask_b32_e64 v124, v124, v132, s[8:9]
	v_cndmask_b32_e64 v32, v32, v36, s[8:9]
	v_mov_b32_e32 v7, v124
	v_add_u32_e32 v15, 0x70, v32
	v_cmp_gt_f32_e64 s[8:9], v1, v0
	v_cmp_gt_f32_e64 s[10:11], v3, v2
	v_cmp_gt_f32_e64 s[12:13], v5, v4
	v_cmp_gt_f32_e64 s[24:25], v7, v6
	v_cndmask_b32_e64 v40, v0, v1, s[8:9]
	v_cndmask_b32_e64 v44, 0, 1, s[8:9]
	v_cndmask_b32_e64 v141, v8, v9, s[8:9]
	v_cndmask_b32_e64 v41, v2, v3, s[10:11]
	v_cndmask_b32_e64 v45, 2, 3, s[10:11]
	v_cndmask_b32_e64 v142, v10, v11, s[10:11]
	v_cndmask_b32_e64 v42, v4, v5, s[12:13]
	v_cndmask_b32_e64 v46, 4, 5, s[12:13]
	v_cndmask_b32_e64 v143, v12, v13, s[12:13]
	v_cndmask_b32_e64 v43, v6, v7, s[24:25]
	v_cndmask_b32_e64 v47, 6, 7, s[24:25]
	v_cndmask_b32_e64 v144, v14, v15, s[24:25]
	v_cmp_gt_f32_e64 s[8:9], v41, v40
	v_cmp_gt_f32_e64 s[10:11], v43, v42
	s_nop 0
	v_cndmask_b32_e64 v40, v40, v41, s[8:9]
	v_cndmask_b32_e64 v44, v44, v45, s[8:9]
	v_cndmask_b32_e64 v141, v141, v142, s[8:9]
	v_cndmask_b32_e64 v42, v42, v43, s[10:11]
	v_cndmask_b32_e64 v46, v46, v47, s[10:11]
	v_cndmask_b32_e64 v143, v143, v144, s[10:11]
	v_cmp_gt_f32_e64 s[8:9], v42, v40
	s_nop 1
	v_cndmask_b32_e64 v40, v40, v42, s[8:9]
	v_cndmask_b32_e64 v44, v44, v46, s[8:9]
	v_cndmask_b32_e64 v141, v141, v143, s[8:9]
	ds_write_b32 v149, v40
	ds_write_b8 v150, v141
	v_lshl_add_u32 v146, v141, 2, v54
	ds_write_b32 v146, v60
	v_lshl_add_u32 v147, v44, 6, v54
	ds_read2_b32 v[16:17], v147 offset0:0 offset1:1
	ds_read2_b32 v[18:19], v147 offset0:2 offset1:3
	ds_read2_b32 v[20:21], v147 offset0:4 offset1:5
	ds_read2_b32 v[22:23], v147 offset0:6 offset1:7
	ds_read2_b32 v[24:25], v147 offset0:8 offset1:9
	ds_read2_b32 v[26:27], v147 offset0:10 offset1:11
	ds_read2_b32 v[28:29], v147 offset0:12 offset1:13
	ds_read2_b32 v[30:31], v147 offset0:14 offset1:15
	s_waitcnt lgkmcnt(0)
	v_cmp_gt_f32_e64 s[8:9], v17, v16
	v_cmp_gt_f32_e64 s[10:11], v19, v18
	v_cmp_gt_f32_e64 s[12:13], v21, v20
	v_cmp_gt_f32_e64 s[24:25], v23, v22
	v_cmp_gt_f32_e64 s[26:27], v25, v24
	v_cmp_gt_f32_e64 s[28:29], v27, v26
	v_cmp_gt_f32_e64 s[30:31], v29, v28
	v_cmp_gt_f32_e64 s[34:35], v31, v30
	v_cndmask_b32_e64 v16, v16, v17, s[8:9]
	v_cndmask_b32_e64 v32, 0, 1, s[8:9]
	v_cndmask_b32_e64 v18, v18, v19, s[10:11]
	v_cndmask_b32_e64 v33, 2, 3, s[10:11]
	v_cndmask_b32_e64 v20, v20, v21, s[12:13]
	v_cndmask_b32_e64 v34, 4, 5, s[12:13]
	v_cndmask_b32_e64 v22, v22, v23, s[24:25]
	v_cndmask_b32_e64 v35, 6, 7, s[24:25]
	v_cndmask_b32_e64 v24, v24, v25, s[26:27]
	v_cndmask_b32_e64 v36, 8, 9, s[26:27]
	v_cndmask_b32_e64 v26, v26, v27, s[28:29]
	v_cndmask_b32_e64 v37, 10, 11, s[28:29]
	v_cndmask_b32_e64 v28, v28, v29, s[30:31]
	v_cndmask_b32_e64 v38, 12, 13, s[30:31]
	v_cndmask_b32_e64 v30, v30, v31, s[34:35]
	v_cndmask_b32_e64 v39, 14, 15, s[34:35]
	v_cmp_gt_f32_e64 s[8:9], v18, v16
	v_cmp_gt_f32_e64 s[10:11], v22, v20
	v_cmp_gt_f32_e64 s[12:13], v26, v24
	v_cmp_gt_f32_e64 s[24:25], v30, v28
	v_cndmask_b32_e64 v16, v16, v18, s[8:9]
	v_cndmask_b32_e64 v32, v32, v33, s[8:9]
	v_cndmask_b32_e64 v20, v20, v22, s[10:11]
	v_cndmask_b32_e64 v34, v34, v35, s[10:11]
	v_cndmask_b32_e64 v24, v24, v26, s[12:13]
	v_cndmask_b32_e64 v36, v36, v37, s[12:13]
	v_cndmask_b32_e64 v28, v28, v30, s[24:25]
	v_cndmask_b32_e64 v38, v38, v39, s[24:25]
	v_cmp_gt_f32_e64 s[8:9], v20, v16
	v_cmp_gt_f32_e64 s[10:11], v28, v24
	s_nop 0
	v_cndmask_b32_e64 v16, v16, v20, s[8:9]
	v_cndmask_b32_e64 v32, v32, v34, s[8:9]
	v_cndmask_b32_e64 v24, v24, v28, s[10:11]
	v_cndmask_b32_e64 v36, v36, v38, s[10:11]
	v_cmp_gt_f32_e64 s[8:9], v24, v16
	s_nop 1
	v_cndmask_b32_e64 v16, v16, v24, s[8:9]
	v_cndmask_b32_e64 v32, v32, v36, s[8:9]
	v_lshl_add_u32 v148, v44, 4, v32
	v_cmp_eq_u32_e64 s[8:9], 0, v44
	v_cmp_eq_u32_e64 s[10:11], 1, v44
	v_cmp_eq_u32_e64 s[12:13], 2, v44
	v_cmp_eq_u32_e64 s[24:25], 3, v44
; DI void peer_topk_item(const Params& p, int tt128, int head, char* smem) {
;     ...
; #pragma unroll 1
;     for (int r = 0; r < 16; ++r) {
;       float best = gm[0]; int bg = 0; int bi = gi[0];
; #pragma unroll
;       for (int g = 1; g < 8; ++g) if (gm[g] > best) { best = gm[g]; bg = g; bi = gi[g]; }
;       topv[tid * 16 + r] = best; topi[tid * 16 + r] = (unsigned char)bi;
;       row[bi] = -INFINITY;
;       float m = -INFINITY; int mi = bg * 16;
; #pragma unroll
;       for (int j = 0; j < 16; ++j) { float v = row[bg * 16 + j]; if (v > m) { m = v; mi = bg * 16 + j; } }
; #pragma unroll
;       for (int g = 0; g < 8; ++g) { gm[g] = (g == bg) ? m : gm[g]; gi[g] = (g == bg) ? mi : gi[g]; }
;     }
	v_cmp_eq_u32_e64 s[26:27], 4, v44
	v_cmp_eq_u32_e64 s[28:29], 5, v44
	v_cmp_eq_u32_e64 s[30:31], 6, v44
	v_cmp_eq_u32_e64 s[34:35], 7, v44
	v_cndmask_b32_e64 v0, v0, v16, s[8:9]
	v_cndmask_b32_e64 v8, v8, v148, s[8:9]
	v_cndmask_b32_e64 v1, v1, v16, s[10:11]
	v_cndmask_b32_e64 v9, v9, v148, s[10:11]
	v_cndmask_b32_e64 v2, v2, v16, s[12:13]
	v_cndmask_b32_e64 v10, v10, v148, s[12:13]
	v_cndmask_b32_e64 v3, v3, v16, s[24:25]
	v_cndmask_b32_e64 v11, v11, v148, s[24:25]
	v_cndmask_b32_e64 v4, v4, v16, s[26:27]
	v_cndmask_b32_e64 v12, v12, v148, s[26:27]
	v_cndmask_b32_e64 v5, v5, v16, s[28:29]
	v_cndmask_b32_e64 v13, v13, v148, s[28:29]
	v_cndmask_b32_e64 v6, v6, v16, s[30:31]
	v_cndmask_b32_e64 v14, v14, v148, s[30:31]
	v_cndmask_b32_e64 v7, v7, v16, s[34:35]
	v_cndmask_b32_e64 v15, v15, v148, s[34:35]
	v_cmp_gt_f32_e64 s[8:9], v1, v0
	v_cmp_gt_f32_e64 s[10:11], v3, v2
	v_cmp_gt_f32_e64 s[12:13], v5, v4
	v_cmp_gt_f32_e64 s[24:25], v7, v6
	v_cndmask_b32_e64 v40, v0, v1, s[8:9]
	v_cndmask_b32_e64 v44, 0, 1, s[8:9]
	v_cndmask_b32_e64 v141, v8, v9, s[8:9]
	v_cndmask_b32_e64 v41, v2, v3, s[10:11]
	v_cndmask_b32_e64 v45, 2, 3, s[10:11]
	v_cndmask_b32_e64 v142, v10, v11, s[10:11]
	v_cndmask_b32_e64 v42, v4, v5, s[12:13]
	v_cndmask_b32_e64 v46, 4, 5, s[12:13]
	v_cndmask_b32_e64 v143, v12, v13, s[12:13]
	v_cndmask_b32_e64 v43, v6, v7, s[24:25]
	v_cndmask_b32_e64 v47, 6, 7, s[24:25]
	v_cndmask_b32_e64 v144, v14, v15, s[24:25]
	v_cmp_gt_f32_e64 s[8:9], v41, v40
	v_cmp_gt_f32_e64 s[10:11], v43, v42
	s_nop 0
	v_cndmask_b32_e64 v40, v40, v41, s[8:9]
	v_cndmask_b32_e64 v44, v44, v45, s[8:9]
	v_cndmask_b32_e64 v141, v141, v142, s[8:9]
	v_cndmask_b32_e64 v42, v42, v43, s[10:11]
	v_cndmask_b32_e64 v46, v46, v47, s[10:11]
	v_cndmask_b32_e64 v143, v143, v144, s[10:11]
	v_cmp_gt_f32_e64 s[8:9], v42, v40
	s_nop 1
	v_cndmask_b32_e64 v40, v40, v42, s[8:9]
	v_cndmask_b32_e64 v44, v44, v46, s[8:9]
	v_cndmask_b32_e64 v141, v141, v143, s[8:9]
	ds_write_b32 v149, v40 offset:1024
	ds_write_b8 v150, v141 offset:256
	v_lshl_add_u32 v146, v141, 2, v54
	ds_write_b32 v146, v60
	v_lshl_add_u32 v147, v44, 6, v54
	ds_read2_b32 v[16:17], v147 offset0:0 offset1:1
	ds_read2_b32 v[18:19], v147 offset0:2 offset1:3
	ds_read2_b32 v[20:21], v147 offset0:4 offset1:5
	ds_read2_b32 v[22:23], v147 offset0:6 offset1:7
	ds_read2_b32 v[24:25], v147 offset0:8 offset1:9
	ds_read2_b32 v[26:27], v147 offset0:10 offset1:11
	ds_read2_b32 v[28:29], v147 offset0:12 offset1:13
	ds_read2_b32 v[30:31], v147 offset0:14 offset1:15
	s_waitcnt lgkmcnt(0)
	v_cmp_gt_f32_e64 s[8:9], v17, v16
	v_cmp_gt_f32_e64 s[10:11], v19, v18
	v_cmp_gt_f32_e64 s[12:13], v21, v20
	v_cmp_gt_f32_e64 s[24:25], v23, v22
	v_cmp_gt_f32_e64 s[26:27], v25, v24
	v_cmp_gt_f32_e64 s[28:29], v27, v26
	v_cmp_gt_f32_e64 s[30:31], v29, v28
	v_cmp_gt_f32_e64 s[34:35], v31, v30
	v_cndmask_b32_e64 v16, v16, v17, s[8:9]
	v_cndmask_b32_e64 v32, 0, 1, s[8:9]
	v_cndmask_b32_e64 v18, v18, v19, s[10:11]
	v_cndmask_b32_e64 v33, 2, 3, s[10:11]
	v_cndmask_b32_e64 v20, v20, v21, s[12:13]
	v_cndmask_b32_e64 v34, 4, 5, s[12:13]
	v_cndmask_b32_e64 v22, v22, v23, s[24:25]
	v_cndmask_b32_e64 v35, 6, 7, s[24:25]
	v_cndmask_b32_e64 v24, v24, v25, s[26:27]
	v_cndmask_b32_e64 v36, 8, 9, s[26:27]
	v_cndmask_b32_e64 v26, v26, v27, s[28:29]
	v_cndmask_b32_e64 v37, 10, 11, s[28:29]
	v_cndmask_b32_e64 v28, v28, v29, s[30:31]
	v_cndmask_b32_e64 v38, 12, 13, s[30:31]
	v_cndmask_b32_e64 v30, v30, v31, s[34:35]
	v_cndmask_b32_e64 v39, 14, 15, s[34:35]
	v_cmp_gt_f32_e64 s[8:9], v18, v16
	v_cmp_gt_f32_e64 s[10:11], v22, v20
	v_cmp_gt_f32_e64 s[12:13], v26, v24
	v_cmp_gt_f32_e64 s[24:25], v30, v28
	v_cndmask_b32_e64 v16, v16, v18, s[8:9]
	v_cndmask_b32_e64 v32, v32, v33, s[8:9]
	v_cndmask_b32_e64 v20, v20, v22, s[10:11]
	v_cndmask_b32_e64 v34, v34, v35, s[10:11]
	v_cndmask_b32_e64 v24, v24, v26, s[12:13]
	v_cndmask_b32_e64 v36, v36, v37, s[12:13]
	v_cndmask_b32_e64 v28, v28, v30, s[24:25]
	v_cndmask_b32_e64 v38, v38, v39, s[24:25]
	v_cmp_gt_f32_e64 s[8:9], v20, v16
	v_cmp_gt_f32_e64 s[10:11], v28, v24
	s_nop 0
	v_cndmask_b32_e64 v16, v16, v20, s[8:9]
	v_cndmask_b32_e64 v32, v32, v34, s[8:9]
	v_cndmask_b32_e64 v24, v24, v28, s[10:11]
	v_cndmask_b32_e64 v36, v36, v38, s[10:11]
	v_cmp_gt_f32_e64 s[8:9], v24, v16
	s_nop 1
	v_cndmask_b32_e64 v16, v16, v24, s[8:9]
	v_cndmask_b32_e64 v32, v32, v36, s[8:9]
	v_lshl_add_u32 v148, v44, 4, v32
	v_cmp_eq_u32_e64 s[8:9], 0, v44
	v_cmp_eq_u32_e64 s[10:11], 1, v44
	v_cmp_eq_u32_e64 s[12:13], 2, v44
	v_cmp_eq_u32_e64 s[24:25], 3, v44
	v_cmp_eq_u32_e64 s[26:27], 4, v44
	v_cmp_eq_u32_e64 s[28:29], 5, v44
	v_cmp_eq_u32_e64 s[30:31], 6, v44
	v_cmp_eq_u32_e64 s[34:35], 7, v44
	v_cndmask_b32_e64 v0, v0, v16, s[8:9]
	v_cndmask_b32_e64 v8, v8, v148, s[8:9]
	v_cndmask_b32_e64 v1, v1, v16, s[10:11]
	v_cndmask_b32_e64 v9, v9, v148, s[10:11]
	v_cndmask_b32_e64 v2, v2, v16, s[12:13]
	v_cndmask_b32_e64 v10, v10, v148, s[12:13]
	v_cndmask_b32_e64 v3, v3, v16, s[24:25]
	v_cndmask_b32_e64 v11, v11, v148, s[24:25]
	v_cndmask_b32_e64 v4, v4, v16, s[26:27]
	v_cndmask_b32_e64 v12, v12, v148, s[26:27]
	v_cndmask_b32_e64 v5, v5, v16, s[28:29]
	v_cndmask_b32_e64 v13, v13, v148, s[28:29]
	v_cndmask_b32_e64 v6, v6, v16, s[30:31]
	v_cndmask_b32_e64 v14, v14, v148, s[30:31]
	v_cndmask_b32_e64 v7, v7, v16, s[34:35]
	v_cndmask_b32_e64 v15, v15, v148, s[34:35]
	v_cmp_gt_f32_e64 s[8:9], v1, v0
	v_cmp_gt_f32_e64 s[10:11], v3, v2
	v_cmp_gt_f32_e64 s[12:13], v5, v4
	v_cmp_gt_f32_e64 s[24:25], v7, v6
	v_cndmask_b32_e64 v40, v0, v1, s[8:9]
	v_cndmask_b32_e64 v44, 0, 1, s[8:9]
	v_cndmask_b32_e64 v141, v8, v9, s[8:9]
	v_cndmask_b32_e64 v41, v2, v3, s[10:11]
	v_cndmask_b32_e64 v45, 2, 3, s[10:11]
	v_cndmask_b32_e64 v142, v10, v11, s[10:11]
	v_cndmask_b32_e64 v42, v4, v5, s[12:13]
	v_cndmask_b32_e64 v46, 4, 5, s[12:13]
	v_cndmask_b32_e64 v143, v12, v13, s[12:13]
	v_cndmask_b32_e64 v43, v6, v7, s[24:25]
	v_cndmask_b32_e64 v47, 6, 7, s[24:25]
	v_cndmask_b32_e64 v144, v14, v15, s[24:25]
	v_cmp_gt_f32_e64 s[8:9], v41, v40
	v_cmp_gt_f32_e64 s[10:11], v43, v42
	s_nop 0
	v_cndmask_b32_e64 v40, v40, v41, s[8:9]
	v_cndmask_b32_e64 v44, v44, v45, s[8:9]
	v_cndmask_b32_e64 v141, v141, v142, s[8:9]
	v_cndmask_b32_e64 v42, v42, v43, s[10:11]
	v_cndmask_b32_e64 v46, v46, v47, s[10:11]
	v_cndmask_b32_e64 v143, v143, v144, s[10:11]
	v_cmp_gt_f32_e64 s[8:9], v42, v40
	s_nop 1
	v_cndmask_b32_e64 v40, v40, v42, s[8:9]
	v_cndmask_b32_e64 v44, v44, v46, s[8:9]
	v_cndmask_b32_e64 v141, v141, v143, s[8:9]
	ds_write_b32 v149, v40 offset:2048
	ds_write_b8 v150, v141 offset:512
	v_lshl_add_u32 v146, v141, 2, v54
	ds_write_b32 v146, v60
	v_lshl_add_u32 v147, v44, 6, v54
	ds_read2_b32 v[16:17], v147 offset0:0 offset1:1
	ds_read2_b32 v[18:19], v147 offset0:2 offset1:3
	ds_read2_b32 v[20:21], v147 offset0:4 offset1:5
	ds_read2_b32 v[22:23], v147 offset0:6 offset1:7
	ds_read2_b32 v[24:25], v147 offset0:8 offset1:9
	ds_read2_b32 v[26:27], v147 offset0:10 offset1:11
	ds_read2_b32 v[28:29], v147 offset0:12 offset1:13
	ds_read2_b32 v[30:31], v147 offset0:14 offset1:15
	s_waitcnt lgkmcnt(0)
; DI void peer_topk_item(const Params& p, int tt128, int head, char* smem) {
;     ...
; #pragma unroll 1
;     for (int r = 0; r < 16; ++r) {
;       float best = gm[0]; int bg = 0; int bi = gi[0];
; #pragma unroll
;       for (int g = 1; g < 8; ++g) if (gm[g] > best) { best = gm[g]; bg = g; bi = gi[g]; }
;       topv[tid * 16 + r] = best; topi[tid * 16 + r] = (unsigned char)bi;
;       row[bi] = -INFINITY;
;       float m = -INFINITY; int mi = bg * 16;
; #pragma unroll
;       for (int j = 0; j < 16; ++j) { float v = row[bg * 16 + j]; if (v > m) { m = v; mi = bg * 16 + j; } }
; #pragma unroll
;       for (int g = 0; g < 8; ++g) { gm[g] = (g == bg) ? m : gm[g]; gi[g] = (g == bg) ? mi : gi[g]; }
;     }
	v_cmp_gt_f32_e64 s[8:9], v17, v16
	v_cmp_gt_f32_e64 s[10:11], v19, v18
	v_cmp_gt_f32_e64 s[12:13], v21, v20
	v_cmp_gt_f32_e64 s[24:25], v23, v22
	v_cmp_gt_f32_e64 s[26:27], v25, v24
	v_cmp_gt_f32_e64 s[28:29], v27, v26
	v_cmp_gt_f32_e64 s[30:31], v29, v28
	v_cmp_gt_f32_e64 s[34:35], v31, v30
	v_cndmask_b32_e64 v16, v16, v17, s[8:9]
	v_cndmask_b32_e64 v32, 0, 1, s[8:9]
	v_cndmask_b32_e64 v18, v18, v19, s[10:11]
	v_cndmask_b32_e64 v33, 2, 3, s[10:11]
	v_cndmask_b32_e64 v20, v20, v21, s[12:13]
	v_cndmask_b32_e64 v34, 4, 5, s[12:13]
	v_cndmask_b32_e64 v22, v22, v23, s[24:25]
	v_cndmask_b32_e64 v35, 6, 7, s[24:25]
	v_cndmask_b32_e64 v24, v24, v25, s[26:27]
	v_cndmask_b32_e64 v36, 8, 9, s[26:27]
	v_cndmask_b32_e64 v26, v26, v27, s[28:29]
	v_cndmask_b32_e64 v37, 10, 11, s[28:29]
	v_cndmask_b32_e64 v28, v28, v29, s[30:31]
	v_cndmask_b32_e64 v38, 12, 13, s[30:31]
	v_cndmask_b32_e64 v30, v30, v31, s[34:35]
	v_cndmask_b32_e64 v39, 14, 15, s[34:35]
	v_cmp_gt_f32_e64 s[8:9], v18, v16
	v_cmp_gt_f32_e64 s[10:11], v22, v20
	v_cmp_gt_f32_e64 s[12:13], v26, v24
	v_cmp_gt_f32_e64 s[24:25], v30, v28
	v_cndmask_b32_e64 v16, v16, v18, s[8:9]
	v_cndmask_b32_e64 v32, v32, v33, s[8:9]
	v_cndmask_b32_e64 v20, v20, v22, s[10:11]
	v_cndmask_b32_e64 v34, v34, v35, s[10:11]
	v_cndmask_b32_e64 v24, v24, v26, s[12:13]
	v_cndmask_b32_e64 v36, v36, v37, s[12:13]
	v_cndmask_b32_e64 v28, v28, v30, s[24:25]
	v_cndmask_b32_e64 v38, v38, v39, s[24:25]
	v_cmp_gt_f32_e64 s[8:9], v20, v16
	v_cmp_gt_f32_e64 s[10:11], v28, v24
	s_nop 0
	v_cndmask_b32_e64 v16, v16, v20, s[8:9]
	v_cndmask_b32_e64 v32, v32, v34, s[8:9]
	v_cndmask_b32_e64 v24, v24, v28, s[10:11]
	v_cndmask_b32_e64 v36, v36, v38, s[10:11]
	v_cmp_gt_f32_e64 s[8:9], v24, v16
	s_nop 1
	v_cndmask_b32_e64 v16, v16, v24, s[8:9]
	v_cndmask_b32_e64 v32, v32, v36, s[8:9]
	v_lshl_add_u32 v148, v44, 4, v32
	v_cmp_eq_u32_e64 s[8:9], 0, v44
	v_cmp_eq_u32_e64 s[10:11], 1, v44
	v_cmp_eq_u32_e64 s[12:13], 2, v44
	v_cmp_eq_u32_e64 s[24:25], 3, v44
	v_cmp_eq_u32_e64 s[26:27], 4, v44
	v_cmp_eq_u32_e64 s[28:29], 5, v44
	v_cmp_eq_u32_e64 s[30:31], 6, v44
	v_cmp_eq_u32_e64 s[34:35], 7, v44
	v_cndmask_b32_e64 v0, v0, v16, s[8:9]
	v_cndmask_b32_e64 v8, v8, v148, s[8:9]
	v_cndmask_b32_e64 v1, v1, v16, s[10:11]
	v_cndmask_b32_e64 v9, v9, v148, s[10:11]
	v_cndmask_b32_e64 v2, v2, v16, s[12:13]
	v_cndmask_b32_e64 v10, v10, v148, s[12:13]
	v_cndmask_b32_e64 v3, v3, v16, s[24:25]
	v_cndmask_b32_e64 v11, v11, v148, s[24:25]
	v_cndmask_b32_e64 v4, v4, v16, s[26:27]
	v_cndmask_b32_e64 v12, v12, v148, s[26:27]
	v_cndmask_b32_e64 v5, v5, v16, s[28:29]
	v_cndmask_b32_e64 v13, v13, v148, s[28:29]
	v_cndmask_b32_e64 v6, v6, v16, s[30:31]
	v_cndmask_b32_e64 v14, v14, v148, s[30:31]
	v_cndmask_b32_e64 v7, v7, v16, s[34:35]
	v_cndmask_b32_e64 v15, v15, v148, s[34:35]
	v_cmp_gt_f32_e64 s[8:9], v1, v0
	v_cmp_gt_f32_e64 s[10:11], v3, v2
	v_cmp_gt_f32_e64 s[12:13], v5, v4
	v_cmp_gt_f32_e64 s[24:25], v7, v6
	v_cndmask_b32_e64 v40, v0, v1, s[8:9]
	v_cndmask_b32_e64 v44, 0, 1, s[8:9]
	v_cndmask_b32_e64 v141, v8, v9, s[8:9]
	v_cndmask_b32_e64 v41, v2, v3, s[10:11]
	v_cndmask_b32_e64 v45, 2, 3, s[10:11]
	v_cndmask_b32_e64 v142, v10, v11, s[10:11]
	v_cndmask_b32_e64 v42, v4, v5, s[12:13]
	v_cndmask_b32_e64 v46, 4, 5, s[12:13]
	v_cndmask_b32_e64 v143, v12, v13, s[12:13]
	v_cndmask_b32_e64 v43, v6, v7, s[24:25]
	v_cndmask_b32_e64 v47, 6, 7, s[24:25]
	v_cndmask_b32_e64 v144, v14, v15, s[24:25]
	v_cmp_gt_f32_e64 s[8:9], v41, v40
	v_cmp_gt_f32_e64 s[10:11], v43, v42
	s_nop 0
	v_cndmask_b32_e64 v40, v40, v41, s[8:9]
	v_cndmask_b32_e64 v44, v44, v45, s[8:9]
	v_cndmask_b32_e64 v141, v141, v142, s[8:9]
	v_cndmask_b32_e64 v42, v42, v43, s[10:11]
	v_cndmask_b32_e64 v46, v46, v47, s[10:11]
	v_cndmask_b32_e64 v143, v143, v144, s[10:11]
	v_cmp_gt_f32_e64 s[8:9], v42, v40
	s_nop 1
	v_cndmask_b32_e64 v40, v40, v42, s[8:9]
	v_cndmask_b32_e64 v44, v44, v46, s[8:9]
	v_cndmask_b32_e64 v141, v141, v143, s[8:9]
	ds_write_b32 v149, v40 offset:3072
	ds_write_b8 v150, v141 offset:768
	v_lshl_add_u32 v146, v141, 2, v54
	ds_write_b32 v146, v60
	v_lshl_add_u32 v147, v44, 6, v54
	ds_read2_b32 v[16:17], v147 offset0:0 offset1:1
	ds_read2_b32 v[18:19], v147 offset0:2 offset1:3
	ds_read2_b32 v[20:21], v147 offset0:4 offset1:5
	ds_read2_b32 v[22:23], v147 offset0:6 offset1:7
	ds_read2_b32 v[24:25], v147 offset0:8 offset1:9
	ds_read2_b32 v[26:27], v147 offset0:10 offset1:11
	ds_read2_b32 v[28:29], v147 offset0:12 offset1:13
	ds_read2_b32 v[30:31], v147 offset0:14 offset1:15
	s_waitcnt lgkmcnt(0)
; DI void peer_topk_item(const Params& p, int tt128, int head, char* smem) {
;     ...
; #pragma unroll 1
;     for (int r = 0; r < 16; ++r) {
;       float best = gm[0]; int bg = 0; int bi = gi[0];
; #pragma unroll
;       for (int g = 1; g < 8; ++g) if (gm[g] > best) { best = gm[g]; bg = g; bi = gi[g]; }
;       topv[tid * 16 + r] = best; topi[tid * 16 + r] = (unsigned char)bi;
;       row[bi] = -INFINITY;
;       float m = -INFINITY; int mi = bg * 16;
; #pragma unroll
;       for (int j = 0; j < 16; ++j) { float v = row[bg * 16 + j]; if (v > m) { m = v; mi = bg * 16 + j; } }
; #pragma unroll
;       for (int g = 0; g < 8; ++g) { gm[g] = (g == bg) ? m : gm[g]; gi[g] = (g == bg) ? mi : gi[g]; }
;     }
	v_cmp_gt_f32_e64 s[8:9], v17, v16
	v_cmp_gt_f32_e64 s[10:11], v19, v18
	v_cmp_gt_f32_e64 s[12:13], v21, v20
	v_cmp_gt_f32_e64 s[24:25], v23, v22
	v_cmp_gt_f32_e64 s[26:27], v25, v24
	v_cmp_gt_f32_e64 s[28:29], v27, v26
	v_cmp_gt_f32_e64 s[30:31], v29, v28
	v_cmp_gt_f32_e64 s[34:35], v31, v30
	v_cndmask_b32_e64 v16, v16, v17, s[8:9]
	v_cndmask_b32_e64 v32, 0, 1, s[8:9]
	v_cndmask_b32_e64 v18, v18, v19, s[10:11]
	v_cndmask_b32_e64 v33, 2, 3, s[10:11]
	v_cndmask_b32_e64 v20, v20, v21, s[12:13]
	v_cndmask_b32_e64 v34, 4, 5, s[12:13]
	v_cndmask_b32_e64 v22, v22, v23, s[24:25]
	v_cndmask_b32_e64 v35, 6, 7, s[24:25]
	v_cndmask_b32_e64 v24, v24, v25, s[26:27]
	v_cndmask_b32_e64 v36, 8, 9, s[26:27]
	v_cndmask_b32_e64 v26, v26, v27, s[28:29]
	v_cndmask_b32_e64 v37, 10, 11, s[28:29]
	v_cndmask_b32_e64 v28, v28, v29, s[30:31]
	v_cndmask_b32_e64 v38, 12, 13, s[30:31]
	v_cndmask_b32_e64 v30, v30, v31, s[34:35]
	v_cndmask_b32_e64 v39, 14, 15, s[34:35]
	v_cmp_gt_f32_e64 s[8:9], v18, v16
	v_cmp_gt_f32_e64 s[10:11], v22, v20
	v_cmp_gt_f32_e64 s[12:13], v26, v24
	v_cmp_gt_f32_e64 s[24:25], v30, v28
	v_cndmask_b32_e64 v16, v16, v18, s[8:9]
	v_cndmask_b32_e64 v32, v32, v33, s[8:9]
	v_cndmask_b32_e64 v20, v20, v22, s[10:11]
	v_cndmask_b32_e64 v34, v34, v35, s[10:11]
	v_cndmask_b32_e64 v24, v24, v26, s[12:13]
	v_cndmask_b32_e64 v36, v36, v37, s[12:13]
	v_cndmask_b32_e64 v28, v28, v30, s[24:25]
	v_cndmask_b32_e64 v38, v38, v39, s[24:25]
	v_cmp_gt_f32_e64 s[8:9], v20, v16
	v_cmp_gt_f32_e64 s[10:11], v28, v24
	s_nop 0
	v_cndmask_b32_e64 v16, v16, v20, s[8:9]
	v_cndmask_b32_e64 v32, v32, v34, s[8:9]
	v_cndmask_b32_e64 v24, v24, v28, s[10:11]
	v_cndmask_b32_e64 v36, v36, v38, s[10:11]
	v_cmp_gt_f32_e64 s[8:9], v24, v16
	s_nop 1
	v_cndmask_b32_e64 v16, v16, v24, s[8:9]
	v_cndmask_b32_e64 v32, v32, v36, s[8:9]
	v_lshl_add_u32 v148, v44, 4, v32
	v_cmp_eq_u32_e64 s[8:9], 0, v44
	v_cmp_eq_u32_e64 s[10:11], 1, v44
	v_cmp_eq_u32_e64 s[12:13], 2, v44
	v_cmp_eq_u32_e64 s[24:25], 3, v44
	v_cmp_eq_u32_e64 s[26:27], 4, v44
	v_cmp_eq_u32_e64 s[28:29], 5, v44
	v_cmp_eq_u32_e64 s[30:31], 6, v44
	v_cmp_eq_u32_e64 s[34:35], 7, v44
	v_cndmask_b32_e64 v0, v0, v16, s[8:9]
	v_cndmask_b32_e64 v8, v8, v148, s[8:9]
	v_cndmask_b32_e64 v1, v1, v16, s[10:11]
	v_cndmask_b32_e64 v9, v9, v148, s[10:11]
	v_cndmask_b32_e64 v2, v2, v16, s[12:13]
	v_cndmask_b32_e64 v10, v10, v148, s[12:13]
	v_cndmask_b32_e64 v3, v3, v16, s[24:25]
	v_cndmask_b32_e64 v11, v11, v148, s[24:25]
	v_cndmask_b32_e64 v4, v4, v16, s[26:27]
	v_cndmask_b32_e64 v12, v12, v148, s[26:27]
	v_cndmask_b32_e64 v5, v5, v16, s[28:29]
	v_cndmask_b32_e64 v13, v13, v148, s[28:29]
	v_cndmask_b32_e64 v6, v6, v16, s[30:31]
	v_cndmask_b32_e64 v14, v14, v148, s[30:31]
	v_cndmask_b32_e64 v7, v7, v16, s[34:35]
	v_cndmask_b32_e64 v15, v15, v148, s[34:35]
	v_cmp_gt_f32_e64 s[8:9], v1, v0
	v_cmp_gt_f32_e64 s[10:11], v3, v2
	v_cmp_gt_f32_e64 s[12:13], v5, v4
	v_cmp_gt_f32_e64 s[24:25], v7, v6
	v_cndmask_b32_e64 v40, v0, v1, s[8:9]
	v_cndmask_b32_e64 v44, 0, 1, s[8:9]
	v_cndmask_b32_e64 v141, v8, v9, s[8:9]
	v_cndmask_b32_e64 v41, v2, v3, s[10:11]
	v_cndmask_b32_e64 v45, 2, 3, s[10:11]
	v_cndmask_b32_e64 v142, v10, v11, s[10:11]
	v_cndmask_b32_e64 v42, v4, v5, s[12:13]
	v_cndmask_b32_e64 v46, 4, 5, s[12:13]
	v_cndmask_b32_e64 v143, v12, v13, s[12:13]
	v_cndmask_b32_e64 v43, v6, v7, s[24:25]
	v_cndmask_b32_e64 v47, 6, 7, s[24:25]
	v_cndmask_b32_e64 v144, v14, v15, s[24:25]
	v_cmp_gt_f32_e64 s[8:9], v41, v40
	v_cmp_gt_f32_e64 s[10:11], v43, v42
	s_nop 0
	v_cndmask_b32_e64 v40, v40, v41, s[8:9]
	v_cndmask_b32_e64 v44, v44, v45, s[8:9]
	v_cndmask_b32_e64 v141, v141, v142, s[8:9]
	v_cndmask_b32_e64 v42, v42, v43, s[10:11]
	v_cndmask_b32_e64 v46, v46, v47, s[10:11]
	v_cndmask_b32_e64 v143, v143, v144, s[10:11]
	v_cmp_gt_f32_e64 s[8:9], v42, v40
	s_nop 1
	v_cndmask_b32_e64 v40, v40, v42, s[8:9]
	v_cndmask_b32_e64 v44, v44, v46, s[8:9]
	v_cndmask_b32_e64 v141, v141, v143, s[8:9]
	ds_write_b32 v149, v40 offset:4096
	ds_write_b8 v150, v141 offset:1024
	v_lshl_add_u32 v146, v141, 2, v54
	ds_write_b32 v146, v60
	v_lshl_add_u32 v147, v44, 6, v54
	ds_read2_b32 v[16:17], v147 offset0:0 offset1:1
	ds_read2_b32 v[18:19], v147 offset0:2 offset1:3
	ds_read2_b32 v[20:21], v147 offset0:4 offset1:5
	ds_read2_b32 v[22:23], v147 offset0:6 offset1:7
	ds_read2_b32 v[24:25], v147 offset0:8 offset1:9
	ds_read2_b32 v[26:27], v147 offset0:10 offset1:11
	ds_read2_b32 v[28:29], v147 offset0:12 offset1:13
	ds_read2_b32 v[30:31], v147 offset0:14 offset1:15
	s_waitcnt lgkmcnt(0)
; DI void peer_topk_item(const Params& p, int tt128, int head, char* smem) {
;     ...
; #pragma unroll 1
;     for (int r = 0; r < 16; ++r) {
;       float best = gm[0]; int bg = 0; int bi = gi[0];
; #pragma unroll
;       for (int g = 1; g < 8; ++g) if (gm[g] > best) { best = gm[g]; bg = g; bi = gi[g]; }
;       topv[tid * 16 + r] = best; topi[tid * 16 + r] = (unsigned char)bi;
;       row[bi] = -INFINITY;
;       float m = -INFINITY; int mi = bg * 16;
; #pragma unroll
;       for (int j = 0; j < 16; ++j) { float v = row[bg * 16 + j]; if (v > m) { m = v; mi = bg * 16 + j; } }
; #pragma unroll
;       for (int g = 0; g < 8; ++g) { gm[g] = (g == bg) ? m : gm[g]; gi[g] = (g == bg) ? mi : gi[g]; }
;     }
	v_cmp_gt_f32_e64 s[8:9], v17, v16
	v_cmp_gt_f32_e64 s[10:11], v19, v18
	v_cmp_gt_f32_e64 s[12:13], v21, v20
	v_cmp_gt_f32_e64 s[24:25], v23, v22
	v_cmp_gt_f32_e64 s[26:27], v25, v24
	v_cmp_gt_f32_e64 s[28:29], v27, v26
	v_cmp_gt_f32_e64 s[30:31], v29, v28
	v_cmp_gt_f32_e64 s[34:35], v31, v30
	v_cndmask_b32_e64 v16, v16, v17, s[8:9]
	v_cndmask_b32_e64 v32, 0, 1, s[8:9]
	v_cndmask_b32_e64 v18, v18, v19, s[10:11]
	v_cndmask_b32_e64 v33, 2, 3, s[10:11]
	v_cndmask_b32_e64 v20, v20, v21, s[12:13]
	v_cndmask_b32_e64 v34, 4, 5, s[12:13]
	v_cndmask_b32_e64 v22, v22, v23, s[24:25]
	v_cndmask_b32_e64 v35, 6, 7, s[24:25]
	v_cndmask_b32_e64 v24, v24, v25, s[26:27]
	v_cndmask_b32_e64 v36, 8, 9, s[26:27]
	v_cndmask_b32_e64 v26, v26, v27, s[28:29]
	v_cndmask_b32_e64 v37, 10, 11, s[28:29]
	v_cndmask_b32_e64 v28, v28, v29, s[30:31]
	v_cndmask_b32_e64 v38, 12, 13, s[30:31]
	v_cndmask_b32_e64 v30, v30, v31, s[34:35]
	v_cndmask_b32_e64 v39, 14, 15, s[34:35]
	v_cmp_gt_f32_e64 s[8:9], v18, v16
	v_cmp_gt_f32_e64 s[10:11], v22, v20
	v_cmp_gt_f32_e64 s[12:13], v26, v24
	v_cmp_gt_f32_e64 s[24:25], v30, v28
	v_cndmask_b32_e64 v16, v16, v18, s[8:9]
	v_cndmask_b32_e64 v32, v32, v33, s[8:9]
	v_cndmask_b32_e64 v20, v20, v22, s[10:11]
	v_cndmask_b32_e64 v34, v34, v35, s[10:11]
	v_cndmask_b32_e64 v24, v24, v26, s[12:13]
	v_cndmask_b32_e64 v36, v36, v37, s[12:13]
	v_cndmask_b32_e64 v28, v28, v30, s[24:25]
	v_cndmask_b32_e64 v38, v38, v39, s[24:25]
	v_cmp_gt_f32_e64 s[8:9], v20, v16
	v_cmp_gt_f32_e64 s[10:11], v28, v24
	s_nop 0
	v_cndmask_b32_e64 v16, v16, v20, s[8:9]
	v_cndmask_b32_e64 v32, v32, v34, s[8:9]
	v_cndmask_b32_e64 v24, v24, v28, s[10:11]
	v_cndmask_b32_e64 v36, v36, v38, s[10:11]
	v_cmp_gt_f32_e64 s[8:9], v24, v16
	s_nop 1
	v_cndmask_b32_e64 v16, v16, v24, s[8:9]
	v_cndmask_b32_e64 v32, v32, v36, s[8:9]
	v_lshl_add_u32 v148, v44, 4, v32
	v_cmp_eq_u32_e64 s[8:9], 0, v44
	v_cmp_eq_u32_e64 s[10:11], 1, v44
	v_cmp_eq_u32_e64 s[12:13], 2, v44
	v_cmp_eq_u32_e64 s[24:25], 3, v44
	v_cmp_eq_u32_e64 s[26:27], 4, v44
	v_cmp_eq_u32_e64 s[28:29], 5, v44
	v_cmp_eq_u32_e64 s[30:31], 6, v44
	v_cmp_eq_u32_e64 s[34:35], 7, v44
	v_cndmask_b32_e64 v0, v0, v16, s[8:9]
	v_cndmask_b32_e64 v8, v8, v148, s[8:9]
	v_cndmask_b32_e64 v1, v1, v16, s[10:11]
	v_cndmask_b32_e64 v9, v9, v148, s[10:11]
	v_cndmask_b32_e64 v2, v2, v16, s[12:13]
	v_cndmask_b32_e64 v10, v10, v148, s[12:13]
	v_cndmask_b32_e64 v3, v3, v16, s[24:25]
	v_cndmask_b32_e64 v11, v11, v148, s[24:25]
	v_cndmask_b32_e64 v4, v4, v16, s[26:27]
	v_cndmask_b32_e64 v12, v12, v148, s[26:27]
	v_cndmask_b32_e64 v5, v5, v16, s[28:29]
	v_cndmask_b32_e64 v13, v13, v148, s[28:29]
	v_cndmask_b32_e64 v6, v6, v16, s[30:31]
	v_cndmask_b32_e64 v14, v14, v148, s[30:31]
	v_cndmask_b32_e64 v7, v7, v16, s[34:35]
	v_cndmask_b32_e64 v15, v15, v148, s[34:35]
	v_cmp_gt_f32_e64 s[8:9], v1, v0
	v_cmp_gt_f32_e64 s[10:11], v3, v2
	v_cmp_gt_f32_e64 s[12:13], v5, v4
	v_cmp_gt_f32_e64 s[24:25], v7, v6
	v_cndmask_b32_e64 v40, v0, v1, s[8:9]
	v_cndmask_b32_e64 v44, 0, 1, s[8:9]
	v_cndmask_b32_e64 v141, v8, v9, s[8:9]
	v_cndmask_b32_e64 v41, v2, v3, s[10:11]
	v_cndmask_b32_e64 v45, 2, 3, s[10:11]
	v_cndmask_b32_e64 v142, v10, v11, s[10:11]
	v_cndmask_b32_e64 v42, v4, v5, s[12:13]
	v_cndmask_b32_e64 v46, 4, 5, s[12:13]
	v_cndmask_b32_e64 v143, v12, v13, s[12:13]
	v_cndmask_b32_e64 v43, v6, v7, s[24:25]
	v_cndmask_b32_e64 v47, 6, 7, s[24:25]
	v_cndmask_b32_e64 v144, v14, v15, s[24:25]
	v_cmp_gt_f32_e64 s[8:9], v41, v40
	v_cmp_gt_f32_e64 s[10:11], v43, v42
	s_nop 0
	v_cndmask_b32_e64 v40, v40, v41, s[8:9]
	v_cndmask_b32_e64 v44, v44, v45, s[8:9]
	v_cndmask_b32_e64 v141, v141, v142, s[8:9]
	v_cndmask_b32_e64 v42, v42, v43, s[10:11]
	v_cndmask_b32_e64 v46, v46, v47, s[10:11]
	v_cndmask_b32_e64 v143, v143, v144, s[10:11]
	v_cmp_gt_f32_e64 s[8:9], v42, v40
	s_nop 1
	v_cndmask_b32_e64 v40, v40, v42, s[8:9]
	v_cndmask_b32_e64 v44, v44, v46, s[8:9]
	v_cndmask_b32_e64 v141, v141, v143, s[8:9]
	ds_write_b32 v149, v40 offset:5120
	ds_write_b8 v150, v141 offset:1280
	v_lshl_add_u32 v146, v141, 2, v54
	ds_write_b32 v146, v60
	v_lshl_add_u32 v147, v44, 6, v54
	ds_read2_b32 v[16:17], v147 offset0:0 offset1:1
	ds_read2_b32 v[18:19], v147 offset0:2 offset1:3
	ds_read2_b32 v[20:21], v147 offset0:4 offset1:5
	ds_read2_b32 v[22:23], v147 offset0:6 offset1:7
	ds_read2_b32 v[24:25], v147 offset0:8 offset1:9
	ds_read2_b32 v[26:27], v147 offset0:10 offset1:11
	ds_read2_b32 v[28:29], v147 offset0:12 offset1:13
	ds_read2_b32 v[30:31], v147 offset0:14 offset1:15
	s_waitcnt lgkmcnt(0)
; DI void peer_topk_item(const Params& p, int tt128, int head, char* smem) {
;     ...
; #pragma unroll 1
;     for (int r = 0; r < 16; ++r) {
;       float best = gm[0]; int bg = 0; int bi = gi[0];
; #pragma unroll
;       for (int g = 1; g < 8; ++g) if (gm[g] > best) { best = gm[g]; bg = g; bi = gi[g]; }
;       topv[tid * 16 + r] = best; topi[tid * 16 + r] = (unsigned char)bi;
;       row[bi] = -INFINITY;
;       float m = -INFINITY; int mi = bg * 16;
; #pragma unroll
;       for (int j = 0; j < 16; ++j) { float v = row[bg * 16 + j]; if (v > m) { m = v; mi = bg * 16 + j; } }
; #pragma unroll
;       for (int g = 0; g < 8; ++g) { gm[g] = (g == bg) ? m : gm[g]; gi[g] = (g == bg) ? mi : gi[g]; }
;     }
	v_cmp_gt_f32_e64 s[8:9], v17, v16
	v_cmp_gt_f32_e64 s[10:11], v19, v18
	v_cmp_gt_f32_e64 s[12:13], v21, v20
	v_cmp_gt_f32_e64 s[24:25], v23, v22
	v_cmp_gt_f32_e64 s[26:27], v25, v24
	v_cmp_gt_f32_e64 s[28:29], v27, v26
	v_cmp_gt_f32_e64 s[30:31], v29, v28
	v_cmp_gt_f32_e64 s[34:35], v31, v30
	v_cndmask_b32_e64 v16, v16, v17, s[8:9]
	v_cndmask_b32_e64 v32, 0, 1, s[8:9]
	v_cndmask_b32_e64 v18, v18, v19, s[10:11]
	v_cndmask_b32_e64 v33, 2, 3, s[10:11]
	v_cndmask_b32_e64 v20, v20, v21, s[12:13]
	v_cndmask_b32_e64 v34, 4, 5, s[12:13]
	v_cndmask_b32_e64 v22, v22, v23, s[24:25]
	v_cndmask_b32_e64 v35, 6, 7, s[24:25]
	v_cndmask_b32_e64 v24, v24, v25, s[26:27]
	v_cndmask_b32_e64 v36, 8, 9, s[26:27]
	v_cndmask_b32_e64 v26, v26, v27, s[28:29]
	v_cndmask_b32_e64 v37, 10, 11, s[28:29]
	v_cndmask_b32_e64 v28, v28, v29, s[30:31]
	v_cndmask_b32_e64 v38, 12, 13, s[30:31]
	v_cndmask_b32_e64 v30, v30, v31, s[34:35]
	v_cndmask_b32_e64 v39, 14, 15, s[34:35]
	v_cmp_gt_f32_e64 s[8:9], v18, v16
	v_cmp_gt_f32_e64 s[10:11], v22, v20
	v_cmp_gt_f32_e64 s[12:13], v26, v24
	v_cmp_gt_f32_e64 s[24:25], v30, v28
	v_cndmask_b32_e64 v16, v16, v18, s[8:9]
	v_cndmask_b32_e64 v32, v32, v33, s[8:9]
	v_cndmask_b32_e64 v20, v20, v22, s[10:11]
	v_cndmask_b32_e64 v34, v34, v35, s[10:11]
	v_cndmask_b32_e64 v24, v24, v26, s[12:13]
	v_cndmask_b32_e64 v36, v36, v37, s[12:13]
	v_cndmask_b32_e64 v28, v28, v30, s[24:25]
	v_cndmask_b32_e64 v38, v38, v39, s[24:25]
	v_cmp_gt_f32_e64 s[8:9], v20, v16
	v_cmp_gt_f32_e64 s[10:11], v28, v24
	s_nop 0
	v_cndmask_b32_e64 v16, v16, v20, s[8:9]
	v_cndmask_b32_e64 v32, v32, v34, s[8:9]
	v_cndmask_b32_e64 v24, v24, v28, s[10:11]
	v_cndmask_b32_e64 v36, v36, v38, s[10:11]
	v_cmp_gt_f32_e64 s[8:9], v24, v16
	s_nop 1
	v_cndmask_b32_e64 v16, v16, v24, s[8:9]
	v_cndmask_b32_e64 v32, v32, v36, s[8:9]
	v_lshl_add_u32 v148, v44, 4, v32
	v_cmp_eq_u32_e64 s[8:9], 0, v44
	v_cmp_eq_u32_e64 s[10:11], 1, v44
	v_cmp_eq_u32_e64 s[12:13], 2, v44
	v_cmp_eq_u32_e64 s[24:25], 3, v44
	v_cmp_eq_u32_e64 s[26:27], 4, v44
	v_cmp_eq_u32_e64 s[28:29], 5, v44
	v_cmp_eq_u32_e64 s[30:31], 6, v44
	v_cmp_eq_u32_e64 s[34:35], 7, v44
	v_cndmask_b32_e64 v0, v0, v16, s[8:9]
	v_cndmask_b32_e64 v8, v8, v148, s[8:9]
	v_cndmask_b32_e64 v1, v1, v16, s[10:11]
	v_cndmask_b32_e64 v9, v9, v148, s[10:11]
	v_cndmask_b32_e64 v2, v2, v16, s[12:13]
	v_cndmask_b32_e64 v10, v10, v148, s[12:13]
	v_cndmask_b32_e64 v3, v3, v16, s[24:25]
	v_cndmask_b32_e64 v11, v11, v148, s[24:25]
	v_cndmask_b32_e64 v4, v4, v16, s[26:27]
	v_cndmask_b32_e64 v12, v12, v148, s[26:27]
	v_cndmask_b32_e64 v5, v5, v16, s[28:29]
	v_cndmask_b32_e64 v13, v13, v148, s[28:29]
	v_cndmask_b32_e64 v6, v6, v16, s[30:31]
	v_cndmask_b32_e64 v14, v14, v148, s[30:31]
	v_cndmask_b32_e64 v7, v7, v16, s[34:35]
	v_cndmask_b32_e64 v15, v15, v148, s[34:35]
	v_cmp_gt_f32_e64 s[8:9], v1, v0
	v_cmp_gt_f32_e64 s[10:11], v3, v2
	v_cmp_gt_f32_e64 s[12:13], v5, v4
	v_cmp_gt_f32_e64 s[24:25], v7, v6
	v_cndmask_b32_e64 v40, v0, v1, s[8:9]
	v_cndmask_b32_e64 v44, 0, 1, s[8:9]
	v_cndmask_b32_e64 v141, v8, v9, s[8:9]
	v_cndmask_b32_e64 v41, v2, v3, s[10:11]
	v_cndmask_b32_e64 v45, 2, 3, s[10:11]
	v_cndmask_b32_e64 v142, v10, v11, s[10:11]
	v_cndmask_b32_e64 v42, v4, v5, s[12:13]
	v_cndmask_b32_e64 v46, 4, 5, s[12:13]
	v_cndmask_b32_e64 v143, v12, v13, s[12:13]
	v_cndmask_b32_e64 v43, v6, v7, s[24:25]
	v_cndmask_b32_e64 v47, 6, 7, s[24:25]
	v_cndmask_b32_e64 v144, v14, v15, s[24:25]
	v_cmp_gt_f32_e64 s[8:9], v41, v40
	v_cmp_gt_f32_e64 s[10:11], v43, v42
	s_nop 0
	v_cndmask_b32_e64 v40, v40, v41, s[8:9]
	v_cndmask_b32_e64 v44, v44, v45, s[8:9]
	v_cndmask_b32_e64 v141, v141, v142, s[8:9]
	v_cndmask_b32_e64 v42, v42, v43, s[10:11]
	v_cndmask_b32_e64 v46, v46, v47, s[10:11]
	v_cndmask_b32_e64 v143, v143, v144, s[10:11]
	v_cmp_gt_f32_e64 s[8:9], v42, v40
	s_nop 1
	v_cndmask_b32_e64 v40, v40, v42, s[8:9]
	v_cndmask_b32_e64 v44, v44, v46, s[8:9]
	v_cndmask_b32_e64 v141, v141, v143, s[8:9]
	ds_write_b32 v149, v40 offset:6144
	ds_write_b8 v150, v141 offset:1536
	v_lshl_add_u32 v146, v141, 2, v54
	ds_write_b32 v146, v60
	v_lshl_add_u32 v147, v44, 6, v54
	ds_read2_b32 v[16:17], v147 offset0:0 offset1:1
	ds_read2_b32 v[18:19], v147 offset0:2 offset1:3
	ds_read2_b32 v[20:21], v147 offset0:4 offset1:5
	ds_read2_b32 v[22:23], v147 offset0:6 offset1:7
	ds_read2_b32 v[24:25], v147 offset0:8 offset1:9
	ds_read2_b32 v[26:27], v147 offset0:10 offset1:11
	ds_read2_b32 v[28:29], v147 offset0:12 offset1:13
	ds_read2_b32 v[30:31], v147 offset0:14 offset1:15
	s_waitcnt lgkmcnt(0)
; DI void peer_topk_item(const Params& p, int tt128, int head, char* smem) {
;     ...
; #pragma unroll 1
;     for (int r = 0; r < 16; ++r) {
;       float best = gm[0]; int bg = 0; int bi = gi[0];
; #pragma unroll
;       for (int g = 1; g < 8; ++g) if (gm[g] > best) { best = gm[g]; bg = g; bi = gi[g]; }
;       topv[tid * 16 + r] = best; topi[tid * 16 + r] = (unsigned char)bi;
;       row[bi] = -INFINITY;
;       float m = -INFINITY; int mi = bg * 16;
; #pragma unroll
;       for (int j = 0; j < 16; ++j) { float v = row[bg * 16 + j]; if (v > m) { m = v; mi = bg * 16 + j; } }
; #pragma unroll
;       for (int g = 0; g < 8; ++g) { gm[g] = (g == bg) ? m : gm[g]; gi[g] = (g == bg) ? mi : gi[g]; }
;     }
	v_cmp_gt_f32_e64 s[8:9], v17, v16
	v_cmp_gt_f32_e64 s[10:11], v19, v18
	v_cmp_gt_f32_e64 s[12:13], v21, v20
	v_cmp_gt_f32_e64 s[24:25], v23, v22
	v_cmp_gt_f32_e64 s[26:27], v25, v24
	v_cmp_gt_f32_e64 s[28:29], v27, v26
	v_cmp_gt_f32_e64 s[30:31], v29, v28
	v_cmp_gt_f32_e64 s[34:35], v31, v30
	v_cndmask_b32_e64 v16, v16, v17, s[8:9]
	v_cndmask_b32_e64 v32, 0, 1, s[8:9]
	v_cndmask_b32_e64 v18, v18, v19, s[10:11]
	v_cndmask_b32_e64 v33, 2, 3, s[10:11]
	v_cndmask_b32_e64 v20, v20, v21, s[12:13]
	v_cndmask_b32_e64 v34, 4, 5, s[12:13]
	v_cndmask_b32_e64 v22, v22, v23, s[24:25]
	v_cndmask_b32_e64 v35, 6, 7, s[24:25]
	v_cndmask_b32_e64 v24, v24, v25, s[26:27]
	v_cndmask_b32_e64 v36, 8, 9, s[26:27]
	v_cndmask_b32_e64 v26, v26, v27, s[28:29]
	v_cndmask_b32_e64 v37, 10, 11, s[28:29]
	v_cndmask_b32_e64 v28, v28, v29, s[30:31]
	v_cndmask_b32_e64 v38, 12, 13, s[30:31]
	v_cndmask_b32_e64 v30, v30, v31, s[34:35]
	v_cndmask_b32_e64 v39, 14, 15, s[34:35]
	v_cmp_gt_f32_e64 s[8:9], v18, v16
	v_cmp_gt_f32_e64 s[10:11], v22, v20
	v_cmp_gt_f32_e64 s[12:13], v26, v24
	v_cmp_gt_f32_e64 s[24:25], v30, v28
	v_cndmask_b32_e64 v16, v16, v18, s[8:9]
	v_cndmask_b32_e64 v32, v32, v33, s[8:9]
	v_cndmask_b32_e64 v20, v20, v22, s[10:11]
	v_cndmask_b32_e64 v34, v34, v35, s[10:11]
	v_cndmask_b32_e64 v24, v24, v26, s[12:13]
	v_cndmask_b32_e64 v36, v36, v37, s[12:13]
	v_cndmask_b32_e64 v28, v28, v30, s[24:25]
	v_cndmask_b32_e64 v38, v38, v39, s[24:25]
	v_cmp_gt_f32_e64 s[8:9], v20, v16
	v_cmp_gt_f32_e64 s[10:11], v28, v24
	s_nop 0
	v_cndmask_b32_e64 v16, v16, v20, s[8:9]
	v_cndmask_b32_e64 v32, v32, v34, s[8:9]
	v_cndmask_b32_e64 v24, v24, v28, s[10:11]
	v_cndmask_b32_e64 v36, v36, v38, s[10:11]
	v_cmp_gt_f32_e64 s[8:9], v24, v16
	s_nop 1
	v_cndmask_b32_e64 v16, v16, v24, s[8:9]
	v_cndmask_b32_e64 v32, v32, v36, s[8:9]
	v_lshl_add_u32 v148, v44, 4, v32
	v_cmp_eq_u32_e64 s[8:9], 0, v44
	v_cmp_eq_u32_e64 s[10:11], 1, v44
	v_cmp_eq_u32_e64 s[12:13], 2, v44
	v_cmp_eq_u32_e64 s[24:25], 3, v44
	v_cmp_eq_u32_e64 s[26:27], 4, v44
	v_cmp_eq_u32_e64 s[28:29], 5, v44
	v_cmp_eq_u32_e64 s[30:31], 6, v44
	v_cmp_eq_u32_e64 s[34:35], 7, v44
	v_cndmask_b32_e64 v0, v0, v16, s[8:9]
	v_cndmask_b32_e64 v8, v8, v148, s[8:9]
	v_cndmask_b32_e64 v1, v1, v16, s[10:11]
	v_cndmask_b32_e64 v9, v9, v148, s[10:11]
	v_cndmask_b32_e64 v2, v2, v16, s[12:13]
	v_cndmask_b32_e64 v10, v10, v148, s[12:13]
	v_cndmask_b32_e64 v3, v3, v16, s[24:25]
	v_cndmask_b32_e64 v11, v11, v148, s[24:25]
	v_cndmask_b32_e64 v4, v4, v16, s[26:27]
	v_cndmask_b32_e64 v12, v12, v148, s[26:27]
	v_cndmask_b32_e64 v5, v5, v16, s[28:29]
	v_cndmask_b32_e64 v13, v13, v148, s[28:29]
	v_cndmask_b32_e64 v6, v6, v16, s[30:31]
	v_cndmask_b32_e64 v14, v14, v148, s[30:31]
	v_cndmask_b32_e64 v7, v7, v16, s[34:35]
	v_cndmask_b32_e64 v15, v15, v148, s[34:35]
	v_cmp_gt_f32_e64 s[8:9], v1, v0
	v_cmp_gt_f32_e64 s[10:11], v3, v2
	v_cmp_gt_f32_e64 s[12:13], v5, v4
	v_cmp_gt_f32_e64 s[24:25], v7, v6
	v_cndmask_b32_e64 v40, v0, v1, s[8:9]
	v_cndmask_b32_e64 v44, 0, 1, s[8:9]
	v_cndmask_b32_e64 v141, v8, v9, s[8:9]
	v_cndmask_b32_e64 v41, v2, v3, s[10:11]
	v_cndmask_b32_e64 v45, 2, 3, s[10:11]
	v_cndmask_b32_e64 v142, v10, v11, s[10:11]
	v_cndmask_b32_e64 v42, v4, v5, s[12:13]
	v_cndmask_b32_e64 v46, 4, 5, s[12:13]
	v_cndmask_b32_e64 v143, v12, v13, s[12:13]
	v_cndmask_b32_e64 v43, v6, v7, s[24:25]
	v_cndmask_b32_e64 v47, 6, 7, s[24:25]
	v_cndmask_b32_e64 v144, v14, v15, s[24:25]
	v_cmp_gt_f32_e64 s[8:9], v41, v40
	v_cmp_gt_f32_e64 s[10:11], v43, v42
	s_nop 0
	v_cndmask_b32_e64 v40, v40, v41, s[8:9]
	v_cndmask_b32_e64 v44, v44, v45, s[8:9]
	v_cndmask_b32_e64 v141, v141, v142, s[8:9]
	v_cndmask_b32_e64 v42, v42, v43, s[10:11]
	v_cndmask_b32_e64 v46, v46, v47, s[10:11]
	v_cndmask_b32_e64 v143, v143, v144, s[10:11]
	v_cmp_gt_f32_e64 s[8:9], v42, v40
	s_nop 1
	v_cndmask_b32_e64 v40, v40, v42, s[8:9]
	v_cndmask_b32_e64 v44, v44, v46, s[8:9]
	v_cndmask_b32_e64 v141, v141, v143, s[8:9]
	ds_write_b32 v149, v40 offset:7168
	ds_write_b8 v150, v141 offset:1792
	v_lshl_add_u32 v146, v141, 2, v54
	ds_write_b32 v146, v60
	v_lshl_add_u32 v147, v44, 6, v54
	ds_read2_b32 v[16:17], v147 offset0:0 offset1:1
	ds_read2_b32 v[18:19], v147 offset0:2 offset1:3
	ds_read2_b32 v[20:21], v147 offset0:4 offset1:5
	ds_read2_b32 v[22:23], v147 offset0:6 offset1:7
	ds_read2_b32 v[24:25], v147 offset0:8 offset1:9
	ds_read2_b32 v[26:27], v147 offset0:10 offset1:11
	ds_read2_b32 v[28:29], v147 offset0:12 offset1:13
	ds_read2_b32 v[30:31], v147 offset0:14 offset1:15
	s_waitcnt lgkmcnt(0)
; DI void peer_topk_item(const Params& p, int tt128, int head, char* smem) {
;     ...
; #pragma unroll 1
;     for (int r = 0; r < 16; ++r) {
;       float best = gm[0]; int bg = 0; int bi = gi[0];
; #pragma unroll
;       for (int g = 1; g < 8; ++g) if (gm[g] > best) { best = gm[g]; bg = g; bi = gi[g]; }
;       topv[tid * 16 + r] = best; topi[tid * 16 + r] = (unsigned char)bi;
;       row[bi] = -INFINITY;
;       float m = -INFINITY; int mi = bg * 16;
; #pragma unroll
;       for (int j = 0; j < 16; ++j) { float v = row[bg * 16 + j]; if (v > m) { m = v; mi = bg * 16 + j; } }
; #pragma unroll
;       for (int g = 0; g < 8; ++g) { gm[g] = (g == bg) ? m : gm[g]; gi[g] = (g == bg) ? mi : gi[g]; }
;     }
	v_cmp_gt_f32_e64 s[8:9], v17, v16
	v_cmp_gt_f32_e64 s[10:11], v19, v18
	v_cmp_gt_f32_e64 s[12:13], v21, v20
	v_cmp_gt_f32_e64 s[24:25], v23, v22
	v_cmp_gt_f32_e64 s[26:27], v25, v24
	v_cmp_gt_f32_e64 s[28:29], v27, v26
	v_cmp_gt_f32_e64 s[30:31], v29, v28
	v_cmp_gt_f32_e64 s[34:35], v31, v30
	v_cndmask_b32_e64 v16, v16, v17, s[8:9]
	v_cndmask_b32_e64 v32, 0, 1, s[8:9]
	v_cndmask_b32_e64 v18, v18, v19, s[10:11]
	v_cndmask_b32_e64 v33, 2, 3, s[10:11]
	v_cndmask_b32_e64 v20, v20, v21, s[12:13]
	v_cndmask_b32_e64 v34, 4, 5, s[12:13]
	v_cndmask_b32_e64 v22, v22, v23, s[24:25]
	v_cndmask_b32_e64 v35, 6, 7, s[24:25]
	v_cndmask_b32_e64 v24, v24, v25, s[26:27]
	v_cndmask_b32_e64 v36, 8, 9, s[26:27]
	v_cndmask_b32_e64 v26, v26, v27, s[28:29]
	v_cndmask_b32_e64 v37, 10, 11, s[28:29]
	v_cndmask_b32_e64 v28, v28, v29, s[30:31]
	v_cndmask_b32_e64 v38, 12, 13, s[30:31]
	v_cndmask_b32_e64 v30, v30, v31, s[34:35]
	v_cndmask_b32_e64 v39, 14, 15, s[34:35]
	v_cmp_gt_f32_e64 s[8:9], v18, v16
	v_cmp_gt_f32_e64 s[10:11], v22, v20
	v_cmp_gt_f32_e64 s[12:13], v26, v24
	v_cmp_gt_f32_e64 s[24:25], v30, v28
	v_cndmask_b32_e64 v16, v16, v18, s[8:9]
	v_cndmask_b32_e64 v32, v32, v33, s[8:9]
	v_cndmask_b32_e64 v20, v20, v22, s[10:11]
	v_cndmask_b32_e64 v34, v34, v35, s[10:11]
	v_cndmask_b32_e64 v24, v24, v26, s[12:13]
	v_cndmask_b32_e64 v36, v36, v37, s[12:13]
	v_cndmask_b32_e64 v28, v28, v30, s[24:25]
	v_cndmask_b32_e64 v38, v38, v39, s[24:25]
	v_cmp_gt_f32_e64 s[8:9], v20, v16
	v_cmp_gt_f32_e64 s[10:11], v28, v24
	s_nop 0
	v_cndmask_b32_e64 v16, v16, v20, s[8:9]
	v_cndmask_b32_e64 v32, v32, v34, s[8:9]
	v_cndmask_b32_e64 v24, v24, v28, s[10:11]
	v_cndmask_b32_e64 v36, v36, v38, s[10:11]
	v_cmp_gt_f32_e64 s[8:9], v24, v16
	s_nop 1
	v_cndmask_b32_e64 v16, v16, v24, s[8:9]
	v_cndmask_b32_e64 v32, v32, v36, s[8:9]
	v_lshl_add_u32 v148, v44, 4, v32
	v_cmp_eq_u32_e64 s[8:9], 0, v44
	v_cmp_eq_u32_e64 s[10:11], 1, v44
	v_cmp_eq_u32_e64 s[12:13], 2, v44
	v_cmp_eq_u32_e64 s[24:25], 3, v44
	v_cmp_eq_u32_e64 s[26:27], 4, v44
	v_cmp_eq_u32_e64 s[28:29], 5, v44
	v_cmp_eq_u32_e64 s[30:31], 6, v44
	v_cmp_eq_u32_e64 s[34:35], 7, v44
	v_cndmask_b32_e64 v0, v0, v16, s[8:9]
	v_cndmask_b32_e64 v8, v8, v148, s[8:9]
	v_cndmask_b32_e64 v1, v1, v16, s[10:11]
	v_cndmask_b32_e64 v9, v9, v148, s[10:11]
	v_cndmask_b32_e64 v2, v2, v16, s[12:13]
	v_cndmask_b32_e64 v10, v10, v148, s[12:13]
	v_cndmask_b32_e64 v3, v3, v16, s[24:25]
	v_cndmask_b32_e64 v11, v11, v148, s[24:25]
	v_cndmask_b32_e64 v4, v4, v16, s[26:27]
	v_cndmask_b32_e64 v12, v12, v148, s[26:27]
	v_cndmask_b32_e64 v5, v5, v16, s[28:29]
	v_cndmask_b32_e64 v13, v13, v148, s[28:29]
	v_cndmask_b32_e64 v6, v6, v16, s[30:31]
	v_cndmask_b32_e64 v14, v14, v148, s[30:31]
	v_cndmask_b32_e64 v7, v7, v16, s[34:35]
	v_cndmask_b32_e64 v15, v15, v148, s[34:35]
	v_cmp_gt_f32_e64 s[8:9], v1, v0
	v_cmp_gt_f32_e64 s[10:11], v3, v2
	v_cmp_gt_f32_e64 s[12:13], v5, v4
	v_cmp_gt_f32_e64 s[24:25], v7, v6
	v_cndmask_b32_e64 v40, v0, v1, s[8:9]
	v_cndmask_b32_e64 v44, 0, 1, s[8:9]
	v_cndmask_b32_e64 v141, v8, v9, s[8:9]
	v_cndmask_b32_e64 v41, v2, v3, s[10:11]
	v_cndmask_b32_e64 v45, 2, 3, s[10:11]
	v_cndmask_b32_e64 v142, v10, v11, s[10:11]
	v_cndmask_b32_e64 v42, v4, v5, s[12:13]
	v_cndmask_b32_e64 v46, 4, 5, s[12:13]
	v_cndmask_b32_e64 v143, v12, v13, s[12:13]
	v_cndmask_b32_e64 v43, v6, v7, s[24:25]
	v_cndmask_b32_e64 v47, 6, 7, s[24:25]
	v_cndmask_b32_e64 v144, v14, v15, s[24:25]
	v_cmp_gt_f32_e64 s[8:9], v41, v40
	v_cmp_gt_f32_e64 s[10:11], v43, v42
	s_nop 0
	v_cndmask_b32_e64 v40, v40, v41, s[8:9]
	v_cndmask_b32_e64 v44, v44, v45, s[8:9]
	v_cndmask_b32_e64 v141, v141, v142, s[8:9]
	v_cndmask_b32_e64 v42, v42, v43, s[10:11]
	v_cndmask_b32_e64 v46, v46, v47, s[10:11]
	v_cndmask_b32_e64 v143, v143, v144, s[10:11]
	v_cmp_gt_f32_e64 s[8:9], v42, v40
	s_nop 1
	v_cndmask_b32_e64 v40, v40, v42, s[8:9]
	v_cndmask_b32_e64 v44, v44, v46, s[8:9]
	v_cndmask_b32_e64 v141, v141, v143, s[8:9]
	ds_write_b32 v149, v40 offset:8192
	ds_write_b8 v150, v141 offset:2048
	v_lshl_add_u32 v146, v141, 2, v54
	ds_write_b32 v146, v60
	v_lshl_add_u32 v147, v44, 6, v54
	ds_read2_b32 v[16:17], v147 offset0:0 offset1:1
	ds_read2_b32 v[18:19], v147 offset0:2 offset1:3
	ds_read2_b32 v[20:21], v147 offset0:4 offset1:5
	ds_read2_b32 v[22:23], v147 offset0:6 offset1:7
	ds_read2_b32 v[24:25], v147 offset0:8 offset1:9
	ds_read2_b32 v[26:27], v147 offset0:10 offset1:11
	ds_read2_b32 v[28:29], v147 offset0:12 offset1:13
	ds_read2_b32 v[30:31], v147 offset0:14 offset1:15
	s_waitcnt lgkmcnt(0)
; DI void peer_topk_item(const Params& p, int tt128, int head, char* smem) {
;     ...
; #pragma unroll 1
;     for (int r = 0; r < 16; ++r) {
;       float best = gm[0]; int bg = 0; int bi = gi[0];
; #pragma unroll
;       for (int g = 1; g < 8; ++g) if (gm[g] > best) { best = gm[g]; bg = g; bi = gi[g]; }
;       topv[tid * 16 + r] = best; topi[tid * 16 + r] = (unsigned char)bi;
;       row[bi] = -INFINITY;
;       float m = -INFINITY; int mi = bg * 16;
; #pragma unroll
;       for (int j = 0; j < 16; ++j) { float v = row[bg * 16 + j]; if (v > m) { m = v; mi = bg * 16 + j; } }
; #pragma unroll
;       for (int g = 0; g < 8; ++g) { gm[g] = (g == bg) ? m : gm[g]; gi[g] = (g == bg) ? mi : gi[g]; }
;     }
	v_cmp_gt_f32_e64 s[8:9], v17, v16
	v_cmp_gt_f32_e64 s[10:11], v19, v18
	v_cmp_gt_f32_e64 s[12:13], v21, v20
	v_cmp_gt_f32_e64 s[24:25], v23, v22
	v_cmp_gt_f32_e64 s[26:27], v25, v24
	v_cmp_gt_f32_e64 s[28:29], v27, v26
	v_cmp_gt_f32_e64 s[30:31], v29, v28
	v_cmp_gt_f32_e64 s[34:35], v31, v30
	v_cndmask_b32_e64 v16, v16, v17, s[8:9]
	v_cndmask_b32_e64 v32, 0, 1, s[8:9]
	v_cndmask_b32_e64 v18, v18, v19, s[10:11]
	v_cndmask_b32_e64 v33, 2, 3, s[10:11]
	v_cndmask_b32_e64 v20, v20, v21, s[12:13]
	v_cndmask_b32_e64 v34, 4, 5, s[12:13]
	v_cndmask_b32_e64 v22, v22, v23, s[24:25]
	v_cndmask_b32_e64 v35, 6, 7, s[24:25]
	v_cndmask_b32_e64 v24, v24, v25, s[26:27]
	v_cndmask_b32_e64 v36, 8, 9, s[26:27]
	v_cndmask_b32_e64 v26, v26, v27, s[28:29]
	v_cndmask_b32_e64 v37, 10, 11, s[28:29]
	v_cndmask_b32_e64 v28, v28, v29, s[30:31]
	v_cndmask_b32_e64 v38, 12, 13, s[30:31]
	v_cndmask_b32_e64 v30, v30, v31, s[34:35]
	v_cndmask_b32_e64 v39, 14, 15, s[34:35]
	v_cmp_gt_f32_e64 s[8:9], v18, v16
	v_cmp_gt_f32_e64 s[10:11], v22, v20
	v_cmp_gt_f32_e64 s[12:13], v26, v24
	v_cmp_gt_f32_e64 s[24:25], v30, v28
	v_cndmask_b32_e64 v16, v16, v18, s[8:9]
	v_cndmask_b32_e64 v32, v32, v33, s[8:9]
	v_cndmask_b32_e64 v20, v20, v22, s[10:11]
	v_cndmask_b32_e64 v34, v34, v35, s[10:11]
	v_cndmask_b32_e64 v24, v24, v26, s[12:13]
	v_cndmask_b32_e64 v36, v36, v37, s[12:13]
	v_cndmask_b32_e64 v28, v28, v30, s[24:25]
	v_cndmask_b32_e64 v38, v38, v39, s[24:25]
	v_cmp_gt_f32_e64 s[8:9], v20, v16
	v_cmp_gt_f32_e64 s[10:11], v28, v24
	s_nop 0
	v_cndmask_b32_e64 v16, v16, v20, s[8:9]
	v_cndmask_b32_e64 v32, v32, v34, s[8:9]
	v_cndmask_b32_e64 v24, v24, v28, s[10:11]
	v_cndmask_b32_e64 v36, v36, v38, s[10:11]
	v_cmp_gt_f32_e64 s[8:9], v24, v16
	s_nop 1
	v_cndmask_b32_e64 v16, v16, v24, s[8:9]
	v_cndmask_b32_e64 v32, v32, v36, s[8:9]
	v_lshl_add_u32 v148, v44, 4, v32
	v_cmp_eq_u32_e64 s[8:9], 0, v44
	v_cmp_eq_u32_e64 s[10:11], 1, v44
	v_cmp_eq_u32_e64 s[12:13], 2, v44
	v_cmp_eq_u32_e64 s[24:25], 3, v44
	v_cmp_eq_u32_e64 s[26:27], 4, v44
	v_cmp_eq_u32_e64 s[28:29], 5, v44
	v_cmp_eq_u32_e64 s[30:31], 6, v44
	v_cmp_eq_u32_e64 s[34:35], 7, v44
	v_cndmask_b32_e64 v0, v0, v16, s[8:9]
	v_cndmask_b32_e64 v8, v8, v148, s[8:9]
	v_cndmask_b32_e64 v1, v1, v16, s[10:11]
	v_cndmask_b32_e64 v9, v9, v148, s[10:11]
	v_cndmask_b32_e64 v2, v2, v16, s[12:13]
	v_cndmask_b32_e64 v10, v10, v148, s[12:13]
	v_cndmask_b32_e64 v3, v3, v16, s[24:25]
	v_cndmask_b32_e64 v11, v11, v148, s[24:25]
	v_cndmask_b32_e64 v4, v4, v16, s[26:27]
	v_cndmask_b32_e64 v12, v12, v148, s[26:27]
	v_cndmask_b32_e64 v5, v5, v16, s[28:29]
	v_cndmask_b32_e64 v13, v13, v148, s[28:29]
	v_cndmask_b32_e64 v6, v6, v16, s[30:31]
	v_cndmask_b32_e64 v14, v14, v148, s[30:31]
	v_cndmask_b32_e64 v7, v7, v16, s[34:35]
	v_cndmask_b32_e64 v15, v15, v148, s[34:35]
	v_cmp_gt_f32_e64 s[8:9], v1, v0
	v_cmp_gt_f32_e64 s[10:11], v3, v2
	v_cmp_gt_f32_e64 s[12:13], v5, v4
	v_cmp_gt_f32_e64 s[24:25], v7, v6
	v_cndmask_b32_e64 v40, v0, v1, s[8:9]
	v_cndmask_b32_e64 v44, 0, 1, s[8:9]
	v_cndmask_b32_e64 v141, v8, v9, s[8:9]
	v_cndmask_b32_e64 v41, v2, v3, s[10:11]
	v_cndmask_b32_e64 v45, 2, 3, s[10:11]
	v_cndmask_b32_e64 v142, v10, v11, s[10:11]
	v_cndmask_b32_e64 v42, v4, v5, s[12:13]
	v_cndmask_b32_e64 v46, 4, 5, s[12:13]
	v_cndmask_b32_e64 v143, v12, v13, s[12:13]
	v_cndmask_b32_e64 v43, v6, v7, s[24:25]
	v_cndmask_b32_e64 v47, 6, 7, s[24:25]
	v_cndmask_b32_e64 v144, v14, v15, s[24:25]
	v_cmp_gt_f32_e64 s[8:9], v41, v40
	v_cmp_gt_f32_e64 s[10:11], v43, v42
	s_nop 0
	v_cndmask_b32_e64 v40, v40, v41, s[8:9]
	v_cndmask_b32_e64 v44, v44, v45, s[8:9]
	v_cndmask_b32_e64 v141, v141, v142, s[8:9]
	v_cndmask_b32_e64 v42, v42, v43, s[10:11]
	v_cndmask_b32_e64 v46, v46, v47, s[10:11]
	v_cndmask_b32_e64 v143, v143, v144, s[10:11]
	v_cmp_gt_f32_e64 s[8:9], v42, v40
	s_nop 1
	v_cndmask_b32_e64 v40, v40, v42, s[8:9]
	v_cndmask_b32_e64 v44, v44, v46, s[8:9]
	v_cndmask_b32_e64 v141, v141, v143, s[8:9]
	ds_write_b32 v149, v40 offset:9216
	ds_write_b8 v150, v141 offset:2304
	v_lshl_add_u32 v146, v141, 2, v54
	ds_write_b32 v146, v60
	v_lshl_add_u32 v147, v44, 6, v54
	ds_read2_b32 v[16:17], v147 offset0:0 offset1:1
	ds_read2_b32 v[18:19], v147 offset0:2 offset1:3
	ds_read2_b32 v[20:21], v147 offset0:4 offset1:5
	ds_read2_b32 v[22:23], v147 offset0:6 offset1:7
	ds_read2_b32 v[24:25], v147 offset0:8 offset1:9
	ds_read2_b32 v[26:27], v147 offset0:10 offset1:11
	ds_read2_b32 v[28:29], v147 offset0:12 offset1:13
	ds_read2_b32 v[30:31], v147 offset0:14 offset1:15
	s_waitcnt lgkmcnt(0)
; DI void peer_topk_item(const Params& p, int tt128, int head, char* smem) {
;     ...
; #pragma unroll 1
;     for (int r = 0; r < 16; ++r) {
;       float best = gm[0]; int bg = 0; int bi = gi[0];
; #pragma unroll
;       for (int g = 1; g < 8; ++g) if (gm[g] > best) { best = gm[g]; bg = g; bi = gi[g]; }
;       topv[tid * 16 + r] = best; topi[tid * 16 + r] = (unsigned char)bi;
;       row[bi] = -INFINITY;
;       float m = -INFINITY; int mi = bg * 16;
; #pragma unroll
;       for (int j = 0; j < 16; ++j) { float v = row[bg * 16 + j]; if (v > m) { m = v; mi = bg * 16 + j; } }
; #pragma unroll
;       for (int g = 0; g < 8; ++g) { gm[g] = (g == bg) ? m : gm[g]; gi[g] = (g == bg) ? mi : gi[g]; }
;     }
	v_cmp_gt_f32_e64 s[8:9], v17, v16
	v_cmp_gt_f32_e64 s[10:11], v19, v18
	v_cmp_gt_f32_e64 s[12:13], v21, v20
	v_cmp_gt_f32_e64 s[24:25], v23, v22
	v_cmp_gt_f32_e64 s[26:27], v25, v24
	v_cmp_gt_f32_e64 s[28:29], v27, v26
	v_cmp_gt_f32_e64 s[30:31], v29, v28
	v_cmp_gt_f32_e64 s[34:35], v31, v30
	v_cndmask_b32_e64 v16, v16, v17, s[8:9]
	v_cndmask_b32_e64 v32, 0, 1, s[8:9]
	v_cndmask_b32_e64 v18, v18, v19, s[10:11]
	v_cndmask_b32_e64 v33, 2, 3, s[10:11]
	v_cndmask_b32_e64 v20, v20, v21, s[12:13]
	v_cndmask_b32_e64 v34, 4, 5, s[12:13]
	v_cndmask_b32_e64 v22, v22, v23, s[24:25]
	v_cndmask_b32_e64 v35, 6, 7, s[24:25]
	v_cndmask_b32_e64 v24, v24, v25, s[26:27]
	v_cndmask_b32_e64 v36, 8, 9, s[26:27]
	v_cndmask_b32_e64 v26, v26, v27, s[28:29]
	v_cndmask_b32_e64 v37, 10, 11, s[28:29]
	v_cndmask_b32_e64 v28, v28, v29, s[30:31]
	v_cndmask_b32_e64 v38, 12, 13, s[30:31]
	v_cndmask_b32_e64 v30, v30, v31, s[34:35]
	v_cndmask_b32_e64 v39, 14, 15, s[34:35]
	v_cmp_gt_f32_e64 s[8:9], v18, v16
	v_cmp_gt_f32_e64 s[10:11], v22, v20
	v_cmp_gt_f32_e64 s[12:13], v26, v24
	v_cmp_gt_f32_e64 s[24:25], v30, v28
	v_cndmask_b32_e64 v16, v16, v18, s[8:9]
	v_cndmask_b32_e64 v32, v32, v33, s[8:9]
	v_cndmask_b32_e64 v20, v20, v22, s[10:11]
	v_cndmask_b32_e64 v34, v34, v35, s[10:11]
	v_cndmask_b32_e64 v24, v24, v26, s[12:13]
	v_cndmask_b32_e64 v36, v36, v37, s[12:13]
	v_cndmask_b32_e64 v28, v28, v30, s[24:25]
	v_cndmask_b32_e64 v38, v38, v39, s[24:25]
	v_cmp_gt_f32_e64 s[8:9], v20, v16
	v_cmp_gt_f32_e64 s[10:11], v28, v24
	s_nop 0
	v_cndmask_b32_e64 v16, v16, v20, s[8:9]
	v_cndmask_b32_e64 v32, v32, v34, s[8:9]
	v_cndmask_b32_e64 v24, v24, v28, s[10:11]
	v_cndmask_b32_e64 v36, v36, v38, s[10:11]
	v_cmp_gt_f32_e64 s[8:9], v24, v16
	s_nop 1
	v_cndmask_b32_e64 v16, v16, v24, s[8:9]
	v_cndmask_b32_e64 v32, v32, v36, s[8:9]
	v_lshl_add_u32 v148, v44, 4, v32
	v_cmp_eq_u32_e64 s[8:9], 0, v44
	v_cmp_eq_u32_e64 s[10:11], 1, v44
	v_cmp_eq_u32_e64 s[12:13], 2, v44
	v_cmp_eq_u32_e64 s[24:25], 3, v44
	v_cmp_eq_u32_e64 s[26:27], 4, v44
	v_cmp_eq_u32_e64 s[28:29], 5, v44
	v_cmp_eq_u32_e64 s[30:31], 6, v44
	v_cmp_eq_u32_e64 s[34:35], 7, v44
	v_cndmask_b32_e64 v0, v0, v16, s[8:9]
	v_cndmask_b32_e64 v8, v8, v148, s[8:9]
	v_cndmask_b32_e64 v1, v1, v16, s[10:11]
	v_cndmask_b32_e64 v9, v9, v148, s[10:11]
	v_cndmask_b32_e64 v2, v2, v16, s[12:13]
	v_cndmask_b32_e64 v10, v10, v148, s[12:13]
	v_cndmask_b32_e64 v3, v3, v16, s[24:25]
	v_cndmask_b32_e64 v11, v11, v148, s[24:25]
	v_cndmask_b32_e64 v4, v4, v16, s[26:27]
	v_cndmask_b32_e64 v12, v12, v148, s[26:27]
	v_cndmask_b32_e64 v5, v5, v16, s[28:29]
	v_cndmask_b32_e64 v13, v13, v148, s[28:29]
	v_cndmask_b32_e64 v6, v6, v16, s[30:31]
	v_cndmask_b32_e64 v14, v14, v148, s[30:31]
	v_cndmask_b32_e64 v7, v7, v16, s[34:35]
	v_cndmask_b32_e64 v15, v15, v148, s[34:35]
	v_cmp_gt_f32_e64 s[8:9], v1, v0
	v_cmp_gt_f32_e64 s[10:11], v3, v2
	v_cmp_gt_f32_e64 s[12:13], v5, v4
	v_cmp_gt_f32_e64 s[24:25], v7, v6
	v_cndmask_b32_e64 v40, v0, v1, s[8:9]
	v_cndmask_b32_e64 v44, 0, 1, s[8:9]
	v_cndmask_b32_e64 v141, v8, v9, s[8:9]
	v_cndmask_b32_e64 v41, v2, v3, s[10:11]
	v_cndmask_b32_e64 v45, 2, 3, s[10:11]
	v_cndmask_b32_e64 v142, v10, v11, s[10:11]
	v_cndmask_b32_e64 v42, v4, v5, s[12:13]
	v_cndmask_b32_e64 v46, 4, 5, s[12:13]
	v_cndmask_b32_e64 v143, v12, v13, s[12:13]
	v_cndmask_b32_e64 v43, v6, v7, s[24:25]
	v_cndmask_b32_e64 v47, 6, 7, s[24:25]
	v_cndmask_b32_e64 v144, v14, v15, s[24:25]
	v_cmp_gt_f32_e64 s[8:9], v41, v40
	v_cmp_gt_f32_e64 s[10:11], v43, v42
	s_nop 0
	v_cndmask_b32_e64 v40, v40, v41, s[8:9]
	v_cndmask_b32_e64 v44, v44, v45, s[8:9]
	v_cndmask_b32_e64 v141, v141, v142, s[8:9]
	v_cndmask_b32_e64 v42, v42, v43, s[10:11]
	v_cndmask_b32_e64 v46, v46, v47, s[10:11]
	v_cndmask_b32_e64 v143, v143, v144, s[10:11]
	v_cmp_gt_f32_e64 s[8:9], v42, v40
	s_nop 1
	v_cndmask_b32_e64 v40, v40, v42, s[8:9]
	v_cndmask_b32_e64 v44, v44, v46, s[8:9]
	v_cndmask_b32_e64 v141, v141, v143, s[8:9]
	ds_write_b32 v149, v40 offset:10240
	ds_write_b8 v150, v141 offset:2560
	v_lshl_add_u32 v146, v141, 2, v54
	ds_write_b32 v146, v60
	v_lshl_add_u32 v147, v44, 6, v54
	ds_read2_b32 v[16:17], v147 offset0:0 offset1:1
	ds_read2_b32 v[18:19], v147 offset0:2 offset1:3
	ds_read2_b32 v[20:21], v147 offset0:4 offset1:5
	ds_read2_b32 v[22:23], v147 offset0:6 offset1:7
	ds_read2_b32 v[24:25], v147 offset0:8 offset1:9
	ds_read2_b32 v[26:27], v147 offset0:10 offset1:11
	ds_read2_b32 v[28:29], v147 offset0:12 offset1:13
	ds_read2_b32 v[30:31], v147 offset0:14 offset1:15
	s_waitcnt lgkmcnt(0)
; DI void peer_topk_item(const Params& p, int tt128, int head, char* smem) {
;     ...
; #pragma unroll 1
;     for (int r = 0; r < 16; ++r) {
;       float best = gm[0]; int bg = 0; int bi = gi[0];
; #pragma unroll
;       for (int g = 1; g < 8; ++g) if (gm[g] > best) { best = gm[g]; bg = g; bi = gi[g]; }
;       topv[tid * 16 + r] = best; topi[tid * 16 + r] = (unsigned char)bi;
;       row[bi] = -INFINITY;
;       float m = -INFINITY; int mi = bg * 16;
; #pragma unroll
;       for (int j = 0; j < 16; ++j) { float v = row[bg * 16 + j]; if (v > m) { m = v; mi = bg * 16 + j; } }
; #pragma unroll
;       for (int g = 0; g < 8; ++g) { gm[g] = (g == bg) ? m : gm[g]; gi[g] = (g == bg) ? mi : gi[g]; }
;     }
	v_cmp_gt_f32_e64 s[8:9], v17, v16
	v_cmp_gt_f32_e64 s[10:11], v19, v18
	v_cmp_gt_f32_e64 s[12:13], v21, v20
	v_cmp_gt_f32_e64 s[24:25], v23, v22
	v_cmp_gt_f32_e64 s[26:27], v25, v24
	v_cmp_gt_f32_e64 s[28:29], v27, v26
	v_cmp_gt_f32_e64 s[30:31], v29, v28
	v_cmp_gt_f32_e64 s[34:35], v31, v30
	v_cndmask_b32_e64 v16, v16, v17, s[8:9]
	v_cndmask_b32_e64 v32, 0, 1, s[8:9]
	v_cndmask_b32_e64 v18, v18, v19, s[10:11]
	v_cndmask_b32_e64 v33, 2, 3, s[10:11]
	v_cndmask_b32_e64 v20, v20, v21, s[12:13]
	v_cndmask_b32_e64 v34, 4, 5, s[12:13]
	v_cndmask_b32_e64 v22, v22, v23, s[24:25]
	v_cndmask_b32_e64 v35, 6, 7, s[24:25]
	v_cndmask_b32_e64 v24, v24, v25, s[26:27]
	v_cndmask_b32_e64 v36, 8, 9, s[26:27]
	v_cndmask_b32_e64 v26, v26, v27, s[28:29]
	v_cndmask_b32_e64 v37, 10, 11, s[28:29]
	v_cndmask_b32_e64 v28, v28, v29, s[30:31]
	v_cndmask_b32_e64 v38, 12, 13, s[30:31]
	v_cndmask_b32_e64 v30, v30, v31, s[34:35]
	v_cndmask_b32_e64 v39, 14, 15, s[34:35]
	v_cmp_gt_f32_e64 s[8:9], v18, v16
	v_cmp_gt_f32_e64 s[10:11], v22, v20
	v_cmp_gt_f32_e64 s[12:13], v26, v24
	v_cmp_gt_f32_e64 s[24:25], v30, v28
	v_cndmask_b32_e64 v16, v16, v18, s[8:9]
	v_cndmask_b32_e64 v32, v32, v33, s[8:9]
	v_cndmask_b32_e64 v20, v20, v22, s[10:11]
	v_cndmask_b32_e64 v34, v34, v35, s[10:11]
	v_cndmask_b32_e64 v24, v24, v26, s[12:13]
	v_cndmask_b32_e64 v36, v36, v37, s[12:13]
	v_cndmask_b32_e64 v28, v28, v30, s[24:25]
	v_cndmask_b32_e64 v38, v38, v39, s[24:25]
	v_cmp_gt_f32_e64 s[8:9], v20, v16
	v_cmp_gt_f32_e64 s[10:11], v28, v24
	s_nop 0
	v_cndmask_b32_e64 v16, v16, v20, s[8:9]
	v_cndmask_b32_e64 v32, v32, v34, s[8:9]
	v_cndmask_b32_e64 v24, v24, v28, s[10:11]
	v_cndmask_b32_e64 v36, v36, v38, s[10:11]
	v_cmp_gt_f32_e64 s[8:9], v24, v16
	s_nop 1
	v_cndmask_b32_e64 v16, v16, v24, s[8:9]
	v_cndmask_b32_e64 v32, v32, v36, s[8:9]
	v_lshl_add_u32 v148, v44, 4, v32
	v_cmp_eq_u32_e64 s[8:9], 0, v44
	v_cmp_eq_u32_e64 s[10:11], 1, v44
	v_cmp_eq_u32_e64 s[12:13], 2, v44
	v_cmp_eq_u32_e64 s[24:25], 3, v44
	v_cmp_eq_u32_e64 s[26:27], 4, v44
	v_cmp_eq_u32_e64 s[28:29], 5, v44
	v_cmp_eq_u32_e64 s[30:31], 6, v44
	v_cmp_eq_u32_e64 s[34:35], 7, v44
	v_cndmask_b32_e64 v0, v0, v16, s[8:9]
	v_cndmask_b32_e64 v8, v8, v148, s[8:9]
	v_cndmask_b32_e64 v1, v1, v16, s[10:11]
	v_cndmask_b32_e64 v9, v9, v148, s[10:11]
	v_cndmask_b32_e64 v2, v2, v16, s[12:13]
	v_cndmask_b32_e64 v10, v10, v148, s[12:13]
	v_cndmask_b32_e64 v3, v3, v16, s[24:25]
	v_cndmask_b32_e64 v11, v11, v148, s[24:25]
	v_cndmask_b32_e64 v4, v4, v16, s[26:27]
	v_cndmask_b32_e64 v12, v12, v148, s[26:27]
	v_cndmask_b32_e64 v5, v5, v16, s[28:29]
	v_cndmask_b32_e64 v13, v13, v148, s[28:29]
	v_cndmask_b32_e64 v6, v6, v16, s[30:31]
	v_cndmask_b32_e64 v14, v14, v148, s[30:31]
	v_cndmask_b32_e64 v7, v7, v16, s[34:35]
	v_cndmask_b32_e64 v15, v15, v148, s[34:35]
	v_cmp_gt_f32_e64 s[8:9], v1, v0
	v_cmp_gt_f32_e64 s[10:11], v3, v2
	v_cmp_gt_f32_e64 s[12:13], v5, v4
	v_cmp_gt_f32_e64 s[24:25], v7, v6
	v_cndmask_b32_e64 v40, v0, v1, s[8:9]
	v_cndmask_b32_e64 v44, 0, 1, s[8:9]
	v_cndmask_b32_e64 v141, v8, v9, s[8:9]
	v_cndmask_b32_e64 v41, v2, v3, s[10:11]
	v_cndmask_b32_e64 v45, 2, 3, s[10:11]
	v_cndmask_b32_e64 v142, v10, v11, s[10:11]
	v_cndmask_b32_e64 v42, v4, v5, s[12:13]
	v_cndmask_b32_e64 v46, 4, 5, s[12:13]
	v_cndmask_b32_e64 v143, v12, v13, s[12:13]
	v_cndmask_b32_e64 v43, v6, v7, s[24:25]
	v_cndmask_b32_e64 v47, 6, 7, s[24:25]
	v_cndmask_b32_e64 v144, v14, v15, s[24:25]
	v_cmp_gt_f32_e64 s[8:9], v41, v40
	v_cmp_gt_f32_e64 s[10:11], v43, v42
	s_nop 0
	v_cndmask_b32_e64 v40, v40, v41, s[8:9]
	v_cndmask_b32_e64 v44, v44, v45, s[8:9]
	v_cndmask_b32_e64 v141, v141, v142, s[8:9]
	v_cndmask_b32_e64 v42, v42, v43, s[10:11]
	v_cndmask_b32_e64 v46, v46, v47, s[10:11]
	v_cndmask_b32_e64 v143, v143, v144, s[10:11]
	v_cmp_gt_f32_e64 s[8:9], v42, v40
	s_nop 1
	v_cndmask_b32_e64 v40, v40, v42, s[8:9]
	v_cndmask_b32_e64 v44, v44, v46, s[8:9]
	v_cndmask_b32_e64 v141, v141, v143, s[8:9]
	ds_write_b32 v149, v40 offset:11264
	ds_write_b8 v150, v141 offset:2816
	v_lshl_add_u32 v146, v141, 2, v54
	ds_write_b32 v146, v60
	v_lshl_add_u32 v147, v44, 6, v54
	ds_read2_b32 v[16:17], v147 offset0:0 offset1:1
	ds_read2_b32 v[18:19], v147 offset0:2 offset1:3
	ds_read2_b32 v[20:21], v147 offset0:4 offset1:5
	ds_read2_b32 v[22:23], v147 offset0:6 offset1:7
	ds_read2_b32 v[24:25], v147 offset0:8 offset1:9
	ds_read2_b32 v[26:27], v147 offset0:10 offset1:11
	ds_read2_b32 v[28:29], v147 offset0:12 offset1:13
	ds_read2_b32 v[30:31], v147 offset0:14 offset1:15
	s_waitcnt lgkmcnt(0)
; DI void peer_topk_item(const Params& p, int tt128, int head, char* smem) {
;     ...
; #pragma unroll 1
;     for (int r = 0; r < 16; ++r) {
;       float best = gm[0]; int bg = 0; int bi = gi[0];
; #pragma unroll
;       for (int g = 1; g < 8; ++g) if (gm[g] > best) { best = gm[g]; bg = g; bi = gi[g]; }
;       topv[tid * 16 + r] = best; topi[tid * 16 + r] = (unsigned char)bi;
;       row[bi] = -INFINITY;
;       float m = -INFINITY; int mi = bg * 16;
; #pragma unroll
;       for (int j = 0; j < 16; ++j) { float v = row[bg * 16 + j]; if (v > m) { m = v; mi = bg * 16 + j; } }
; #pragma unroll
;       for (int g = 0; g < 8; ++g) { gm[g] = (g == bg) ? m : gm[g]; gi[g] = (g == bg) ? mi : gi[g]; }
;     }
	v_cmp_gt_f32_e64 s[8:9], v17, v16
	v_cmp_gt_f32_e64 s[10:11], v19, v18
	v_cmp_gt_f32_e64 s[12:13], v21, v20
	v_cmp_gt_f32_e64 s[24:25], v23, v22
	v_cmp_gt_f32_e64 s[26:27], v25, v24
	v_cmp_gt_f32_e64 s[28:29], v27, v26
	v_cmp_gt_f32_e64 s[30:31], v29, v28
	v_cmp_gt_f32_e64 s[34:35], v31, v30
	v_cndmask_b32_e64 v16, v16, v17, s[8:9]
	v_cndmask_b32_e64 v32, 0, 1, s[8:9]
	v_cndmask_b32_e64 v18, v18, v19, s[10:11]
	v_cndmask_b32_e64 v33, 2, 3, s[10:11]
	v_cndmask_b32_e64 v20, v20, v21, s[12:13]
	v_cndmask_b32_e64 v34, 4, 5, s[12:13]
	v_cndmask_b32_e64 v22, v22, v23, s[24:25]
	v_cndmask_b32_e64 v35, 6, 7, s[24:25]
	v_cndmask_b32_e64 v24, v24, v25, s[26:27]
	v_cndmask_b32_e64 v36, 8, 9, s[26:27]
	v_cndmask_b32_e64 v26, v26, v27, s[28:29]
	v_cndmask_b32_e64 v37, 10, 11, s[28:29]
	v_cndmask_b32_e64 v28, v28, v29, s[30:31]
	v_cndmask_b32_e64 v38, 12, 13, s[30:31]
	v_cndmask_b32_e64 v30, v30, v31, s[34:35]
	v_cndmask_b32_e64 v39, 14, 15, s[34:35]
	v_cmp_gt_f32_e64 s[8:9], v18, v16
	v_cmp_gt_f32_e64 s[10:11], v22, v20
	v_cmp_gt_f32_e64 s[12:13], v26, v24
	v_cmp_gt_f32_e64 s[24:25], v30, v28
	v_cndmask_b32_e64 v16, v16, v18, s[8:9]
	v_cndmask_b32_e64 v32, v32, v33, s[8:9]
	v_cndmask_b32_e64 v20, v20, v22, s[10:11]
	v_cndmask_b32_e64 v34, v34, v35, s[10:11]
	v_cndmask_b32_e64 v24, v24, v26, s[12:13]
	v_cndmask_b32_e64 v36, v36, v37, s[12:13]
	v_cndmask_b32_e64 v28, v28, v30, s[24:25]
	v_cndmask_b32_e64 v38, v38, v39, s[24:25]
	v_cmp_gt_f32_e64 s[8:9], v20, v16
	v_cmp_gt_f32_e64 s[10:11], v28, v24
	s_nop 0
	v_cndmask_b32_e64 v16, v16, v20, s[8:9]
	v_cndmask_b32_e64 v32, v32, v34, s[8:9]
	v_cndmask_b32_e64 v24, v24, v28, s[10:11]
	v_cndmask_b32_e64 v36, v36, v38, s[10:11]
	v_cmp_gt_f32_e64 s[8:9], v24, v16
	s_nop 1
	v_cndmask_b32_e64 v16, v16, v24, s[8:9]
	v_cndmask_b32_e64 v32, v32, v36, s[8:9]
	v_lshl_add_u32 v148, v44, 4, v32
	v_cmp_eq_u32_e64 s[8:9], 0, v44
	v_cmp_eq_u32_e64 s[10:11], 1, v44
	v_cmp_eq_u32_e64 s[12:13], 2, v44
	v_cmp_eq_u32_e64 s[24:25], 3, v44
	v_cmp_eq_u32_e64 s[26:27], 4, v44
	v_cmp_eq_u32_e64 s[28:29], 5, v44
	v_cmp_eq_u32_e64 s[30:31], 6, v44
	v_cmp_eq_u32_e64 s[34:35], 7, v44
	v_cndmask_b32_e64 v0, v0, v16, s[8:9]
	v_cndmask_b32_e64 v8, v8, v148, s[8:9]
	v_cndmask_b32_e64 v1, v1, v16, s[10:11]
	v_cndmask_b32_e64 v9, v9, v148, s[10:11]
	v_cndmask_b32_e64 v2, v2, v16, s[12:13]
	v_cndmask_b32_e64 v10, v10, v148, s[12:13]
	v_cndmask_b32_e64 v3, v3, v16, s[24:25]
	v_cndmask_b32_e64 v11, v11, v148, s[24:25]
	v_cndmask_b32_e64 v4, v4, v16, s[26:27]
	v_cndmask_b32_e64 v12, v12, v148, s[26:27]
	v_cndmask_b32_e64 v5, v5, v16, s[28:29]
	v_cndmask_b32_e64 v13, v13, v148, s[28:29]
	v_cndmask_b32_e64 v6, v6, v16, s[30:31]
	v_cndmask_b32_e64 v14, v14, v148, s[30:31]
	v_cndmask_b32_e64 v7, v7, v16, s[34:35]
	v_cndmask_b32_e64 v15, v15, v148, s[34:35]
	v_cmp_gt_f32_e64 s[8:9], v1, v0
	v_cmp_gt_f32_e64 s[10:11], v3, v2
	v_cmp_gt_f32_e64 s[12:13], v5, v4
	v_cmp_gt_f32_e64 s[24:25], v7, v6
	v_cndmask_b32_e64 v40, v0, v1, s[8:9]
	v_cndmask_b32_e64 v44, 0, 1, s[8:9]
	v_cndmask_b32_e64 v141, v8, v9, s[8:9]
	v_cndmask_b32_e64 v41, v2, v3, s[10:11]
	v_cndmask_b32_e64 v45, 2, 3, s[10:11]
	v_cndmask_b32_e64 v142, v10, v11, s[10:11]
	v_cndmask_b32_e64 v42, v4, v5, s[12:13]
	v_cndmask_b32_e64 v46, 4, 5, s[12:13]
	v_cndmask_b32_e64 v143, v12, v13, s[12:13]
	v_cndmask_b32_e64 v43, v6, v7, s[24:25]
	v_cndmask_b32_e64 v47, 6, 7, s[24:25]
	v_cndmask_b32_e64 v144, v14, v15, s[24:25]
	v_cmp_gt_f32_e64 s[8:9], v41, v40
	v_cmp_gt_f32_e64 s[10:11], v43, v42
	s_nop 0
	v_cndmask_b32_e64 v40, v40, v41, s[8:9]
	v_cndmask_b32_e64 v44, v44, v45, s[8:9]
	v_cndmask_b32_e64 v141, v141, v142, s[8:9]
	v_cndmask_b32_e64 v42, v42, v43, s[10:11]
	v_cndmask_b32_e64 v46, v46, v47, s[10:11]
	v_cndmask_b32_e64 v143, v143, v144, s[10:11]
	v_cmp_gt_f32_e64 s[8:9], v42, v40
	s_nop 1
	v_cndmask_b32_e64 v40, v40, v42, s[8:9]
	v_cndmask_b32_e64 v44, v44, v46, s[8:9]
	v_cndmask_b32_e64 v141, v141, v143, s[8:9]
	ds_write_b32 v149, v40 offset:12288
	ds_write_b8 v150, v141 offset:3072
	v_lshl_add_u32 v146, v141, 2, v54
	ds_write_b32 v146, v60
	v_lshl_add_u32 v147, v44, 6, v54
	ds_read2_b32 v[16:17], v147 offset0:0 offset1:1
	ds_read2_b32 v[18:19], v147 offset0:2 offset1:3
	ds_read2_b32 v[20:21], v147 offset0:4 offset1:5
	ds_read2_b32 v[22:23], v147 offset0:6 offset1:7
	ds_read2_b32 v[24:25], v147 offset0:8 offset1:9
	ds_read2_b32 v[26:27], v147 offset0:10 offset1:11
	ds_read2_b32 v[28:29], v147 offset0:12 offset1:13
	ds_read2_b32 v[30:31], v147 offset0:14 offset1:15
	s_waitcnt lgkmcnt(0)
; DI void peer_topk_item(const Params& p, int tt128, int head, char* smem) {
;     ...
; #pragma unroll 1
;     for (int r = 0; r < 16; ++r) {
;       float best = gm[0]; int bg = 0; int bi = gi[0];
; #pragma unroll
;       for (int g = 1; g < 8; ++g) if (gm[g] > best) { best = gm[g]; bg = g; bi = gi[g]; }
;       topv[tid * 16 + r] = best; topi[tid * 16 + r] = (unsigned char)bi;
;       row[bi] = -INFINITY;
;       float m = -INFINITY; int mi = bg * 16;
; #pragma unroll
;       for (int j = 0; j < 16; ++j) { float v = row[bg * 16 + j]; if (v > m) { m = v; mi = bg * 16 + j; } }
; #pragma unroll
;       for (int g = 0; g < 8; ++g) { gm[g] = (g == bg) ? m : gm[g]; gi[g] = (g == bg) ? mi : gi[g]; }
;     }
	v_cmp_gt_f32_e64 s[8:9], v17, v16
	v_cmp_gt_f32_e64 s[10:11], v19, v18
	v_cmp_gt_f32_e64 s[12:13], v21, v20
	v_cmp_gt_f32_e64 s[24:25], v23, v22
	v_cmp_gt_f32_e64 s[26:27], v25, v24
	v_cmp_gt_f32_e64 s[28:29], v27, v26
	v_cmp_gt_f32_e64 s[30:31], v29, v28
	v_cmp_gt_f32_e64 s[34:35], v31, v30
	v_cndmask_b32_e64 v16, v16, v17, s[8:9]
	v_cndmask_b32_e64 v32, 0, 1, s[8:9]
	v_cndmask_b32_e64 v18, v18, v19, s[10:11]
	v_cndmask_b32_e64 v33, 2, 3, s[10:11]
	v_cndmask_b32_e64 v20, v20, v21, s[12:13]
	v_cndmask_b32_e64 v34, 4, 5, s[12:13]
	v_cndmask_b32_e64 v22, v22, v23, s[24:25]
	v_cndmask_b32_e64 v35, 6, 7, s[24:25]
	v_cndmask_b32_e64 v24, v24, v25, s[26:27]
	v_cndmask_b32_e64 v36, 8, 9, s[26:27]
	v_cndmask_b32_e64 v26, v26, v27, s[28:29]
	v_cndmask_b32_e64 v37, 10, 11, s[28:29]
	v_cndmask_b32_e64 v28, v28, v29, s[30:31]
	v_cndmask_b32_e64 v38, 12, 13, s[30:31]
	v_cndmask_b32_e64 v30, v30, v31, s[34:35]
	v_cndmask_b32_e64 v39, 14, 15, s[34:35]
	v_cmp_gt_f32_e64 s[8:9], v18, v16
	v_cmp_gt_f32_e64 s[10:11], v22, v20
	v_cmp_gt_f32_e64 s[12:13], v26, v24
	v_cmp_gt_f32_e64 s[24:25], v30, v28
	v_cndmask_b32_e64 v16, v16, v18, s[8:9]
	v_cndmask_b32_e64 v32, v32, v33, s[8:9]
	v_cndmask_b32_e64 v20, v20, v22, s[10:11]
	v_cndmask_b32_e64 v34, v34, v35, s[10:11]
	v_cndmask_b32_e64 v24, v24, v26, s[12:13]
	v_cndmask_b32_e64 v36, v36, v37, s[12:13]
	v_cndmask_b32_e64 v28, v28, v30, s[24:25]
	v_cndmask_b32_e64 v38, v38, v39, s[24:25]
	v_cmp_gt_f32_e64 s[8:9], v20, v16
	v_cmp_gt_f32_e64 s[10:11], v28, v24
	s_nop 0
	v_cndmask_b32_e64 v16, v16, v20, s[8:9]
	v_cndmask_b32_e64 v32, v32, v34, s[8:9]
	v_cndmask_b32_e64 v24, v24, v28, s[10:11]
	v_cndmask_b32_e64 v36, v36, v38, s[10:11]
	v_cmp_gt_f32_e64 s[8:9], v24, v16
	s_nop 1
	v_cndmask_b32_e64 v16, v16, v24, s[8:9]
	v_cndmask_b32_e64 v32, v32, v36, s[8:9]
	v_lshl_add_u32 v148, v44, 4, v32
	v_cmp_eq_u32_e64 s[8:9], 0, v44
	v_cmp_eq_u32_e64 s[10:11], 1, v44
	v_cmp_eq_u32_e64 s[12:13], 2, v44
	v_cmp_eq_u32_e64 s[24:25], 3, v44
	v_cmp_eq_u32_e64 s[26:27], 4, v44
	v_cmp_eq_u32_e64 s[28:29], 5, v44
	v_cmp_eq_u32_e64 s[30:31], 6, v44
	v_cmp_eq_u32_e64 s[34:35], 7, v44
	v_cndmask_b32_e64 v0, v0, v16, s[8:9]
	v_cndmask_b32_e64 v8, v8, v148, s[8:9]
	v_cndmask_b32_e64 v1, v1, v16, s[10:11]
	v_cndmask_b32_e64 v9, v9, v148, s[10:11]
	v_cndmask_b32_e64 v2, v2, v16, s[12:13]
	v_cndmask_b32_e64 v10, v10, v148, s[12:13]
	v_cndmask_b32_e64 v3, v3, v16, s[24:25]
	v_cndmask_b32_e64 v11, v11, v148, s[24:25]
	v_cndmask_b32_e64 v4, v4, v16, s[26:27]
	v_cndmask_b32_e64 v12, v12, v148, s[26:27]
	v_cndmask_b32_e64 v5, v5, v16, s[28:29]
	v_cndmask_b32_e64 v13, v13, v148, s[28:29]
	v_cndmask_b32_e64 v6, v6, v16, s[30:31]
	v_cndmask_b32_e64 v14, v14, v148, s[30:31]
	v_cndmask_b32_e64 v7, v7, v16, s[34:35]
	v_cndmask_b32_e64 v15, v15, v148, s[34:35]
	v_cmp_gt_f32_e64 s[8:9], v1, v0
	v_cmp_gt_f32_e64 s[10:11], v3, v2
	v_cmp_gt_f32_e64 s[12:13], v5, v4
	v_cmp_gt_f32_e64 s[24:25], v7, v6
	v_cndmask_b32_e64 v40, v0, v1, s[8:9]
	v_cndmask_b32_e64 v44, 0, 1, s[8:9]
	v_cndmask_b32_e64 v141, v8, v9, s[8:9]
	v_cndmask_b32_e64 v41, v2, v3, s[10:11]
	v_cndmask_b32_e64 v45, 2, 3, s[10:11]
	v_cndmask_b32_e64 v142, v10, v11, s[10:11]
	v_cndmask_b32_e64 v42, v4, v5, s[12:13]
	v_cndmask_b32_e64 v46, 4, 5, s[12:13]
	v_cndmask_b32_e64 v143, v12, v13, s[12:13]
	v_cndmask_b32_e64 v43, v6, v7, s[24:25]
	v_cndmask_b32_e64 v47, 6, 7, s[24:25]
	v_cndmask_b32_e64 v144, v14, v15, s[24:25]
	v_cmp_gt_f32_e64 s[8:9], v41, v40
	v_cmp_gt_f32_e64 s[10:11], v43, v42
	s_nop 0
	v_cndmask_b32_e64 v40, v40, v41, s[8:9]
	v_cndmask_b32_e64 v44, v44, v45, s[8:9]
	v_cndmask_b32_e64 v141, v141, v142, s[8:9]
	v_cndmask_b32_e64 v42, v42, v43, s[10:11]
	v_cndmask_b32_e64 v46, v46, v47, s[10:11]
	v_cndmask_b32_e64 v143, v143, v144, s[10:11]
	v_cmp_gt_f32_e64 s[8:9], v42, v40
	s_nop 1
	v_cndmask_b32_e64 v40, v40, v42, s[8:9]
	v_cndmask_b32_e64 v44, v44, v46, s[8:9]
	v_cndmask_b32_e64 v141, v141, v143, s[8:9]
	ds_write_b32 v149, v40 offset:13312
	ds_write_b8 v150, v141 offset:3328
	v_lshl_add_u32 v146, v141, 2, v54
	ds_write_b32 v146, v60
	v_lshl_add_u32 v147, v44, 6, v54
	ds_read2_b32 v[16:17], v147 offset0:0 offset1:1
	ds_read2_b32 v[18:19], v147 offset0:2 offset1:3
	ds_read2_b32 v[20:21], v147 offset0:4 offset1:5
	ds_read2_b32 v[22:23], v147 offset0:6 offset1:7
	ds_read2_b32 v[24:25], v147 offset0:8 offset1:9
	ds_read2_b32 v[26:27], v147 offset0:10 offset1:11
	ds_read2_b32 v[28:29], v147 offset0:12 offset1:13
	ds_read2_b32 v[30:31], v147 offset0:14 offset1:15
	s_waitcnt lgkmcnt(0)
; DI void peer_topk_item(const Params& p, int tt128, int head, char* smem) {
;     ...
; #pragma unroll 1
;     for (int r = 0; r < 16; ++r) {
;       float best = gm[0]; int bg = 0; int bi = gi[0];
; #pragma unroll
;       for (int g = 1; g < 8; ++g) if (gm[g] > best) { best = gm[g]; bg = g; bi = gi[g]; }
;       topv[tid * 16 + r] = best; topi[tid * 16 + r] = (unsigned char)bi;
;       row[bi] = -INFINITY;
;       float m = -INFINITY; int mi = bg * 16;
; #pragma unroll
;       for (int j = 0; j < 16; ++j) { float v = row[bg * 16 + j]; if (v > m) { m = v; mi = bg * 16 + j; } }
; #pragma unroll
;       for (int g = 0; g < 8; ++g) { gm[g] = (g == bg) ? m : gm[g]; gi[g] = (g == bg) ? mi : gi[g]; }
;     }
	v_cmp_gt_f32_e64 s[8:9], v17, v16
	v_cmp_gt_f32_e64 s[10:11], v19, v18
	v_cmp_gt_f32_e64 s[12:13], v21, v20
	v_cmp_gt_f32_e64 s[24:25], v23, v22
	v_cmp_gt_f32_e64 s[26:27], v25, v24
	v_cmp_gt_f32_e64 s[28:29], v27, v26
	v_cmp_gt_f32_e64 s[30:31], v29, v28
	v_cmp_gt_f32_e64 s[34:35], v31, v30
	v_cndmask_b32_e64 v16, v16, v17, s[8:9]
	v_cndmask_b32_e64 v32, 0, 1, s[8:9]
	v_cndmask_b32_e64 v18, v18, v19, s[10:11]
	v_cndmask_b32_e64 v33, 2, 3, s[10:11]
	v_cndmask_b32_e64 v20, v20, v21, s[12:13]
	v_cndmask_b32_e64 v34, 4, 5, s[12:13]
	v_cndmask_b32_e64 v22, v22, v23, s[24:25]
	v_cndmask_b32_e64 v35, 6, 7, s[24:25]
	v_cndmask_b32_e64 v24, v24, v25, s[26:27]
	v_cndmask_b32_e64 v36, 8, 9, s[26:27]
	v_cndmask_b32_e64 v26, v26, v27, s[28:29]
	v_cndmask_b32_e64 v37, 10, 11, s[28:29]
	v_cndmask_b32_e64 v28, v28, v29, s[30:31]
	v_cndmask_b32_e64 v38, 12, 13, s[30:31]
	v_cndmask_b32_e64 v30, v30, v31, s[34:35]
	v_cndmask_b32_e64 v39, 14, 15, s[34:35]
	v_cmp_gt_f32_e64 s[8:9], v18, v16
	v_cmp_gt_f32_e64 s[10:11], v22, v20
	v_cmp_gt_f32_e64 s[12:13], v26, v24
	v_cmp_gt_f32_e64 s[24:25], v30, v28
	v_cndmask_b32_e64 v16, v16, v18, s[8:9]
	v_cndmask_b32_e64 v32, v32, v33, s[8:9]
	v_cndmask_b32_e64 v20, v20, v22, s[10:11]
	v_cndmask_b32_e64 v34, v34, v35, s[10:11]
	v_cndmask_b32_e64 v24, v24, v26, s[12:13]
	v_cndmask_b32_e64 v36, v36, v37, s[12:13]
	v_cndmask_b32_e64 v28, v28, v30, s[24:25]
	v_cndmask_b32_e64 v38, v38, v39, s[24:25]
	v_cmp_gt_f32_e64 s[8:9], v20, v16
	v_cmp_gt_f32_e64 s[10:11], v28, v24
	s_nop 0
	v_cndmask_b32_e64 v16, v16, v20, s[8:9]
	v_cndmask_b32_e64 v32, v32, v34, s[8:9]
	v_cndmask_b32_e64 v24, v24, v28, s[10:11]
	v_cndmask_b32_e64 v36, v36, v38, s[10:11]
	v_cmp_gt_f32_e64 s[8:9], v24, v16
	s_nop 1
	v_cndmask_b32_e64 v16, v16, v24, s[8:9]
	v_cndmask_b32_e64 v32, v32, v36, s[8:9]
	v_lshl_add_u32 v148, v44, 4, v32
	v_cmp_eq_u32_e64 s[8:9], 0, v44
	v_cmp_eq_u32_e64 s[10:11], 1, v44
	v_cmp_eq_u32_e64 s[12:13], 2, v44
	v_cmp_eq_u32_e64 s[24:25], 3, v44
	v_cmp_eq_u32_e64 s[26:27], 4, v44
	v_cmp_eq_u32_e64 s[28:29], 5, v44
	v_cmp_eq_u32_e64 s[30:31], 6, v44
	v_cmp_eq_u32_e64 s[34:35], 7, v44
	v_cndmask_b32_e64 v0, v0, v16, s[8:9]
	v_cndmask_b32_e64 v8, v8, v148, s[8:9]
	v_cndmask_b32_e64 v1, v1, v16, s[10:11]
	v_cndmask_b32_e64 v9, v9, v148, s[10:11]
	v_cndmask_b32_e64 v2, v2, v16, s[12:13]
	v_cndmask_b32_e64 v10, v10, v148, s[12:13]
	v_cndmask_b32_e64 v3, v3, v16, s[24:25]
	v_cndmask_b32_e64 v11, v11, v148, s[24:25]
	v_cndmask_b32_e64 v4, v4, v16, s[26:27]
	v_cndmask_b32_e64 v12, v12, v148, s[26:27]
	v_cndmask_b32_e64 v5, v5, v16, s[28:29]
	v_cndmask_b32_e64 v13, v13, v148, s[28:29]
	v_cndmask_b32_e64 v6, v6, v16, s[30:31]
	v_cndmask_b32_e64 v14, v14, v148, s[30:31]
	v_cndmask_b32_e64 v7, v7, v16, s[34:35]
	v_cndmask_b32_e64 v15, v15, v148, s[34:35]
	v_cmp_gt_f32_e64 s[8:9], v1, v0
	v_cmp_gt_f32_e64 s[10:11], v3, v2
	v_cmp_gt_f32_e64 s[12:13], v5, v4
	v_cmp_gt_f32_e64 s[24:25], v7, v6
	v_cndmask_b32_e64 v40, v0, v1, s[8:9]
	v_cndmask_b32_e64 v44, 0, 1, s[8:9]
	v_cndmask_b32_e64 v141, v8, v9, s[8:9]
	v_cndmask_b32_e64 v41, v2, v3, s[10:11]
	v_cndmask_b32_e64 v45, 2, 3, s[10:11]
	v_cndmask_b32_e64 v142, v10, v11, s[10:11]
	v_cndmask_b32_e64 v42, v4, v5, s[12:13]
	v_cndmask_b32_e64 v46, 4, 5, s[12:13]
	v_cndmask_b32_e64 v143, v12, v13, s[12:13]
	v_cndmask_b32_e64 v43, v6, v7, s[24:25]
	v_cndmask_b32_e64 v47, 6, 7, s[24:25]
	v_cndmask_b32_e64 v144, v14, v15, s[24:25]
	v_cmp_gt_f32_e64 s[8:9], v41, v40
	v_cmp_gt_f32_e64 s[10:11], v43, v42
	s_nop 0
	v_cndmask_b32_e64 v40, v40, v41, s[8:9]
	v_cndmask_b32_e64 v44, v44, v45, s[8:9]
	v_cndmask_b32_e64 v141, v141, v142, s[8:9]
	v_cndmask_b32_e64 v42, v42, v43, s[10:11]
	v_cndmask_b32_e64 v46, v46, v47, s[10:11]
	v_cndmask_b32_e64 v143, v143, v144, s[10:11]
	v_cmp_gt_f32_e64 s[8:9], v42, v40
	s_nop 1
	v_cndmask_b32_e64 v40, v40, v42, s[8:9]
	v_cndmask_b32_e64 v44, v44, v46, s[8:9]
	v_cndmask_b32_e64 v141, v141, v143, s[8:9]
	ds_write_b32 v149, v40 offset:14336
	ds_write_b8 v150, v141 offset:3584
	v_lshl_add_u32 v146, v141, 2, v54
	ds_write_b32 v146, v60
	v_lshl_add_u32 v147, v44, 6, v54
	ds_read2_b32 v[16:17], v147 offset0:0 offset1:1
	ds_read2_b32 v[18:19], v147 offset0:2 offset1:3
	ds_read2_b32 v[20:21], v147 offset0:4 offset1:5
	ds_read2_b32 v[22:23], v147 offset0:6 offset1:7
	ds_read2_b32 v[24:25], v147 offset0:8 offset1:9
	ds_read2_b32 v[26:27], v147 offset0:10 offset1:11
	ds_read2_b32 v[28:29], v147 offset0:12 offset1:13
	ds_read2_b32 v[30:31], v147 offset0:14 offset1:15
	s_waitcnt lgkmcnt(0)
; DI void peer_topk_item(const Params& p, int tt128, int head, char* smem) {
;     ...
; #pragma unroll 1
;     for (int r = 0; r < 16; ++r) {
;       float best = gm[0]; int bg = 0; int bi = gi[0];
; #pragma unroll
;       for (int g = 1; g < 8; ++g) if (gm[g] > best) { best = gm[g]; bg = g; bi = gi[g]; }
;       topv[tid * 16 + r] = best; topi[tid * 16 + r] = (unsigned char)bi;
;       row[bi] = -INFINITY;
;       float m = -INFINITY; int mi = bg * 16;
; #pragma unroll
;       for (int j = 0; j < 16; ++j) { float v = row[bg * 16 + j]; if (v > m) { m = v; mi = bg * 16 + j; } }
; #pragma unroll
;       for (int g = 0; g < 8; ++g) { gm[g] = (g == bg) ? m : gm[g]; gi[g] = (g == bg) ? mi : gi[g]; }
;     }
;   }
;   __syncthreads();
;   if (tid < 128) {
;     const float* av = topv + tid * 16;
;     const float* bv = topv + (128 + tid) * 16;
;     const unsigned char* ai = topi + tid * 16;
;     const unsigned char* bi_ = topi + (128 + tid) * 16;
;     float cur[16]; int pp[16];
;     const float b0 = bv[0];
; #pragma unroll
;     for (int i = 0; i < 16; ++i) { cur[i] = av[i] + b0; pp[i] = 0; }
	v_cmp_gt_f32_e64 s[8:9], v17, v16
	v_cmp_gt_f32_e64 s[10:11], v19, v18
	v_cmp_gt_f32_e64 s[12:13], v21, v20
	v_cmp_gt_f32_e64 s[24:25], v23, v22
	v_cmp_gt_f32_e64 s[26:27], v25, v24
	v_cmp_gt_f32_e64 s[28:29], v27, v26
	v_cmp_gt_f32_e64 s[30:31], v29, v28
	v_cmp_gt_f32_e64 s[34:35], v31, v30
	v_cndmask_b32_e64 v16, v16, v17, s[8:9]
	v_cndmask_b32_e64 v32, 0, 1, s[8:9]
	v_cndmask_b32_e64 v18, v18, v19, s[10:11]
	v_cndmask_b32_e64 v33, 2, 3, s[10:11]
	v_cndmask_b32_e64 v20, v20, v21, s[12:13]
	v_cndmask_b32_e64 v34, 4, 5, s[12:13]
	v_cndmask_b32_e64 v22, v22, v23, s[24:25]
	v_cndmask_b32_e64 v35, 6, 7, s[24:25]
	v_cndmask_b32_e64 v24, v24, v25, s[26:27]
	v_cndmask_b32_e64 v36, 8, 9, s[26:27]
	v_cndmask_b32_e64 v26, v26, v27, s[28:29]
	v_cndmask_b32_e64 v37, 10, 11, s[28:29]
	v_cndmask_b32_e64 v28, v28, v29, s[30:31]
	v_cndmask_b32_e64 v38, 12, 13, s[30:31]
	v_cndmask_b32_e64 v30, v30, v31, s[34:35]
	v_cndmask_b32_e64 v39, 14, 15, s[34:35]
	v_cmp_gt_f32_e64 s[8:9], v18, v16
	v_cmp_gt_f32_e64 s[10:11], v22, v20
	v_cmp_gt_f32_e64 s[12:13], v26, v24
	v_cmp_gt_f32_e64 s[24:25], v30, v28
	v_cndmask_b32_e64 v16, v16, v18, s[8:9]
	v_cndmask_b32_e64 v32, v32, v33, s[8:9]
	v_cndmask_b32_e64 v20, v20, v22, s[10:11]
	v_cndmask_b32_e64 v34, v34, v35, s[10:11]
	v_cndmask_b32_e64 v24, v24, v26, s[12:13]
	v_cndmask_b32_e64 v36, v36, v37, s[12:13]
	v_cndmask_b32_e64 v28, v28, v30, s[24:25]
	v_cndmask_b32_e64 v38, v38, v39, s[24:25]
	v_cmp_gt_f32_e64 s[8:9], v20, v16
	v_cmp_gt_f32_e64 s[10:11], v28, v24
	s_nop 0
	v_cndmask_b32_e64 v16, v16, v20, s[8:9]
	v_cndmask_b32_e64 v32, v32, v34, s[8:9]
	v_cndmask_b32_e64 v24, v24, v28, s[10:11]
	v_cndmask_b32_e64 v36, v36, v38, s[10:11]
	v_cmp_gt_f32_e64 s[8:9], v24, v16
	s_nop 1
	v_cndmask_b32_e64 v16, v16, v24, s[8:9]
	v_cndmask_b32_e64 v32, v32, v36, s[8:9]
	v_lshl_add_u32 v148, v44, 4, v32
	v_cmp_eq_u32_e64 s[8:9], 0, v44
	v_cmp_eq_u32_e64 s[10:11], 1, v44
	v_cmp_eq_u32_e64 s[12:13], 2, v44
	v_cmp_eq_u32_e64 s[24:25], 3, v44
	v_cmp_eq_u32_e64 s[26:27], 4, v44
	v_cmp_eq_u32_e64 s[28:29], 5, v44
	v_cmp_eq_u32_e64 s[30:31], 6, v44
	v_cmp_eq_u32_e64 s[34:35], 7, v44
	v_cndmask_b32_e64 v0, v0, v16, s[8:9]
	v_cndmask_b32_e64 v8, v8, v148, s[8:9]
	v_cndmask_b32_e64 v1, v1, v16, s[10:11]
	v_cndmask_b32_e64 v9, v9, v148, s[10:11]
	v_cndmask_b32_e64 v2, v2, v16, s[12:13]
	v_cndmask_b32_e64 v10, v10, v148, s[12:13]
	v_cndmask_b32_e64 v3, v3, v16, s[24:25]
	v_cndmask_b32_e64 v11, v11, v148, s[24:25]
	v_cndmask_b32_e64 v4, v4, v16, s[26:27]
	v_cndmask_b32_e64 v12, v12, v148, s[26:27]
	v_cndmask_b32_e64 v5, v5, v16, s[28:29]
	v_cndmask_b32_e64 v13, v13, v148, s[28:29]
	v_cndmask_b32_e64 v6, v6, v16, s[30:31]
	v_cndmask_b32_e64 v14, v14, v148, s[30:31]
	v_cndmask_b32_e64 v7, v7, v16, s[34:35]
	v_cndmask_b32_e64 v15, v15, v148, s[34:35]
	v_cmp_gt_f32_e64 s[8:9], v1, v0
	v_cmp_gt_f32_e64 s[10:11], v3, v2
	v_cmp_gt_f32_e64 s[12:13], v5, v4
	v_cmp_gt_f32_e64 s[24:25], v7, v6
	v_cndmask_b32_e64 v40, v0, v1, s[8:9]
	v_cndmask_b32_e64 v44, 0, 1, s[8:9]
	v_cndmask_b32_e64 v141, v8, v9, s[8:9]
	v_cndmask_b32_e64 v41, v2, v3, s[10:11]
	v_cndmask_b32_e64 v45, 2, 3, s[10:11]
	v_cndmask_b32_e64 v142, v10, v11, s[10:11]
	v_cndmask_b32_e64 v42, v4, v5, s[12:13]
	v_cndmask_b32_e64 v46, 4, 5, s[12:13]
	v_cndmask_b32_e64 v143, v12, v13, s[12:13]
	v_cndmask_b32_e64 v43, v6, v7, s[24:25]
	v_cndmask_b32_e64 v47, 6, 7, s[24:25]
	v_cndmask_b32_e64 v144, v14, v15, s[24:25]
	v_cmp_gt_f32_e64 s[8:9], v41, v40
	v_cmp_gt_f32_e64 s[10:11], v43, v42
	s_nop 0
	v_cndmask_b32_e64 v40, v40, v41, s[8:9]
	v_cndmask_b32_e64 v44, v44, v45, s[8:9]
	v_cndmask_b32_e64 v141, v141, v142, s[8:9]
	v_cndmask_b32_e64 v42, v42, v43, s[10:11]
	v_cndmask_b32_e64 v46, v46, v47, s[10:11]
	v_cndmask_b32_e64 v143, v143, v144, s[10:11]
	v_cmp_gt_f32_e64 s[8:9], v42, v40
	s_nop 1
	v_cndmask_b32_e64 v40, v40, v42, s[8:9]
	v_cndmask_b32_e64 v44, v44, v46, s[8:9]
	v_cndmask_b32_e64 v141, v141, v143, s[8:9]
	ds_write_b32 v149, v40 offset:15360
	ds_write_b8 v150, v141 offset:3840
	v_readlane_b32 s20, v255, 5
	v_readlane_b32 s21, v255, 6
	s_waitcnt lgkmcnt(0)
.LBB0_968:
	s_or_b64 exec, exec, s[52:53]
	s_barrier
	s_and_saveexec_b64 s[0:1], s[6:7]
	s_cbranch_execz .LBB0_962
	v_lshlrev_b32_e32 v149, 2, v166
	v_add_u32_e32 v150, 0x24400, v166
	v_add_u32_e32 v149, 0x20400, v149
	ds_read_b32 v0, v149
	ds_read_b32 v1, v149 offset:1024
	ds_read_b32 v2, v149 offset:2048
	ds_read_b32 v3, v149 offset:3072
	ds_read_b32 v4, v149 offset:4096
	ds_read_b32 v5, v149 offset:5120
	ds_read_b32 v6, v149 offset:6144
	ds_read_b32 v7, v149 offset:7168
	ds_read_b32 v8, v149 offset:8192
	ds_read_b32 v9, v149 offset:9216
	ds_read_b32 v10, v149 offset:10240
	ds_read_b32 v11, v149 offset:11264
	ds_read_b32 v12, v149 offset:12288
	ds_read_b32 v13, v149 offset:13312
	ds_read_b32 v14, v149 offset:14336
	ds_read_b32 v15, v149 offset:15360
	ds_read_b32 v27, v149 offset:512
	v_mov_b32_e32 v24, 0
	v_mov_b32_e32 v25, 0
	v_mov_b32_e32 v26, 0xff800000
	s_waitcnt lgkmcnt(0)
; DI void peer_topk_item(const Params& p, int tt128, int head, char* smem) {
;     ...
; #pragma unroll
;     for (int r = 0; r < 16; ++r) {
;       float best = cur[0]; int bi = 0; int bj = pp[0];
; #pragma unroll
;       for (int i = 1; i < 16; ++i) if (cur[i] > best) { best = cur[i]; bi = i; bj = pp[i]; }
;       sel[r] = best;
;       eid[r] = (int)ai[bi] * 128 + (int)bi_[bj];
;       const int nj = bj + 1;
;       const float nv = (nj < 16) ? (av[bi] + bv[nj & 15]) : -INFINITY;
; #pragma unroll
;       for (int i = 0; i < 16; ++i) { cur[i] = (i == bi) ? nv : cur[i]; pp[i] = (i == bi) ? nj : pp[i]; }
;     }
	v_add_f32_e32 v0, v27, v0
	v_add_f32_e32 v1, v27, v1
	v_add_f32_e32 v2, v27, v2
	v_add_f32_e32 v3, v27, v3
	v_add_f32_e32 v4, v27, v4
	v_add_f32_e32 v5, v27, v5
	v_add_f32_e32 v6, v27, v6
	v_add_f32_e32 v7, v27, v7
	v_add_f32_e32 v8, v27, v8
	v_add_f32_e32 v9, v27, v9
	v_add_f32_e32 v10, v27, v10
	v_add_f32_e32 v11, v27, v11
	v_add_f32_e32 v12, v27, v12
	v_add_f32_e32 v13, v27, v13
	v_add_f32_e32 v14, v27, v14
	v_add_f32_e32 v15, v27, v15
	v_cmp_gt_f32_e64 s[8:9], v1, v0
	v_cmp_gt_f32_e64 s[10:11], v3, v2
	v_cmp_gt_f32_e64 s[12:13], v5, v4
	v_cmp_gt_f32_e64 s[24:25], v7, v6
	v_cmp_gt_f32_e64 s[26:27], v9, v8
	v_cmp_gt_f32_e64 s[28:29], v11, v10
	v_cmp_gt_f32_e64 s[30:31], v13, v12
	v_cmp_gt_f32_e64 s[34:35], v15, v14
	v_cndmask_b32_e64 v16, v0, v1, s[8:9]
	v_cndmask_b32_e64 v141, 0, 1, s[8:9]
	v_cndmask_b32_e64 v17, v2, v3, s[10:11]
	v_cndmask_b32_e64 v142, 2, 3, s[10:11]
	v_cndmask_b32_e64 v18, v4, v5, s[12:13]
	v_cndmask_b32_e64 v143, 4, 5, s[12:13]
	v_cndmask_b32_e64 v19, v6, v7, s[24:25]
	v_cndmask_b32_e64 v144, 6, 7, s[24:25]
	v_cndmask_b32_e64 v20, v8, v9, s[26:27]
	v_cndmask_b32_e64 v145, 8, 9, s[26:27]
	v_cndmask_b32_e64 v21, v10, v11, s[28:29]
	v_cndmask_b32_e64 v146, 10, 11, s[28:29]
	v_cndmask_b32_e64 v22, v12, v13, s[30:31]
	v_cndmask_b32_e64 v147, 12, 13, s[30:31]
	v_cndmask_b32_e64 v23, v14, v15, s[34:35]
	v_cndmask_b32_e64 v148, 14, 15, s[34:35]
	v_cmp_gt_f32_e64 s[8:9], v17, v16
	v_cmp_gt_f32_e64 s[10:11], v19, v18
	v_cmp_gt_f32_e64 s[12:13], v21, v20
	v_cmp_gt_f32_e64 s[24:25], v23, v22
	v_cndmask_b32_e64 v16, v16, v17, s[8:9]
	v_cndmask_b32_e64 v141, v141, v142, s[8:9]
	v_cndmask_b32_e64 v18, v18, v19, s[10:11]
	v_cndmask_b32_e64 v143, v143, v144, s[10:11]
	v_cndmask_b32_e64 v20, v20, v21, s[12:13]
	v_cndmask_b32_e64 v145, v145, v146, s[12:13]
	v_cndmask_b32_e64 v22, v22, v23, s[24:25]
	v_cndmask_b32_e64 v147, v147, v148, s[24:25]
	v_cmp_gt_f32_e64 s[8:9], v18, v16
	v_cmp_gt_f32_e64 s[10:11], v22, v20
	s_nop 0
	v_cndmask_b32_e64 v16, v16, v18, s[8:9]
	v_cndmask_b32_e64 v141, v141, v143, s[8:9]
	v_cndmask_b32_e64 v20, v20, v22, s[10:11]
	v_cndmask_b32_e64 v145, v145, v147, s[10:11]
	v_cmp_gt_f32_e64 s[8:9], v20, v16
	s_nop 1
	v_cndmask_b32_e64 v16, v16, v20, s[8:9]
	v_cndmask_b32_e64 v141, v141, v145, s[8:9]
	v_mov_b32_e32 v124, v16
	v_lshl_add_u32 v28, v141, 8, v150
	ds_read_u8 v19, v28
	v_cmp_gt_u32_e64 s[62:63], 8, v141
	v_and_b32_e32 v29, 7, v141
	v_lshlrev_b32_e32 v29, 2, v29
	v_cndmask_b32_e64 v30, v25, v24, s[62:63]
	v_bfe_u32 v31, v30, v29, 4
	v_lshl_add_u32 v52, v31, 8, v150
	ds_read_u8 v21, v52 offset:128
	v_lshl_add_u32 v27, v141, 10, v149
	ds_read_b32 v17, v27
	v_add_u32_e32 v53, 1, v31
	v_and_b32_e32 v27, 15, v53
	v_lshl_add_u32 v27, v27, 10, v149
	ds_read_b32 v18, v27 offset:512
	v_cmp_gt_u32_e64 s[60:61], 15, v31
	v_lshlrev_b32_e64 v28, v29, 1
	s_nop 0
	v_cndmask_b32_e64 v28, 0, v28, s[60:61]
	v_cndmask_b32_e64 v30, 0, v28, s[62:63]
	v_sub_u32_e32 v28, v28, v30
	v_add_u32_e32 v24, v24, v30
	v_add_u32_e32 v25, v25, v28
	v_cmp_eq_u32_e64 s[8:9], 0, v141
	v_cmp_eq_u32_e64 s[10:11], 1, v141
	v_cmp_eq_u32_e64 s[12:13], 2, v141
	v_cmp_eq_u32_e64 s[24:25], 3, v141
	v_cmp_eq_u32_e64 s[26:27], 4, v141
	v_cmp_eq_u32_e64 s[28:29], 5, v141
	v_cmp_eq_u32_e64 s[30:31], 6, v141
	v_cmp_eq_u32_e64 s[34:35], 7, v141
	v_cmp_eq_u32_e64 s[36:37], 8, v141
	v_cmp_eq_u32_e64 s[38:39], 9, v141
	v_cmp_eq_u32_e64 s[40:41], 10, v141
	v_cmp_eq_u32_e64 s[42:43], 11, v141
	v_cmp_eq_u32_e64 s[44:45], 12, v141
	v_cmp_eq_u32_e64 s[46:47], 13, v141
	v_cmp_eq_u32_e64 s[60:61], 14, v141
	v_cmp_eq_u32_e64 s[62:63], 15, v141
	s_waitcnt lgkmcnt(0)
	v_cmp_gt_u32_e64 s[4:5], 16, v53
	v_add_f32_e32 v17, v17, v18
	v_lshl_add_u32 v32, v19, 7, v21
	v_cndmask_b32_e64 v17, v26, v17, s[4:5]
	v_cndmask_b32_e64 v0, v0, v17, s[8:9]
	v_cndmask_b32_e64 v1, v1, v17, s[10:11]
	v_cndmask_b32_e64 v2, v2, v17, s[12:13]
	v_cndmask_b32_e64 v3, v3, v17, s[24:25]
	v_cndmask_b32_e64 v4, v4, v17, s[26:27]
	v_cndmask_b32_e64 v5, v5, v17, s[28:29]
	v_cndmask_b32_e64 v6, v6, v17, s[30:31]
	v_cndmask_b32_e64 v7, v7, v17, s[34:35]
	v_cndmask_b32_e64 v8, v8, v17, s[36:37]
	v_cndmask_b32_e64 v9, v9, v17, s[38:39]
	v_cndmask_b32_e64 v10, v10, v17, s[40:41]
	v_cndmask_b32_e64 v11, v11, v17, s[42:43]
	v_cndmask_b32_e64 v12, v12, v17, s[44:45]
	v_cndmask_b32_e64 v13, v13, v17, s[46:47]
	v_cndmask_b32_e64 v14, v14, v17, s[60:61]
	v_cndmask_b32_e64 v15, v15, v17, s[62:63]
	v_cmp_gt_f32_e64 s[8:9], v1, v0
	v_cmp_gt_f32_e64 s[10:11], v3, v2
	v_cmp_gt_f32_e64 s[12:13], v5, v4
	v_cmp_gt_f32_e64 s[24:25], v7, v6
	v_cmp_gt_f32_e64 s[26:27], v9, v8
	v_cmp_gt_f32_e64 s[28:29], v11, v10
	v_cmp_gt_f32_e64 s[30:31], v13, v12
	v_cmp_gt_f32_e64 s[34:35], v15, v14
	v_cndmask_b32_e64 v16, v0, v1, s[8:9]
	v_cndmask_b32_e64 v141, 0, 1, s[8:9]
	v_cndmask_b32_e64 v17, v2, v3, s[10:11]
	v_cndmask_b32_e64 v142, 2, 3, s[10:11]
	v_cndmask_b32_e64 v18, v4, v5, s[12:13]
	v_cndmask_b32_e64 v143, 4, 5, s[12:13]
	v_cndmask_b32_e64 v19, v6, v7, s[24:25]
	v_cndmask_b32_e64 v144, 6, 7, s[24:25]
	v_cndmask_b32_e64 v20, v8, v9, s[26:27]
	v_cndmask_b32_e64 v145, 8, 9, s[26:27]
	v_cndmask_b32_e64 v21, v10, v11, s[28:29]
	v_cndmask_b32_e64 v146, 10, 11, s[28:29]
	v_cndmask_b32_e64 v22, v12, v13, s[30:31]
	v_cndmask_b32_e64 v147, 12, 13, s[30:31]
	v_cndmask_b32_e64 v23, v14, v15, s[34:35]
	v_cndmask_b32_e64 v148, 14, 15, s[34:35]
	v_cmp_gt_f32_e64 s[8:9], v17, v16
	v_cmp_gt_f32_e64 s[10:11], v19, v18
	v_cmp_gt_f32_e64 s[12:13], v21, v20
	v_cmp_gt_f32_e64 s[24:25], v23, v22
	v_cndmask_b32_e64 v16, v16, v17, s[8:9]
	v_cndmask_b32_e64 v141, v141, v142, s[8:9]
	v_cndmask_b32_e64 v18, v18, v19, s[10:11]
; DI void peer_topk_item(const Params& p, int tt128, int head, char* smem) {
;     ...
; #pragma unroll
;     for (int r = 0; r < 16; ++r) {
;       float best = cur[0]; int bi = 0; int bj = pp[0];
; #pragma unroll
;       for (int i = 1; i < 16; ++i) if (cur[i] > best) { best = cur[i]; bi = i; bj = pp[i]; }
;       sel[r] = best;
;       eid[r] = (int)ai[bi] * 128 + (int)bi_[bj];
;       const int nj = bj + 1;
;       const float nv = (nj < 16) ? (av[bi] + bv[nj & 15]) : -INFINITY;
; #pragma unroll
;       for (int i = 0; i < 16; ++i) { cur[i] = (i == bi) ? nv : cur[i]; pp[i] = (i == bi) ? nj : pp[i]; }
;     }
	v_cndmask_b32_e64 v143, v143, v144, s[10:11]
	v_cndmask_b32_e64 v20, v20, v21, s[12:13]
	v_cndmask_b32_e64 v145, v145, v146, s[12:13]
	v_cndmask_b32_e64 v22, v22, v23, s[24:25]
	v_cndmask_b32_e64 v147, v147, v148, s[24:25]
	v_cmp_gt_f32_e64 s[8:9], v18, v16
	v_cmp_gt_f32_e64 s[10:11], v22, v20
	s_nop 0
	v_cndmask_b32_e64 v16, v16, v18, s[8:9]
	v_cndmask_b32_e64 v141, v141, v143, s[8:9]
	v_cndmask_b32_e64 v20, v20, v22, s[10:11]
	v_cndmask_b32_e64 v145, v145, v147, s[10:11]
	v_cmp_gt_f32_e64 s[8:9], v20, v16
	s_nop 1
	v_cndmask_b32_e64 v16, v16, v20, s[8:9]
	v_cndmask_b32_e64 v141, v141, v145, s[8:9]
	v_mov_b32_e32 v125, v16
	v_lshl_add_u32 v28, v141, 8, v150
	ds_read_u8 v19, v28
	v_cmp_gt_u32_e64 s[62:63], 8, v141
	v_and_b32_e32 v29, 7, v141
	v_lshlrev_b32_e32 v29, 2, v29
	v_cndmask_b32_e64 v30, v25, v24, s[62:63]
	v_bfe_u32 v31, v30, v29, 4
	v_lshl_add_u32 v52, v31, 8, v150
	ds_read_u8 v21, v52 offset:128
	v_lshl_add_u32 v27, v141, 10, v149
	ds_read_b32 v17, v27
	v_add_u32_e32 v53, 1, v31
	v_and_b32_e32 v27, 15, v53
	v_lshl_add_u32 v27, v27, 10, v149
	ds_read_b32 v18, v27 offset:512
	v_cmp_gt_u32_e64 s[60:61], 15, v31
	v_lshlrev_b32_e64 v28, v29, 1
	s_nop 0
	v_cndmask_b32_e64 v28, 0, v28, s[60:61]
	v_cndmask_b32_e64 v30, 0, v28, s[62:63]
	v_sub_u32_e32 v28, v28, v30
	v_add_u32_e32 v24, v24, v30
	v_add_u32_e32 v25, v25, v28
	v_cmp_eq_u32_e64 s[8:9], 0, v141
	v_cmp_eq_u32_e64 s[10:11], 1, v141
	v_cmp_eq_u32_e64 s[12:13], 2, v141
	v_cmp_eq_u32_e64 s[24:25], 3, v141
	v_cmp_eq_u32_e64 s[26:27], 4, v141
	v_cmp_eq_u32_e64 s[28:29], 5, v141
	v_cmp_eq_u32_e64 s[30:31], 6, v141
	v_cmp_eq_u32_e64 s[34:35], 7, v141
	v_cmp_eq_u32_e64 s[36:37], 8, v141
	v_cmp_eq_u32_e64 s[38:39], 9, v141
	v_cmp_eq_u32_e64 s[40:41], 10, v141
	v_cmp_eq_u32_e64 s[42:43], 11, v141
	v_cmp_eq_u32_e64 s[44:45], 12, v141
	v_cmp_eq_u32_e64 s[46:47], 13, v141
	v_cmp_eq_u32_e64 s[60:61], 14, v141
	v_cmp_eq_u32_e64 s[62:63], 15, v141
	s_waitcnt lgkmcnt(0)
	v_cmp_gt_u32_e64 s[4:5], 16, v53
	v_add_f32_e32 v17, v17, v18
	v_lshl_add_u32 v33, v19, 7, v21
	v_cndmask_b32_e64 v17, v26, v17, s[4:5]
	v_cndmask_b32_e64 v0, v0, v17, s[8:9]
	v_cndmask_b32_e64 v1, v1, v17, s[10:11]
	v_cndmask_b32_e64 v2, v2, v17, s[12:13]
	v_cndmask_b32_e64 v3, v3, v17, s[24:25]
	v_cndmask_b32_e64 v4, v4, v17, s[26:27]
	v_cndmask_b32_e64 v5, v5, v17, s[28:29]
	v_cndmask_b32_e64 v6, v6, v17, s[30:31]
	v_cndmask_b32_e64 v7, v7, v17, s[34:35]
	v_cndmask_b32_e64 v8, v8, v17, s[36:37]
	v_cndmask_b32_e64 v9, v9, v17, s[38:39]
	v_cndmask_b32_e64 v10, v10, v17, s[40:41]
	v_cndmask_b32_e64 v11, v11, v17, s[42:43]
	v_cndmask_b32_e64 v12, v12, v17, s[44:45]
	v_cndmask_b32_e64 v13, v13, v17, s[46:47]
	v_cndmask_b32_e64 v14, v14, v17, s[60:61]
	v_cndmask_b32_e64 v15, v15, v17, s[62:63]
	v_cmp_gt_f32_e64 s[8:9], v1, v0
	v_cmp_gt_f32_e64 s[10:11], v3, v2
	v_cmp_gt_f32_e64 s[12:13], v5, v4
	v_cmp_gt_f32_e64 s[24:25], v7, v6
	v_cmp_gt_f32_e64 s[26:27], v9, v8
	v_cmp_gt_f32_e64 s[28:29], v11, v10
	v_cmp_gt_f32_e64 s[30:31], v13, v12
	v_cmp_gt_f32_e64 s[34:35], v15, v14
	v_cndmask_b32_e64 v16, v0, v1, s[8:9]
	v_cndmask_b32_e64 v141, 0, 1, s[8:9]
	v_cndmask_b32_e64 v17, v2, v3, s[10:11]
	v_cndmask_b32_e64 v142, 2, 3, s[10:11]
	v_cndmask_b32_e64 v18, v4, v5, s[12:13]
	v_cndmask_b32_e64 v143, 4, 5, s[12:13]
	v_cndmask_b32_e64 v19, v6, v7, s[24:25]
	v_cndmask_b32_e64 v144, 6, 7, s[24:25]
	v_cndmask_b32_e64 v20, v8, v9, s[26:27]
	v_cndmask_b32_e64 v145, 8, 9, s[26:27]
	v_cndmask_b32_e64 v21, v10, v11, s[28:29]
	v_cndmask_b32_e64 v146, 10, 11, s[28:29]
	v_cndmask_b32_e64 v22, v12, v13, s[30:31]
	v_cndmask_b32_e64 v147, 12, 13, s[30:31]
	v_cndmask_b32_e64 v23, v14, v15, s[34:35]
	v_cndmask_b32_e64 v148, 14, 15, s[34:35]
	v_cmp_gt_f32_e64 s[8:9], v17, v16
	v_cmp_gt_f32_e64 s[10:11], v19, v18
	v_cmp_gt_f32_e64 s[12:13], v21, v20
	v_cmp_gt_f32_e64 s[24:25], v23, v22
	v_cndmask_b32_e64 v16, v16, v17, s[8:9]
	v_cndmask_b32_e64 v141, v141, v142, s[8:9]
	v_cndmask_b32_e64 v18, v18, v19, s[10:11]
	v_cndmask_b32_e64 v143, v143, v144, s[10:11]
	v_cndmask_b32_e64 v20, v20, v21, s[12:13]
	v_cndmask_b32_e64 v145, v145, v146, s[12:13]
	v_cndmask_b32_e64 v22, v22, v23, s[24:25]
	v_cndmask_b32_e64 v147, v147, v148, s[24:25]
	v_cmp_gt_f32_e64 s[8:9], v18, v16
	v_cmp_gt_f32_e64 s[10:11], v22, v20
	s_nop 0
	v_cndmask_b32_e64 v16, v16, v18, s[8:9]
	v_cndmask_b32_e64 v141, v141, v143, s[8:9]
	v_cndmask_b32_e64 v20, v20, v22, s[10:11]
	v_cndmask_b32_e64 v145, v145, v147, s[10:11]
	v_cmp_gt_f32_e64 s[8:9], v20, v16
	s_nop 1
	v_cndmask_b32_e64 v16, v16, v20, s[8:9]
	v_cndmask_b32_e64 v141, v141, v145, s[8:9]
	v_mov_b32_e32 v126, v16
	v_lshl_add_u32 v28, v141, 8, v150
	ds_read_u8 v19, v28
	v_cmp_gt_u32_e64 s[62:63], 8, v141
	v_and_b32_e32 v29, 7, v141
	v_lshlrev_b32_e32 v29, 2, v29
	v_cndmask_b32_e64 v30, v25, v24, s[62:63]
	v_bfe_u32 v31, v30, v29, 4
	v_lshl_add_u32 v52, v31, 8, v150
	ds_read_u8 v21, v52 offset:128
	v_lshl_add_u32 v27, v141, 10, v149
	ds_read_b32 v17, v27
	v_add_u32_e32 v53, 1, v31
	v_and_b32_e32 v27, 15, v53
	v_lshl_add_u32 v27, v27, 10, v149
	ds_read_b32 v18, v27 offset:512
	v_cmp_gt_u32_e64 s[60:61], 15, v31
	v_lshlrev_b32_e64 v28, v29, 1
	s_nop 0
	v_cndmask_b32_e64 v28, 0, v28, s[60:61]
	v_cndmask_b32_e64 v30, 0, v28, s[62:63]
	v_sub_u32_e32 v28, v28, v30
	v_add_u32_e32 v24, v24, v30
	v_add_u32_e32 v25, v25, v28
	v_cmp_eq_u32_e64 s[8:9], 0, v141
	v_cmp_eq_u32_e64 s[10:11], 1, v141
	v_cmp_eq_u32_e64 s[12:13], 2, v141
	v_cmp_eq_u32_e64 s[24:25], 3, v141
	v_cmp_eq_u32_e64 s[26:27], 4, v141
	v_cmp_eq_u32_e64 s[28:29], 5, v141
	v_cmp_eq_u32_e64 s[30:31], 6, v141
	v_cmp_eq_u32_e64 s[34:35], 7, v141
	v_cmp_eq_u32_e64 s[36:37], 8, v141
	v_cmp_eq_u32_e64 s[38:39], 9, v141
	v_cmp_eq_u32_e64 s[40:41], 10, v141
	v_cmp_eq_u32_e64 s[42:43], 11, v141
	v_cmp_eq_u32_e64 s[44:45], 12, v141
	v_cmp_eq_u32_e64 s[46:47], 13, v141
	v_cmp_eq_u32_e64 s[60:61], 14, v141
	v_cmp_eq_u32_e64 s[62:63], 15, v141
	s_waitcnt lgkmcnt(0)
; DI void peer_topk_item(const Params& p, int tt128, int head, char* smem) {
;     ...
; #pragma unroll
;     for (int r = 0; r < 16; ++r) {
;       float best = cur[0]; int bi = 0; int bj = pp[0];
; #pragma unroll
;       for (int i = 1; i < 16; ++i) if (cur[i] > best) { best = cur[i]; bi = i; bj = pp[i]; }
;       sel[r] = best;
;       eid[r] = (int)ai[bi] * 128 + (int)bi_[bj];
;       const int nj = bj + 1;
;       const float nv = (nj < 16) ? (av[bi] + bv[nj & 15]) : -INFINITY;
; #pragma unroll
;       for (int i = 0; i < 16; ++i) { cur[i] = (i == bi) ? nv : cur[i]; pp[i] = (i == bi) ? nj : pp[i]; }
;     }
	v_cmp_gt_u32_e64 s[4:5], 16, v53
	v_add_f32_e32 v17, v17, v18
	v_lshl_add_u32 v34, v19, 7, v21
	v_cndmask_b32_e64 v17, v26, v17, s[4:5]
	v_cndmask_b32_e64 v0, v0, v17, s[8:9]
	v_cndmask_b32_e64 v1, v1, v17, s[10:11]
	v_cndmask_b32_e64 v2, v2, v17, s[12:13]
	v_cndmask_b32_e64 v3, v3, v17, s[24:25]
	v_cndmask_b32_e64 v4, v4, v17, s[26:27]
	v_cndmask_b32_e64 v5, v5, v17, s[28:29]
	v_cndmask_b32_e64 v6, v6, v17, s[30:31]
	v_cndmask_b32_e64 v7, v7, v17, s[34:35]
	v_cndmask_b32_e64 v8, v8, v17, s[36:37]
	v_cndmask_b32_e64 v9, v9, v17, s[38:39]
	v_cndmask_b32_e64 v10, v10, v17, s[40:41]
	v_cndmask_b32_e64 v11, v11, v17, s[42:43]
	v_cndmask_b32_e64 v12, v12, v17, s[44:45]
	v_cndmask_b32_e64 v13, v13, v17, s[46:47]
	v_cndmask_b32_e64 v14, v14, v17, s[60:61]
	v_cndmask_b32_e64 v15, v15, v17, s[62:63]
	v_cmp_gt_f32_e64 s[8:9], v1, v0
	v_cmp_gt_f32_e64 s[10:11], v3, v2
	v_cmp_gt_f32_e64 s[12:13], v5, v4
	v_cmp_gt_f32_e64 s[24:25], v7, v6
	v_cmp_gt_f32_e64 s[26:27], v9, v8
	v_cmp_gt_f32_e64 s[28:29], v11, v10
	v_cmp_gt_f32_e64 s[30:31], v13, v12
	v_cmp_gt_f32_e64 s[34:35], v15, v14
	v_cndmask_b32_e64 v16, v0, v1, s[8:9]
	v_cndmask_b32_e64 v141, 0, 1, s[8:9]
	v_cndmask_b32_e64 v17, v2, v3, s[10:11]
	v_cndmask_b32_e64 v142, 2, 3, s[10:11]
	v_cndmask_b32_e64 v18, v4, v5, s[12:13]
	v_cndmask_b32_e64 v143, 4, 5, s[12:13]
	v_cndmask_b32_e64 v19, v6, v7, s[24:25]
	v_cndmask_b32_e64 v144, 6, 7, s[24:25]
	v_cndmask_b32_e64 v20, v8, v9, s[26:27]
	v_cndmask_b32_e64 v145, 8, 9, s[26:27]
	v_cndmask_b32_e64 v21, v10, v11, s[28:29]
	v_cndmask_b32_e64 v146, 10, 11, s[28:29]
	v_cndmask_b32_e64 v22, v12, v13, s[30:31]
	v_cndmask_b32_e64 v147, 12, 13, s[30:31]
	v_cndmask_b32_e64 v23, v14, v15, s[34:35]
	v_cndmask_b32_e64 v148, 14, 15, s[34:35]
	v_cmp_gt_f32_e64 s[8:9], v17, v16
	v_cmp_gt_f32_e64 s[10:11], v19, v18
	v_cmp_gt_f32_e64 s[12:13], v21, v20
	v_cmp_gt_f32_e64 s[24:25], v23, v22
	v_cndmask_b32_e64 v16, v16, v17, s[8:9]
	v_cndmask_b32_e64 v141, v141, v142, s[8:9]
	v_cndmask_b32_e64 v18, v18, v19, s[10:11]
	v_cndmask_b32_e64 v143, v143, v144, s[10:11]
	v_cndmask_b32_e64 v20, v20, v21, s[12:13]
	v_cndmask_b32_e64 v145, v145, v146, s[12:13]
	v_cndmask_b32_e64 v22, v22, v23, s[24:25]
	v_cndmask_b32_e64 v147, v147, v148, s[24:25]
	v_cmp_gt_f32_e64 s[8:9], v18, v16
	v_cmp_gt_f32_e64 s[10:11], v22, v20
	s_nop 0
	v_cndmask_b32_e64 v16, v16, v18, s[8:9]
	v_cndmask_b32_e64 v141, v141, v143, s[8:9]
	v_cndmask_b32_e64 v20, v20, v22, s[10:11]
	v_cndmask_b32_e64 v145, v145, v147, s[10:11]
	v_cmp_gt_f32_e64 s[8:9], v20, v16
	s_nop 1
	v_cndmask_b32_e64 v16, v16, v20, s[8:9]
	v_cndmask_b32_e64 v141, v141, v145, s[8:9]
	v_mov_b32_e32 v127, v16
	v_lshl_add_u32 v28, v141, 8, v150
	ds_read_u8 v19, v28
	v_cmp_gt_u32_e64 s[62:63], 8, v141
	v_and_b32_e32 v29, 7, v141
	v_lshlrev_b32_e32 v29, 2, v29
	v_cndmask_b32_e64 v30, v25, v24, s[62:63]
	v_bfe_u32 v31, v30, v29, 4
	v_lshl_add_u32 v52, v31, 8, v150
	ds_read_u8 v21, v52 offset:128
	v_lshl_add_u32 v27, v141, 10, v149
	ds_read_b32 v17, v27
	v_add_u32_e32 v53, 1, v31
	v_and_b32_e32 v27, 15, v53
	v_lshl_add_u32 v27, v27, 10, v149
	ds_read_b32 v18, v27 offset:512
	v_cmp_gt_u32_e64 s[60:61], 15, v31
	v_lshlrev_b32_e64 v28, v29, 1
	s_nop 0
	v_cndmask_b32_e64 v28, 0, v28, s[60:61]
	v_cndmask_b32_e64 v30, 0, v28, s[62:63]
	v_sub_u32_e32 v28, v28, v30
	v_add_u32_e32 v24, v24, v30
	v_add_u32_e32 v25, v25, v28
	v_cmp_eq_u32_e64 s[8:9], 0, v141
	v_cmp_eq_u32_e64 s[10:11], 1, v141
	v_cmp_eq_u32_e64 s[12:13], 2, v141
	v_cmp_eq_u32_e64 s[24:25], 3, v141
	v_cmp_eq_u32_e64 s[26:27], 4, v141
	v_cmp_eq_u32_e64 s[28:29], 5, v141
	v_cmp_eq_u32_e64 s[30:31], 6, v141
	v_cmp_eq_u32_e64 s[34:35], 7, v141
	v_cmp_eq_u32_e64 s[36:37], 8, v141
	v_cmp_eq_u32_e64 s[38:39], 9, v141
	v_cmp_eq_u32_e64 s[40:41], 10, v141
	v_cmp_eq_u32_e64 s[42:43], 11, v141
	v_cmp_eq_u32_e64 s[44:45], 12, v141
	v_cmp_eq_u32_e64 s[46:47], 13, v141
	v_cmp_eq_u32_e64 s[60:61], 14, v141
	v_cmp_eq_u32_e64 s[62:63], 15, v141
	s_waitcnt lgkmcnt(0)
	v_cmp_gt_u32_e64 s[4:5], 16, v53
	v_add_f32_e32 v17, v17, v18
	v_lshl_add_u32 v35, v19, 7, v21
	v_cndmask_b32_e64 v17, v26, v17, s[4:5]
	v_cndmask_b32_e64 v0, v0, v17, s[8:9]
	v_cndmask_b32_e64 v1, v1, v17, s[10:11]
	v_cndmask_b32_e64 v2, v2, v17, s[12:13]
	v_cndmask_b32_e64 v3, v3, v17, s[24:25]
	v_cndmask_b32_e64 v4, v4, v17, s[26:27]
	v_cndmask_b32_e64 v5, v5, v17, s[28:29]
	v_cndmask_b32_e64 v6, v6, v17, s[30:31]
	v_cndmask_b32_e64 v7, v7, v17, s[34:35]
	v_cndmask_b32_e64 v8, v8, v17, s[36:37]
	v_cndmask_b32_e64 v9, v9, v17, s[38:39]
	v_cndmask_b32_e64 v10, v10, v17, s[40:41]
	v_cndmask_b32_e64 v11, v11, v17, s[42:43]
	v_cndmask_b32_e64 v12, v12, v17, s[44:45]
	v_cndmask_b32_e64 v13, v13, v17, s[46:47]
	v_cndmask_b32_e64 v14, v14, v17, s[60:61]
	v_cndmask_b32_e64 v15, v15, v17, s[62:63]
	v_cmp_gt_f32_e64 s[8:9], v1, v0
	v_cmp_gt_f32_e64 s[10:11], v3, v2
	v_cmp_gt_f32_e64 s[12:13], v5, v4
	v_cmp_gt_f32_e64 s[24:25], v7, v6
	v_cmp_gt_f32_e64 s[26:27], v9, v8
	v_cmp_gt_f32_e64 s[28:29], v11, v10
	v_cmp_gt_f32_e64 s[30:31], v13, v12
	v_cmp_gt_f32_e64 s[34:35], v15, v14
	v_cndmask_b32_e64 v16, v0, v1, s[8:9]
	v_cndmask_b32_e64 v141, 0, 1, s[8:9]
	v_cndmask_b32_e64 v17, v2, v3, s[10:11]
	v_cndmask_b32_e64 v142, 2, 3, s[10:11]
	v_cndmask_b32_e64 v18, v4, v5, s[12:13]
	v_cndmask_b32_e64 v143, 4, 5, s[12:13]
	v_cndmask_b32_e64 v19, v6, v7, s[24:25]
	v_cndmask_b32_e64 v144, 6, 7, s[24:25]
	v_cndmask_b32_e64 v20, v8, v9, s[26:27]
	v_cndmask_b32_e64 v145, 8, 9, s[26:27]
	v_cndmask_b32_e64 v21, v10, v11, s[28:29]
	v_cndmask_b32_e64 v146, 10, 11, s[28:29]
	v_cndmask_b32_e64 v22, v12, v13, s[30:31]
	v_cndmask_b32_e64 v147, 12, 13, s[30:31]
; DI void peer_topk_item(const Params& p, int tt128, int head, char* smem) {
;     ...
; #pragma unroll
;     for (int r = 0; r < 16; ++r) {
;       float best = cur[0]; int bi = 0; int bj = pp[0];
; #pragma unroll
;       for (int i = 1; i < 16; ++i) if (cur[i] > best) { best = cur[i]; bi = i; bj = pp[i]; }
;       sel[r] = best;
;       eid[r] = (int)ai[bi] * 128 + (int)bi_[bj];
;       const int nj = bj + 1;
;       const float nv = (nj < 16) ? (av[bi] + bv[nj & 15]) : -INFINITY;
; #pragma unroll
;       for (int i = 0; i < 16; ++i) { cur[i] = (i == bi) ? nv : cur[i]; pp[i] = (i == bi) ? nj : pp[i]; }
;     }
	v_cndmask_b32_e64 v23, v14, v15, s[34:35]
	v_cndmask_b32_e64 v148, 14, 15, s[34:35]
	v_cmp_gt_f32_e64 s[8:9], v17, v16
	v_cmp_gt_f32_e64 s[10:11], v19, v18
	v_cmp_gt_f32_e64 s[12:13], v21, v20
	v_cmp_gt_f32_e64 s[24:25], v23, v22
	v_cndmask_b32_e64 v16, v16, v17, s[8:9]
	v_cndmask_b32_e64 v141, v141, v142, s[8:9]
	v_cndmask_b32_e64 v18, v18, v19, s[10:11]
	v_cndmask_b32_e64 v143, v143, v144, s[10:11]
	v_cndmask_b32_e64 v20, v20, v21, s[12:13]
	v_cndmask_b32_e64 v145, v145, v146, s[12:13]
	v_cndmask_b32_e64 v22, v22, v23, s[24:25]
	v_cndmask_b32_e64 v147, v147, v148, s[24:25]
	v_cmp_gt_f32_e64 s[8:9], v18, v16
	v_cmp_gt_f32_e64 s[10:11], v22, v20
	s_nop 0
	v_cndmask_b32_e64 v16, v16, v18, s[8:9]
	v_cndmask_b32_e64 v141, v141, v143, s[8:9]
	v_cndmask_b32_e64 v20, v20, v22, s[10:11]
	v_cndmask_b32_e64 v145, v145, v147, s[10:11]
	v_cmp_gt_f32_e64 s[8:9], v20, v16
	s_nop 1
	v_cndmask_b32_e64 v16, v16, v20, s[8:9]
	v_cndmask_b32_e64 v141, v141, v145, s[8:9]
	v_mov_b32_e32 v128, v16
	v_lshl_add_u32 v28, v141, 8, v150
	ds_read_u8 v19, v28
	v_cmp_gt_u32_e64 s[62:63], 8, v141
	v_and_b32_e32 v29, 7, v141
	v_lshlrev_b32_e32 v29, 2, v29
	v_cndmask_b32_e64 v30, v25, v24, s[62:63]
	v_bfe_u32 v31, v30, v29, 4
	v_lshl_add_u32 v52, v31, 8, v150
	ds_read_u8 v21, v52 offset:128
	v_lshl_add_u32 v27, v141, 10, v149
	ds_read_b32 v17, v27
	v_add_u32_e32 v53, 1, v31
	v_and_b32_e32 v27, 15, v53
	v_lshl_add_u32 v27, v27, 10, v149
	ds_read_b32 v18, v27 offset:512
	v_cmp_gt_u32_e64 s[60:61], 15, v31
	v_lshlrev_b32_e64 v28, v29, 1
	s_nop 0
	v_cndmask_b32_e64 v28, 0, v28, s[60:61]
	v_cndmask_b32_e64 v30, 0, v28, s[62:63]
	v_sub_u32_e32 v28, v28, v30
	v_add_u32_e32 v24, v24, v30
	v_add_u32_e32 v25, v25, v28
	v_cmp_eq_u32_e64 s[8:9], 0, v141
	v_cmp_eq_u32_e64 s[10:11], 1, v141
	v_cmp_eq_u32_e64 s[12:13], 2, v141
	v_cmp_eq_u32_e64 s[24:25], 3, v141
	v_cmp_eq_u32_e64 s[26:27], 4, v141
	v_cmp_eq_u32_e64 s[28:29], 5, v141
	v_cmp_eq_u32_e64 s[30:31], 6, v141
	v_cmp_eq_u32_e64 s[34:35], 7, v141
	v_cmp_eq_u32_e64 s[36:37], 8, v141
	v_cmp_eq_u32_e64 s[38:39], 9, v141
	v_cmp_eq_u32_e64 s[40:41], 10, v141
	v_cmp_eq_u32_e64 s[42:43], 11, v141
	v_cmp_eq_u32_e64 s[44:45], 12, v141
	v_cmp_eq_u32_e64 s[46:47], 13, v141
	v_cmp_eq_u32_e64 s[60:61], 14, v141
	v_cmp_eq_u32_e64 s[62:63], 15, v141
	s_waitcnt lgkmcnt(0)
	v_cmp_gt_u32_e64 s[4:5], 16, v53
	v_add_f32_e32 v17, v17, v18
	v_lshl_add_u32 v36, v19, 7, v21
	v_cndmask_b32_e64 v17, v26, v17, s[4:5]
	v_cndmask_b32_e64 v0, v0, v17, s[8:9]
	v_cndmask_b32_e64 v1, v1, v17, s[10:11]
	v_cndmask_b32_e64 v2, v2, v17, s[12:13]
	v_cndmask_b32_e64 v3, v3, v17, s[24:25]
	v_cndmask_b32_e64 v4, v4, v17, s[26:27]
	v_cndmask_b32_e64 v5, v5, v17, s[28:29]
	v_cndmask_b32_e64 v6, v6, v17, s[30:31]
	v_cndmask_b32_e64 v7, v7, v17, s[34:35]
	v_cndmask_b32_e64 v8, v8, v17, s[36:37]
	v_cndmask_b32_e64 v9, v9, v17, s[38:39]
	v_cndmask_b32_e64 v10, v10, v17, s[40:41]
	v_cndmask_b32_e64 v11, v11, v17, s[42:43]
	v_cndmask_b32_e64 v12, v12, v17, s[44:45]
	v_cndmask_b32_e64 v13, v13, v17, s[46:47]
	v_cndmask_b32_e64 v14, v14, v17, s[60:61]
	v_cndmask_b32_e64 v15, v15, v17, s[62:63]
	v_cmp_gt_f32_e64 s[8:9], v1, v0
	v_cmp_gt_f32_e64 s[10:11], v3, v2
	v_cmp_gt_f32_e64 s[12:13], v5, v4
	v_cmp_gt_f32_e64 s[24:25], v7, v6
	v_cmp_gt_f32_e64 s[26:27], v9, v8
	v_cmp_gt_f32_e64 s[28:29], v11, v10
	v_cmp_gt_f32_e64 s[30:31], v13, v12
	v_cmp_gt_f32_e64 s[34:35], v15, v14
	v_cndmask_b32_e64 v16, v0, v1, s[8:9]
	v_cndmask_b32_e64 v141, 0, 1, s[8:9]
	v_cndmask_b32_e64 v17, v2, v3, s[10:11]
	v_cndmask_b32_e64 v142, 2, 3, s[10:11]
	v_cndmask_b32_e64 v18, v4, v5, s[12:13]
	v_cndmask_b32_e64 v143, 4, 5, s[12:13]
	v_cndmask_b32_e64 v19, v6, v7, s[24:25]
	v_cndmask_b32_e64 v144, 6, 7, s[24:25]
	v_cndmask_b32_e64 v20, v8, v9, s[26:27]
	v_cndmask_b32_e64 v145, 8, 9, s[26:27]
	v_cndmask_b32_e64 v21, v10, v11, s[28:29]
	v_cndmask_b32_e64 v146, 10, 11, s[28:29]
	v_cndmask_b32_e64 v22, v12, v13, s[30:31]
	v_cndmask_b32_e64 v147, 12, 13, s[30:31]
	v_cndmask_b32_e64 v23, v14, v15, s[34:35]
	v_cndmask_b32_e64 v148, 14, 15, s[34:35]
	v_cmp_gt_f32_e64 s[8:9], v17, v16
	v_cmp_gt_f32_e64 s[10:11], v19, v18
	v_cmp_gt_f32_e64 s[12:13], v21, v20
	v_cmp_gt_f32_e64 s[24:25], v23, v22
	v_cndmask_b32_e64 v16, v16, v17, s[8:9]
	v_cndmask_b32_e64 v141, v141, v142, s[8:9]
	v_cndmask_b32_e64 v18, v18, v19, s[10:11]
	v_cndmask_b32_e64 v143, v143, v144, s[10:11]
	v_cndmask_b32_e64 v20, v20, v21, s[12:13]
	v_cndmask_b32_e64 v145, v145, v146, s[12:13]
	v_cndmask_b32_e64 v22, v22, v23, s[24:25]
	v_cndmask_b32_e64 v147, v147, v148, s[24:25]
	v_cmp_gt_f32_e64 s[8:9], v18, v16
	v_cmp_gt_f32_e64 s[10:11], v22, v20
	s_nop 0
	v_cndmask_b32_e64 v16, v16, v18, s[8:9]
	v_cndmask_b32_e64 v141, v141, v143, s[8:9]
	v_cndmask_b32_e64 v20, v20, v22, s[10:11]
	v_cndmask_b32_e64 v145, v145, v147, s[10:11]
	v_cmp_gt_f32_e64 s[8:9], v20, v16
	s_nop 1
	v_cndmask_b32_e64 v16, v16, v20, s[8:9]
	v_cndmask_b32_e64 v141, v141, v145, s[8:9]
	v_mov_b32_e32 v129, v16
	v_lshl_add_u32 v28, v141, 8, v150
	ds_read_u8 v19, v28
	v_cmp_gt_u32_e64 s[62:63], 8, v141
	v_and_b32_e32 v29, 7, v141
	v_lshlrev_b32_e32 v29, 2, v29
	v_cndmask_b32_e64 v30, v25, v24, s[62:63]
	v_bfe_u32 v31, v30, v29, 4
	v_lshl_add_u32 v52, v31, 8, v150
	ds_read_u8 v21, v52 offset:128
	v_lshl_add_u32 v27, v141, 10, v149
	ds_read_b32 v17, v27
	v_add_u32_e32 v53, 1, v31
	v_and_b32_e32 v27, 15, v53
	v_lshl_add_u32 v27, v27, 10, v149
	ds_read_b32 v18, v27 offset:512
	v_cmp_gt_u32_e64 s[60:61], 15, v31
	v_lshlrev_b32_e64 v28, v29, 1
	s_nop 0
	v_cndmask_b32_e64 v28, 0, v28, s[60:61]
	v_cndmask_b32_e64 v30, 0, v28, s[62:63]
	v_sub_u32_e32 v28, v28, v30
	v_add_u32_e32 v24, v24, v30
	v_add_u32_e32 v25, v25, v28
	v_cmp_eq_u32_e64 s[8:9], 0, v141
	v_cmp_eq_u32_e64 s[10:11], 1, v141
	v_cmp_eq_u32_e64 s[12:13], 2, v141
	v_cmp_eq_u32_e64 s[24:25], 3, v141
	v_cmp_eq_u32_e64 s[26:27], 4, v141
	v_cmp_eq_u32_e64 s[28:29], 5, v141
	v_cmp_eq_u32_e64 s[30:31], 6, v141
	v_cmp_eq_u32_e64 s[34:35], 7, v141
	v_cmp_eq_u32_e64 s[36:37], 8, v141
	v_cmp_eq_u32_e64 s[38:39], 9, v141
	v_cmp_eq_u32_e64 s[40:41], 10, v141
	v_cmp_eq_u32_e64 s[42:43], 11, v141
	v_cmp_eq_u32_e64 s[44:45], 12, v141
	v_cmp_eq_u32_e64 s[46:47], 13, v141
	v_cmp_eq_u32_e64 s[60:61], 14, v141
	v_cmp_eq_u32_e64 s[62:63], 15, v141
	s_waitcnt lgkmcnt(0)
; DI void peer_topk_item(const Params& p, int tt128, int head, char* smem) {
;     ...
; #pragma unroll
;     for (int r = 0; r < 16; ++r) {
;       float best = cur[0]; int bi = 0; int bj = pp[0];
; #pragma unroll
;       for (int i = 1; i < 16; ++i) if (cur[i] > best) { best = cur[i]; bi = i; bj = pp[i]; }
;       sel[r] = best;
;       eid[r] = (int)ai[bi] * 128 + (int)bi_[bj];
;       const int nj = bj + 1;
;       const float nv = (nj < 16) ? (av[bi] + bv[nj & 15]) : -INFINITY;
; #pragma unroll
;       for (int i = 0; i < 16; ++i) { cur[i] = (i == bi) ? nv : cur[i]; pp[i] = (i == bi) ? nj : pp[i]; }
;     }
	v_cmp_gt_u32_e64 s[4:5], 16, v53
	v_add_f32_e32 v17, v17, v18
	v_lshl_add_u32 v37, v19, 7, v21
	v_cndmask_b32_e64 v17, v26, v17, s[4:5]
	v_cndmask_b32_e64 v0, v0, v17, s[8:9]
	v_cndmask_b32_e64 v1, v1, v17, s[10:11]
	v_cndmask_b32_e64 v2, v2, v17, s[12:13]
	v_cndmask_b32_e64 v3, v3, v17, s[24:25]
	v_cndmask_b32_e64 v4, v4, v17, s[26:27]
	v_cndmask_b32_e64 v5, v5, v17, s[28:29]
	v_cndmask_b32_e64 v6, v6, v17, s[30:31]
	v_cndmask_b32_e64 v7, v7, v17, s[34:35]
	v_cndmask_b32_e64 v8, v8, v17, s[36:37]
	v_cndmask_b32_e64 v9, v9, v17, s[38:39]
	v_cndmask_b32_e64 v10, v10, v17, s[40:41]
	v_cndmask_b32_e64 v11, v11, v17, s[42:43]
	v_cndmask_b32_e64 v12, v12, v17, s[44:45]
	v_cndmask_b32_e64 v13, v13, v17, s[46:47]
	v_cndmask_b32_e64 v14, v14, v17, s[60:61]
	v_cndmask_b32_e64 v15, v15, v17, s[62:63]
	v_cmp_gt_f32_e64 s[8:9], v1, v0
	v_cmp_gt_f32_e64 s[10:11], v3, v2
	v_cmp_gt_f32_e64 s[12:13], v5, v4
	v_cmp_gt_f32_e64 s[24:25], v7, v6
	v_cmp_gt_f32_e64 s[26:27], v9, v8
	v_cmp_gt_f32_e64 s[28:29], v11, v10
	v_cmp_gt_f32_e64 s[30:31], v13, v12
	v_cmp_gt_f32_e64 s[34:35], v15, v14
	v_cndmask_b32_e64 v16, v0, v1, s[8:9]
	v_cndmask_b32_e64 v141, 0, 1, s[8:9]
	v_cndmask_b32_e64 v17, v2, v3, s[10:11]
	v_cndmask_b32_e64 v142, 2, 3, s[10:11]
	v_cndmask_b32_e64 v18, v4, v5, s[12:13]
	v_cndmask_b32_e64 v143, 4, 5, s[12:13]
	v_cndmask_b32_e64 v19, v6, v7, s[24:25]
	v_cndmask_b32_e64 v144, 6, 7, s[24:25]
	v_cndmask_b32_e64 v20, v8, v9, s[26:27]
	v_cndmask_b32_e64 v145, 8, 9, s[26:27]
	v_cndmask_b32_e64 v21, v10, v11, s[28:29]
	v_cndmask_b32_e64 v146, 10, 11, s[28:29]
	v_cndmask_b32_e64 v22, v12, v13, s[30:31]
	v_cndmask_b32_e64 v147, 12, 13, s[30:31]
	v_cndmask_b32_e64 v23, v14, v15, s[34:35]
	v_cndmask_b32_e64 v148, 14, 15, s[34:35]
	v_cmp_gt_f32_e64 s[8:9], v17, v16
	v_cmp_gt_f32_e64 s[10:11], v19, v18
	v_cmp_gt_f32_e64 s[12:13], v21, v20
	v_cmp_gt_f32_e64 s[24:25], v23, v22
	v_cndmask_b32_e64 v16, v16, v17, s[8:9]
	v_cndmask_b32_e64 v141, v141, v142, s[8:9]
	v_cndmask_b32_e64 v18, v18, v19, s[10:11]
	v_cndmask_b32_e64 v143, v143, v144, s[10:11]
	v_cndmask_b32_e64 v20, v20, v21, s[12:13]
	v_cndmask_b32_e64 v145, v145, v146, s[12:13]
	v_cndmask_b32_e64 v22, v22, v23, s[24:25]
	v_cndmask_b32_e64 v147, v147, v148, s[24:25]
	v_cmp_gt_f32_e64 s[8:9], v18, v16
	v_cmp_gt_f32_e64 s[10:11], v22, v20
	s_nop 0
	v_cndmask_b32_e64 v16, v16, v18, s[8:9]
	v_cndmask_b32_e64 v141, v141, v143, s[8:9]
	v_cndmask_b32_e64 v20, v20, v22, s[10:11]
	v_cndmask_b32_e64 v145, v145, v147, s[10:11]
	v_cmp_gt_f32_e64 s[8:9], v20, v16
	s_nop 1
	v_cndmask_b32_e64 v16, v16, v20, s[8:9]
	v_cndmask_b32_e64 v141, v141, v145, s[8:9]
	v_mov_b32_e32 v130, v16
	v_lshl_add_u32 v28, v141, 8, v150
	ds_read_u8 v19, v28
	v_cmp_gt_u32_e64 s[62:63], 8, v141
	v_and_b32_e32 v29, 7, v141
	v_lshlrev_b32_e32 v29, 2, v29
	v_cndmask_b32_e64 v30, v25, v24, s[62:63]
	v_bfe_u32 v31, v30, v29, 4
	v_lshl_add_u32 v52, v31, 8, v150
	ds_read_u8 v21, v52 offset:128
	v_lshl_add_u32 v27, v141, 10, v149
	ds_read_b32 v17, v27
	v_add_u32_e32 v53, 1, v31
	v_and_b32_e32 v27, 15, v53
	v_lshl_add_u32 v27, v27, 10, v149
	ds_read_b32 v18, v27 offset:512
	v_cmp_gt_u32_e64 s[60:61], 15, v31
	v_lshlrev_b32_e64 v28, v29, 1
	s_nop 0
	v_cndmask_b32_e64 v28, 0, v28, s[60:61]
	v_cndmask_b32_e64 v30, 0, v28, s[62:63]
	v_sub_u32_e32 v28, v28, v30
	v_add_u32_e32 v24, v24, v30
	v_add_u32_e32 v25, v25, v28
	v_cmp_eq_u32_e64 s[8:9], 0, v141
	v_cmp_eq_u32_e64 s[10:11], 1, v141
	v_cmp_eq_u32_e64 s[12:13], 2, v141
	v_cmp_eq_u32_e64 s[24:25], 3, v141
	v_cmp_eq_u32_e64 s[26:27], 4, v141
	v_cmp_eq_u32_e64 s[28:29], 5, v141
	v_cmp_eq_u32_e64 s[30:31], 6, v141
	v_cmp_eq_u32_e64 s[34:35], 7, v141
	v_cmp_eq_u32_e64 s[36:37], 8, v141
	v_cmp_eq_u32_e64 s[38:39], 9, v141
	v_cmp_eq_u32_e64 s[40:41], 10, v141
	v_cmp_eq_u32_e64 s[42:43], 11, v141
	v_cmp_eq_u32_e64 s[44:45], 12, v141
	v_cmp_eq_u32_e64 s[46:47], 13, v141
	v_cmp_eq_u32_e64 s[60:61], 14, v141
	v_cmp_eq_u32_e64 s[62:63], 15, v141
	s_waitcnt lgkmcnt(0)
	v_cmp_gt_u32_e64 s[4:5], 16, v53
	v_add_f32_e32 v17, v17, v18
	v_lshl_add_u32 v38, v19, 7, v21
	v_cndmask_b32_e64 v17, v26, v17, s[4:5]
	v_cndmask_b32_e64 v0, v0, v17, s[8:9]
	v_cndmask_b32_e64 v1, v1, v17, s[10:11]
	v_cndmask_b32_e64 v2, v2, v17, s[12:13]
	v_cndmask_b32_e64 v3, v3, v17, s[24:25]
	v_cndmask_b32_e64 v4, v4, v17, s[26:27]
	v_cndmask_b32_e64 v5, v5, v17, s[28:29]
	v_cndmask_b32_e64 v6, v6, v17, s[30:31]
	v_cndmask_b32_e64 v7, v7, v17, s[34:35]
	v_cndmask_b32_e64 v8, v8, v17, s[36:37]
	v_cndmask_b32_e64 v9, v9, v17, s[38:39]
	v_cndmask_b32_e64 v10, v10, v17, s[40:41]
	v_cndmask_b32_e64 v11, v11, v17, s[42:43]
	v_cndmask_b32_e64 v12, v12, v17, s[44:45]
	v_cndmask_b32_e64 v13, v13, v17, s[46:47]
	v_cndmask_b32_e64 v14, v14, v17, s[60:61]
	v_cndmask_b32_e64 v15, v15, v17, s[62:63]
	v_cmp_gt_f32_e64 s[8:9], v1, v0
	v_cmp_gt_f32_e64 s[10:11], v3, v2
	v_cmp_gt_f32_e64 s[12:13], v5, v4
	v_cmp_gt_f32_e64 s[24:25], v7, v6
	v_cmp_gt_f32_e64 s[26:27], v9, v8
	v_cmp_gt_f32_e64 s[28:29], v11, v10
	v_cmp_gt_f32_e64 s[30:31], v13, v12
	v_cmp_gt_f32_e64 s[34:35], v15, v14
	v_cndmask_b32_e64 v16, v0, v1, s[8:9]
	v_cndmask_b32_e64 v141, 0, 1, s[8:9]
	v_cndmask_b32_e64 v17, v2, v3, s[10:11]
	v_cndmask_b32_e64 v142, 2, 3, s[10:11]
	v_cndmask_b32_e64 v18, v4, v5, s[12:13]
	v_cndmask_b32_e64 v143, 4, 5, s[12:13]
	v_cndmask_b32_e64 v19, v6, v7, s[24:25]
	v_cndmask_b32_e64 v144, 6, 7, s[24:25]
	v_cndmask_b32_e64 v20, v8, v9, s[26:27]
	v_cndmask_b32_e64 v145, 8, 9, s[26:27]
	v_cndmask_b32_e64 v21, v10, v11, s[28:29]
	v_cndmask_b32_e64 v146, 10, 11, s[28:29]
	v_cndmask_b32_e64 v22, v12, v13, s[30:31]
	v_cndmask_b32_e64 v147, 12, 13, s[30:31]
; DI void peer_topk_item(const Params& p, int tt128, int head, char* smem) {
;     ...
; #pragma unroll
;     for (int r = 0; r < 16; ++r) {
;       float best = cur[0]; int bi = 0; int bj = pp[0];
; #pragma unroll
;       for (int i = 1; i < 16; ++i) if (cur[i] > best) { best = cur[i]; bi = i; bj = pp[i]; }
;       sel[r] = best;
;       eid[r] = (int)ai[bi] * 128 + (int)bi_[bj];
;       const int nj = bj + 1;
;       const float nv = (nj < 16) ? (av[bi] + bv[nj & 15]) : -INFINITY;
; #pragma unroll
;       for (int i = 0; i < 16; ++i) { cur[i] = (i == bi) ? nv : cur[i]; pp[i] = (i == bi) ? nj : pp[i]; }
;     }
	v_cndmask_b32_e64 v23, v14, v15, s[34:35]
	v_cndmask_b32_e64 v148, 14, 15, s[34:35]
	v_cmp_gt_f32_e64 s[8:9], v17, v16
	v_cmp_gt_f32_e64 s[10:11], v19, v18
	v_cmp_gt_f32_e64 s[12:13], v21, v20
	v_cmp_gt_f32_e64 s[24:25], v23, v22
	v_cndmask_b32_e64 v16, v16, v17, s[8:9]
	v_cndmask_b32_e64 v141, v141, v142, s[8:9]
	v_cndmask_b32_e64 v18, v18, v19, s[10:11]
	v_cndmask_b32_e64 v143, v143, v144, s[10:11]
	v_cndmask_b32_e64 v20, v20, v21, s[12:13]
	v_cndmask_b32_e64 v145, v145, v146, s[12:13]
	v_cndmask_b32_e64 v22, v22, v23, s[24:25]
	v_cndmask_b32_e64 v147, v147, v148, s[24:25]
	v_cmp_gt_f32_e64 s[8:9], v18, v16
	v_cmp_gt_f32_e64 s[10:11], v22, v20
	s_nop 0
	v_cndmask_b32_e64 v16, v16, v18, s[8:9]
	v_cndmask_b32_e64 v141, v141, v143, s[8:9]
	v_cndmask_b32_e64 v20, v20, v22, s[10:11]
	v_cndmask_b32_e64 v145, v145, v147, s[10:11]
	v_cmp_gt_f32_e64 s[8:9], v20, v16
	s_nop 1
	v_cndmask_b32_e64 v16, v16, v20, s[8:9]
	v_cndmask_b32_e64 v141, v141, v145, s[8:9]
	v_mov_b32_e32 v131, v16
	v_lshl_add_u32 v28, v141, 8, v150
	ds_read_u8 v19, v28
	v_cmp_gt_u32_e64 s[62:63], 8, v141
	v_and_b32_e32 v29, 7, v141
	v_lshlrev_b32_e32 v29, 2, v29
	v_cndmask_b32_e64 v30, v25, v24, s[62:63]
	v_bfe_u32 v31, v30, v29, 4
	v_lshl_add_u32 v52, v31, 8, v150
	ds_read_u8 v21, v52 offset:128
	v_lshl_add_u32 v27, v141, 10, v149
	ds_read_b32 v17, v27
	v_add_u32_e32 v53, 1, v31
	v_and_b32_e32 v27, 15, v53
	v_lshl_add_u32 v27, v27, 10, v149
	ds_read_b32 v18, v27 offset:512
	v_cmp_gt_u32_e64 s[60:61], 15, v31
	v_lshlrev_b32_e64 v28, v29, 1
	s_nop 0
	v_cndmask_b32_e64 v28, 0, v28, s[60:61]
	v_cndmask_b32_e64 v30, 0, v28, s[62:63]
	v_sub_u32_e32 v28, v28, v30
	v_add_u32_e32 v24, v24, v30
	v_add_u32_e32 v25, v25, v28
	v_cmp_eq_u32_e64 s[8:9], 0, v141
	v_cmp_eq_u32_e64 s[10:11], 1, v141
	v_cmp_eq_u32_e64 s[12:13], 2, v141
	v_cmp_eq_u32_e64 s[24:25], 3, v141
	v_cmp_eq_u32_e64 s[26:27], 4, v141
	v_cmp_eq_u32_e64 s[28:29], 5, v141
	v_cmp_eq_u32_e64 s[30:31], 6, v141
	v_cmp_eq_u32_e64 s[34:35], 7, v141
	v_cmp_eq_u32_e64 s[36:37], 8, v141
	v_cmp_eq_u32_e64 s[38:39], 9, v141
	v_cmp_eq_u32_e64 s[40:41], 10, v141
	v_cmp_eq_u32_e64 s[42:43], 11, v141
	v_cmp_eq_u32_e64 s[44:45], 12, v141
	v_cmp_eq_u32_e64 s[46:47], 13, v141
	v_cmp_eq_u32_e64 s[60:61], 14, v141
	v_cmp_eq_u32_e64 s[62:63], 15, v141
	s_waitcnt lgkmcnt(0)
	v_cmp_gt_u32_e64 s[4:5], 16, v53
	v_add_f32_e32 v17, v17, v18
	v_lshl_add_u32 v39, v19, 7, v21
	v_cndmask_b32_e64 v17, v26, v17, s[4:5]
	v_cndmask_b32_e64 v0, v0, v17, s[8:9]
	v_cndmask_b32_e64 v1, v1, v17, s[10:11]
	v_cndmask_b32_e64 v2, v2, v17, s[12:13]
	v_cndmask_b32_e64 v3, v3, v17, s[24:25]
	v_cndmask_b32_e64 v4, v4, v17, s[26:27]
	v_cndmask_b32_e64 v5, v5, v17, s[28:29]
	v_cndmask_b32_e64 v6, v6, v17, s[30:31]
	v_cndmask_b32_e64 v7, v7, v17, s[34:35]
	v_cndmask_b32_e64 v8, v8, v17, s[36:37]
	v_cndmask_b32_e64 v9, v9, v17, s[38:39]
	v_cndmask_b32_e64 v10, v10, v17, s[40:41]
	v_cndmask_b32_e64 v11, v11, v17, s[42:43]
	v_cndmask_b32_e64 v12, v12, v17, s[44:45]
	v_cndmask_b32_e64 v13, v13, v17, s[46:47]
	v_cndmask_b32_e64 v14, v14, v17, s[60:61]
	v_cndmask_b32_e64 v15, v15, v17, s[62:63]
	v_cmp_gt_f32_e64 s[8:9], v1, v0
	v_cmp_gt_f32_e64 s[10:11], v3, v2
	v_cmp_gt_f32_e64 s[12:13], v5, v4
	v_cmp_gt_f32_e64 s[24:25], v7, v6
	v_cmp_gt_f32_e64 s[26:27], v9, v8
	v_cmp_gt_f32_e64 s[28:29], v11, v10
	v_cmp_gt_f32_e64 s[30:31], v13, v12
	v_cmp_gt_f32_e64 s[34:35], v15, v14
	v_cndmask_b32_e64 v16, v0, v1, s[8:9]
	v_cndmask_b32_e64 v141, 0, 1, s[8:9]
	v_cndmask_b32_e64 v17, v2, v3, s[10:11]
	v_cndmask_b32_e64 v142, 2, 3, s[10:11]
	v_cndmask_b32_e64 v18, v4, v5, s[12:13]
	v_cndmask_b32_e64 v143, 4, 5, s[12:13]
	v_cndmask_b32_e64 v19, v6, v7, s[24:25]
	v_cndmask_b32_e64 v144, 6, 7, s[24:25]
	v_cndmask_b32_e64 v20, v8, v9, s[26:27]
	v_cndmask_b32_e64 v145, 8, 9, s[26:27]
	v_cndmask_b32_e64 v21, v10, v11, s[28:29]
	v_cndmask_b32_e64 v146, 10, 11, s[28:29]
	v_cndmask_b32_e64 v22, v12, v13, s[30:31]
	v_cndmask_b32_e64 v147, 12, 13, s[30:31]
	v_cndmask_b32_e64 v23, v14, v15, s[34:35]
	v_cndmask_b32_e64 v148, 14, 15, s[34:35]
	v_cmp_gt_f32_e64 s[8:9], v17, v16
	v_cmp_gt_f32_e64 s[10:11], v19, v18
	v_cmp_gt_f32_e64 s[12:13], v21, v20
	v_cmp_gt_f32_e64 s[24:25], v23, v22
	v_cndmask_b32_e64 v16, v16, v17, s[8:9]
	v_cndmask_b32_e64 v141, v141, v142, s[8:9]
	v_cndmask_b32_e64 v18, v18, v19, s[10:11]
	v_cndmask_b32_e64 v143, v143, v144, s[10:11]
	v_cndmask_b32_e64 v20, v20, v21, s[12:13]
	v_cndmask_b32_e64 v145, v145, v146, s[12:13]
	v_cndmask_b32_e64 v22, v22, v23, s[24:25]
	v_cndmask_b32_e64 v147, v147, v148, s[24:25]
	v_cmp_gt_f32_e64 s[8:9], v18, v16
	v_cmp_gt_f32_e64 s[10:11], v22, v20
	s_nop 0
	v_cndmask_b32_e64 v16, v16, v18, s[8:9]
	v_cndmask_b32_e64 v141, v141, v143, s[8:9]
	v_cndmask_b32_e64 v20, v20, v22, s[10:11]
	v_cndmask_b32_e64 v145, v145, v147, s[10:11]
	v_cmp_gt_f32_e64 s[8:9], v20, v16
	s_nop 1
	v_cndmask_b32_e64 v16, v16, v20, s[8:9]
	v_cndmask_b32_e64 v141, v141, v145, s[8:9]
	v_mov_b32_e32 v132, v16
	v_lshl_add_u32 v28, v141, 8, v150
	ds_read_u8 v19, v28
	v_cmp_gt_u32_e64 s[62:63], 8, v141
	v_and_b32_e32 v29, 7, v141
	v_lshlrev_b32_e32 v29, 2, v29
	v_cndmask_b32_e64 v30, v25, v24, s[62:63]
	v_bfe_u32 v31, v30, v29, 4
	v_lshl_add_u32 v52, v31, 8, v150
	ds_read_u8 v21, v52 offset:128
	v_lshl_add_u32 v27, v141, 10, v149
	ds_read_b32 v17, v27
	v_add_u32_e32 v53, 1, v31
	v_and_b32_e32 v27, 15, v53
	v_lshl_add_u32 v27, v27, 10, v149
	ds_read_b32 v18, v27 offset:512
	v_cmp_gt_u32_e64 s[60:61], 15, v31
	v_lshlrev_b32_e64 v28, v29, 1
	s_nop 0
	v_cndmask_b32_e64 v28, 0, v28, s[60:61]
	v_cndmask_b32_e64 v30, 0, v28, s[62:63]
	v_sub_u32_e32 v28, v28, v30
	v_add_u32_e32 v24, v24, v30
	v_add_u32_e32 v25, v25, v28
	v_cmp_eq_u32_e64 s[8:9], 0, v141
	v_cmp_eq_u32_e64 s[10:11], 1, v141
	v_cmp_eq_u32_e64 s[12:13], 2, v141
	v_cmp_eq_u32_e64 s[24:25], 3, v141
	v_cmp_eq_u32_e64 s[26:27], 4, v141
	v_cmp_eq_u32_e64 s[28:29], 5, v141
	v_cmp_eq_u32_e64 s[30:31], 6, v141
	v_cmp_eq_u32_e64 s[34:35], 7, v141
	v_cmp_eq_u32_e64 s[36:37], 8, v141
	v_cmp_eq_u32_e64 s[38:39], 9, v141
	v_cmp_eq_u32_e64 s[40:41], 10, v141
	v_cmp_eq_u32_e64 s[42:43], 11, v141
	v_cmp_eq_u32_e64 s[44:45], 12, v141
	v_cmp_eq_u32_e64 s[46:47], 13, v141
	v_cmp_eq_u32_e64 s[60:61], 14, v141
	v_cmp_eq_u32_e64 s[62:63], 15, v141
	s_waitcnt lgkmcnt(0)
; DI void peer_topk_item(const Params& p, int tt128, int head, char* smem) {
;     ...
; #pragma unroll
;     for (int r = 0; r < 16; ++r) {
;       float best = cur[0]; int bi = 0; int bj = pp[0];
; #pragma unroll
;       for (int i = 1; i < 16; ++i) if (cur[i] > best) { best = cur[i]; bi = i; bj = pp[i]; }
;       sel[r] = best;
;       eid[r] = (int)ai[bi] * 128 + (int)bi_[bj];
;       const int nj = bj + 1;
;       const float nv = (nj < 16) ? (av[bi] + bv[nj & 15]) : -INFINITY;
; #pragma unroll
;       for (int i = 0; i < 16; ++i) { cur[i] = (i == bi) ? nv : cur[i]; pp[i] = (i == bi) ? nj : pp[i]; }
;     }
	v_cmp_gt_u32_e64 s[4:5], 16, v53
	v_add_f32_e32 v17, v17, v18
	v_lshl_add_u32 v40, v19, 7, v21
	v_cndmask_b32_e64 v17, v26, v17, s[4:5]
	v_cndmask_b32_e64 v0, v0, v17, s[8:9]
	v_cndmask_b32_e64 v1, v1, v17, s[10:11]
	v_cndmask_b32_e64 v2, v2, v17, s[12:13]
	v_cndmask_b32_e64 v3, v3, v17, s[24:25]
	v_cndmask_b32_e64 v4, v4, v17, s[26:27]
	v_cndmask_b32_e64 v5, v5, v17, s[28:29]
	v_cndmask_b32_e64 v6, v6, v17, s[30:31]
	v_cndmask_b32_e64 v7, v7, v17, s[34:35]
	v_cndmask_b32_e64 v8, v8, v17, s[36:37]
	v_cndmask_b32_e64 v9, v9, v17, s[38:39]
	v_cndmask_b32_e64 v10, v10, v17, s[40:41]
	v_cndmask_b32_e64 v11, v11, v17, s[42:43]
	v_cndmask_b32_e64 v12, v12, v17, s[44:45]
	v_cndmask_b32_e64 v13, v13, v17, s[46:47]
	v_cndmask_b32_e64 v14, v14, v17, s[60:61]
	v_cndmask_b32_e64 v15, v15, v17, s[62:63]
	v_cmp_gt_f32_e64 s[8:9], v1, v0
	v_cmp_gt_f32_e64 s[10:11], v3, v2
	v_cmp_gt_f32_e64 s[12:13], v5, v4
	v_cmp_gt_f32_e64 s[24:25], v7, v6
	v_cmp_gt_f32_e64 s[26:27], v9, v8
	v_cmp_gt_f32_e64 s[28:29], v11, v10
	v_cmp_gt_f32_e64 s[30:31], v13, v12
	v_cmp_gt_f32_e64 s[34:35], v15, v14
	v_cndmask_b32_e64 v16, v0, v1, s[8:9]
	v_cndmask_b32_e64 v141, 0, 1, s[8:9]
	v_cndmask_b32_e64 v17, v2, v3, s[10:11]
	v_cndmask_b32_e64 v142, 2, 3, s[10:11]
	v_cndmask_b32_e64 v18, v4, v5, s[12:13]
	v_cndmask_b32_e64 v143, 4, 5, s[12:13]
	v_cndmask_b32_e64 v19, v6, v7, s[24:25]
	v_cndmask_b32_e64 v144, 6, 7, s[24:25]
	v_cndmask_b32_e64 v20, v8, v9, s[26:27]
	v_cndmask_b32_e64 v145, 8, 9, s[26:27]
	v_cndmask_b32_e64 v21, v10, v11, s[28:29]
	v_cndmask_b32_e64 v146, 10, 11, s[28:29]
	v_cndmask_b32_e64 v22, v12, v13, s[30:31]
	v_cndmask_b32_e64 v147, 12, 13, s[30:31]
	v_cndmask_b32_e64 v23, v14, v15, s[34:35]
	v_cndmask_b32_e64 v148, 14, 15, s[34:35]
	v_cmp_gt_f32_e64 s[8:9], v17, v16
	v_cmp_gt_f32_e64 s[10:11], v19, v18
	v_cmp_gt_f32_e64 s[12:13], v21, v20
	v_cmp_gt_f32_e64 s[24:25], v23, v22
	v_cndmask_b32_e64 v16, v16, v17, s[8:9]
	v_cndmask_b32_e64 v141, v141, v142, s[8:9]
	v_cndmask_b32_e64 v18, v18, v19, s[10:11]
	v_cndmask_b32_e64 v143, v143, v144, s[10:11]
	v_cndmask_b32_e64 v20, v20, v21, s[12:13]
	v_cndmask_b32_e64 v145, v145, v146, s[12:13]
	v_cndmask_b32_e64 v22, v22, v23, s[24:25]
	v_cndmask_b32_e64 v147, v147, v148, s[24:25]
	v_cmp_gt_f32_e64 s[8:9], v18, v16
	v_cmp_gt_f32_e64 s[10:11], v22, v20
	s_nop 0
	v_cndmask_b32_e64 v16, v16, v18, s[8:9]
	v_cndmask_b32_e64 v141, v141, v143, s[8:9]
	v_cndmask_b32_e64 v20, v20, v22, s[10:11]
	v_cndmask_b32_e64 v145, v145, v147, s[10:11]
	v_cmp_gt_f32_e64 s[8:9], v20, v16
	s_nop 1
	v_cndmask_b32_e64 v16, v16, v20, s[8:9]
	v_cndmask_b32_e64 v141, v141, v145, s[8:9]
	v_mov_b32_e32 v133, v16
	v_lshl_add_u32 v28, v141, 8, v150
	ds_read_u8 v19, v28
	v_cmp_gt_u32_e64 s[62:63], 8, v141
	v_and_b32_e32 v29, 7, v141
	v_lshlrev_b32_e32 v29, 2, v29
	v_cndmask_b32_e64 v30, v25, v24, s[62:63]
	v_bfe_u32 v31, v30, v29, 4
	v_lshl_add_u32 v52, v31, 8, v150
	ds_read_u8 v21, v52 offset:128
	v_lshl_add_u32 v27, v141, 10, v149
	ds_read_b32 v17, v27
	v_add_u32_e32 v53, 1, v31
	v_and_b32_e32 v27, 15, v53
	v_lshl_add_u32 v27, v27, 10, v149
	ds_read_b32 v18, v27 offset:512
	v_cmp_gt_u32_e64 s[60:61], 15, v31
	v_lshlrev_b32_e64 v28, v29, 1
	s_nop 0
	v_cndmask_b32_e64 v28, 0, v28, s[60:61]
	v_cndmask_b32_e64 v30, 0, v28, s[62:63]
	v_sub_u32_e32 v28, v28, v30
	v_add_u32_e32 v24, v24, v30
	v_add_u32_e32 v25, v25, v28
	v_cmp_eq_u32_e64 s[8:9], 0, v141
	v_cmp_eq_u32_e64 s[10:11], 1, v141
	v_cmp_eq_u32_e64 s[12:13], 2, v141
	v_cmp_eq_u32_e64 s[24:25], 3, v141
	v_cmp_eq_u32_e64 s[26:27], 4, v141
	v_cmp_eq_u32_e64 s[28:29], 5, v141
	v_cmp_eq_u32_e64 s[30:31], 6, v141
	v_cmp_eq_u32_e64 s[34:35], 7, v141
	v_cmp_eq_u32_e64 s[36:37], 8, v141
	v_cmp_eq_u32_e64 s[38:39], 9, v141
	v_cmp_eq_u32_e64 s[40:41], 10, v141
	v_cmp_eq_u32_e64 s[42:43], 11, v141
	v_cmp_eq_u32_e64 s[44:45], 12, v141
	v_cmp_eq_u32_e64 s[46:47], 13, v141
	v_cmp_eq_u32_e64 s[60:61], 14, v141
	v_cmp_eq_u32_e64 s[62:63], 15, v141
	s_waitcnt lgkmcnt(0)
	v_cmp_gt_u32_e64 s[4:5], 16, v53
	v_add_f32_e32 v17, v17, v18
	v_lshl_add_u32 v41, v19, 7, v21
	v_cndmask_b32_e64 v17, v26, v17, s[4:5]
	v_cndmask_b32_e64 v0, v0, v17, s[8:9]
	v_cndmask_b32_e64 v1, v1, v17, s[10:11]
	v_cndmask_b32_e64 v2, v2, v17, s[12:13]
	v_cndmask_b32_e64 v3, v3, v17, s[24:25]
	v_cndmask_b32_e64 v4, v4, v17, s[26:27]
	v_cndmask_b32_e64 v5, v5, v17, s[28:29]
	v_cndmask_b32_e64 v6, v6, v17, s[30:31]
	v_cndmask_b32_e64 v7, v7, v17, s[34:35]
	v_cndmask_b32_e64 v8, v8, v17, s[36:37]
	v_cndmask_b32_e64 v9, v9, v17, s[38:39]
	v_cndmask_b32_e64 v10, v10, v17, s[40:41]
	v_cndmask_b32_e64 v11, v11, v17, s[42:43]
	v_cndmask_b32_e64 v12, v12, v17, s[44:45]
	v_cndmask_b32_e64 v13, v13, v17, s[46:47]
	v_cndmask_b32_e64 v14, v14, v17, s[60:61]
	v_cndmask_b32_e64 v15, v15, v17, s[62:63]
	v_cmp_gt_f32_e64 s[8:9], v1, v0
	v_cmp_gt_f32_e64 s[10:11], v3, v2
	v_cmp_gt_f32_e64 s[12:13], v5, v4
	v_cmp_gt_f32_e64 s[24:25], v7, v6
	v_cmp_gt_f32_e64 s[26:27], v9, v8
	v_cmp_gt_f32_e64 s[28:29], v11, v10
	v_cmp_gt_f32_e64 s[30:31], v13, v12
	v_cmp_gt_f32_e64 s[34:35], v15, v14
	v_cndmask_b32_e64 v16, v0, v1, s[8:9]
	v_cndmask_b32_e64 v141, 0, 1, s[8:9]
	v_cndmask_b32_e64 v17, v2, v3, s[10:11]
	v_cndmask_b32_e64 v142, 2, 3, s[10:11]
	v_cndmask_b32_e64 v18, v4, v5, s[12:13]
	v_cndmask_b32_e64 v143, 4, 5, s[12:13]
	v_cndmask_b32_e64 v19, v6, v7, s[24:25]
	v_cndmask_b32_e64 v144, 6, 7, s[24:25]
	v_cndmask_b32_e64 v20, v8, v9, s[26:27]
	v_cndmask_b32_e64 v145, 8, 9, s[26:27]
	v_cndmask_b32_e64 v21, v10, v11, s[28:29]
	v_cndmask_b32_e64 v146, 10, 11, s[28:29]
	v_cndmask_b32_e64 v22, v12, v13, s[30:31]
	v_cndmask_b32_e64 v147, 12, 13, s[30:31]
; DI void peer_topk_item(const Params& p, int tt128, int head, char* smem) {
;     ...
; #pragma unroll
;     for (int r = 0; r < 16; ++r) {
;       float best = cur[0]; int bi = 0; int bj = pp[0];
; #pragma unroll
;       for (int i = 1; i < 16; ++i) if (cur[i] > best) { best = cur[i]; bi = i; bj = pp[i]; }
;       sel[r] = best;
;       eid[r] = (int)ai[bi] * 128 + (int)bi_[bj];
;       const int nj = bj + 1;
;       const float nv = (nj < 16) ? (av[bi] + bv[nj & 15]) : -INFINITY;
; #pragma unroll
;       for (int i = 0; i < 16; ++i) { cur[i] = (i == bi) ? nv : cur[i]; pp[i] = (i == bi) ? nj : pp[i]; }
;     }
	v_cndmask_b32_e64 v23, v14, v15, s[34:35]
	v_cndmask_b32_e64 v148, 14, 15, s[34:35]
	v_cmp_gt_f32_e64 s[8:9], v17, v16
	v_cmp_gt_f32_e64 s[10:11], v19, v18
	v_cmp_gt_f32_e64 s[12:13], v21, v20
	v_cmp_gt_f32_e64 s[24:25], v23, v22
	v_cndmask_b32_e64 v16, v16, v17, s[8:9]
	v_cndmask_b32_e64 v141, v141, v142, s[8:9]
	v_cndmask_b32_e64 v18, v18, v19, s[10:11]
	v_cndmask_b32_e64 v143, v143, v144, s[10:11]
	v_cndmask_b32_e64 v20, v20, v21, s[12:13]
	v_cndmask_b32_e64 v145, v145, v146, s[12:13]
	v_cndmask_b32_e64 v22, v22, v23, s[24:25]
	v_cndmask_b32_e64 v147, v147, v148, s[24:25]
	v_cmp_gt_f32_e64 s[8:9], v18, v16
	v_cmp_gt_f32_e64 s[10:11], v22, v20
	s_nop 0
	v_cndmask_b32_e64 v16, v16, v18, s[8:9]
	v_cndmask_b32_e64 v141, v141, v143, s[8:9]
	v_cndmask_b32_e64 v20, v20, v22, s[10:11]
	v_cndmask_b32_e64 v145, v145, v147, s[10:11]
	v_cmp_gt_f32_e64 s[8:9], v20, v16
	s_nop 1
	v_cndmask_b32_e64 v16, v16, v20, s[8:9]
	v_cndmask_b32_e64 v141, v141, v145, s[8:9]
	v_mov_b32_e32 v134, v16
	v_lshl_add_u32 v28, v141, 8, v150
	ds_read_u8 v19, v28
	v_cmp_gt_u32_e64 s[62:63], 8, v141
	v_and_b32_e32 v29, 7, v141
	v_lshlrev_b32_e32 v29, 2, v29
	v_cndmask_b32_e64 v30, v25, v24, s[62:63]
	v_bfe_u32 v31, v30, v29, 4
	v_lshl_add_u32 v52, v31, 8, v150
	ds_read_u8 v21, v52 offset:128
	v_lshl_add_u32 v27, v141, 10, v149
	ds_read_b32 v17, v27
	v_add_u32_e32 v53, 1, v31
	v_and_b32_e32 v27, 15, v53
	v_lshl_add_u32 v27, v27, 10, v149
	ds_read_b32 v18, v27 offset:512
	v_cmp_gt_u32_e64 s[60:61], 15, v31
	v_lshlrev_b32_e64 v28, v29, 1
	s_nop 0
	v_cndmask_b32_e64 v28, 0, v28, s[60:61]
	v_cndmask_b32_e64 v30, 0, v28, s[62:63]
	v_sub_u32_e32 v28, v28, v30
	v_add_u32_e32 v24, v24, v30
	v_add_u32_e32 v25, v25, v28
	v_cmp_eq_u32_e64 s[8:9], 0, v141
	v_cmp_eq_u32_e64 s[10:11], 1, v141
	v_cmp_eq_u32_e64 s[12:13], 2, v141
	v_cmp_eq_u32_e64 s[24:25], 3, v141
	v_cmp_eq_u32_e64 s[26:27], 4, v141
	v_cmp_eq_u32_e64 s[28:29], 5, v141
	v_cmp_eq_u32_e64 s[30:31], 6, v141
	v_cmp_eq_u32_e64 s[34:35], 7, v141
	v_cmp_eq_u32_e64 s[36:37], 8, v141
	v_cmp_eq_u32_e64 s[38:39], 9, v141
	v_cmp_eq_u32_e64 s[40:41], 10, v141
	v_cmp_eq_u32_e64 s[42:43], 11, v141
	v_cmp_eq_u32_e64 s[44:45], 12, v141
	v_cmp_eq_u32_e64 s[46:47], 13, v141
	v_cmp_eq_u32_e64 s[60:61], 14, v141
	v_cmp_eq_u32_e64 s[62:63], 15, v141
	s_waitcnt lgkmcnt(0)
	v_cmp_gt_u32_e64 s[4:5], 16, v53
	v_add_f32_e32 v17, v17, v18
	v_lshl_add_u32 v42, v19, 7, v21
	v_cndmask_b32_e64 v17, v26, v17, s[4:5]
	v_cndmask_b32_e64 v0, v0, v17, s[8:9]
	v_cndmask_b32_e64 v1, v1, v17, s[10:11]
	v_cndmask_b32_e64 v2, v2, v17, s[12:13]
	v_cndmask_b32_e64 v3, v3, v17, s[24:25]
	v_cndmask_b32_e64 v4, v4, v17, s[26:27]
	v_cndmask_b32_e64 v5, v5, v17, s[28:29]
	v_cndmask_b32_e64 v6, v6, v17, s[30:31]
	v_cndmask_b32_e64 v7, v7, v17, s[34:35]
	v_cndmask_b32_e64 v8, v8, v17, s[36:37]
	v_cndmask_b32_e64 v9, v9, v17, s[38:39]
	v_cndmask_b32_e64 v10, v10, v17, s[40:41]
	v_cndmask_b32_e64 v11, v11, v17, s[42:43]
	v_cndmask_b32_e64 v12, v12, v17, s[44:45]
	v_cndmask_b32_e64 v13, v13, v17, s[46:47]
	v_cndmask_b32_e64 v14, v14, v17, s[60:61]
	v_cndmask_b32_e64 v15, v15, v17, s[62:63]
	v_cmp_gt_f32_e64 s[8:9], v1, v0
	v_cmp_gt_f32_e64 s[10:11], v3, v2
	v_cmp_gt_f32_e64 s[12:13], v5, v4
	v_cmp_gt_f32_e64 s[24:25], v7, v6
	v_cmp_gt_f32_e64 s[26:27], v9, v8
	v_cmp_gt_f32_e64 s[28:29], v11, v10
	v_cmp_gt_f32_e64 s[30:31], v13, v12
	v_cmp_gt_f32_e64 s[34:35], v15, v14
	v_cndmask_b32_e64 v16, v0, v1, s[8:9]
	v_cndmask_b32_e64 v141, 0, 1, s[8:9]
	v_cndmask_b32_e64 v17, v2, v3, s[10:11]
	v_cndmask_b32_e64 v142, 2, 3, s[10:11]
	v_cndmask_b32_e64 v18, v4, v5, s[12:13]
	v_cndmask_b32_e64 v143, 4, 5, s[12:13]
	v_cndmask_b32_e64 v19, v6, v7, s[24:25]
	v_cndmask_b32_e64 v144, 6, 7, s[24:25]
	v_cndmask_b32_e64 v20, v8, v9, s[26:27]
	v_cndmask_b32_e64 v145, 8, 9, s[26:27]
	v_cndmask_b32_e64 v21, v10, v11, s[28:29]
	v_cndmask_b32_e64 v146, 10, 11, s[28:29]
	v_cndmask_b32_e64 v22, v12, v13, s[30:31]
	v_cndmask_b32_e64 v147, 12, 13, s[30:31]
	v_cndmask_b32_e64 v23, v14, v15, s[34:35]
	v_cndmask_b32_e64 v148, 14, 15, s[34:35]
	v_cmp_gt_f32_e64 s[8:9], v17, v16
	v_cmp_gt_f32_e64 s[10:11], v19, v18
	v_cmp_gt_f32_e64 s[12:13], v21, v20
	v_cmp_gt_f32_e64 s[24:25], v23, v22
	v_cndmask_b32_e64 v16, v16, v17, s[8:9]
	v_cndmask_b32_e64 v141, v141, v142, s[8:9]
	v_cndmask_b32_e64 v18, v18, v19, s[10:11]
	v_cndmask_b32_e64 v143, v143, v144, s[10:11]
	v_cndmask_b32_e64 v20, v20, v21, s[12:13]
	v_cndmask_b32_e64 v145, v145, v146, s[12:13]
	v_cndmask_b32_e64 v22, v22, v23, s[24:25]
	v_cndmask_b32_e64 v147, v147, v148, s[24:25]
	v_cmp_gt_f32_e64 s[8:9], v18, v16
	v_cmp_gt_f32_e64 s[10:11], v22, v20
	s_nop 0
	v_cndmask_b32_e64 v16, v16, v18, s[8:9]
	v_cndmask_b32_e64 v141, v141, v143, s[8:9]
	v_cndmask_b32_e64 v20, v20, v22, s[10:11]
	v_cndmask_b32_e64 v145, v145, v147, s[10:11]
	v_cmp_gt_f32_e64 s[8:9], v20, v16
	s_nop 1
	v_cndmask_b32_e64 v16, v16, v20, s[8:9]
	v_cndmask_b32_e64 v141, v141, v145, s[8:9]
	v_mov_b32_e32 v135, v16
	v_lshl_add_u32 v28, v141, 8, v150
	ds_read_u8 v19, v28
	v_cmp_gt_u32_e64 s[62:63], 8, v141
	v_and_b32_e32 v29, 7, v141
	v_lshlrev_b32_e32 v29, 2, v29
	v_cndmask_b32_e64 v30, v25, v24, s[62:63]
	v_bfe_u32 v31, v30, v29, 4
	v_lshl_add_u32 v52, v31, 8, v150
	ds_read_u8 v21, v52 offset:128
	v_lshl_add_u32 v27, v141, 10, v149
	ds_read_b32 v17, v27
	v_add_u32_e32 v53, 1, v31
	v_and_b32_e32 v27, 15, v53
	v_lshl_add_u32 v27, v27, 10, v149
	ds_read_b32 v18, v27 offset:512
	v_cmp_gt_u32_e64 s[60:61], 15, v31
	v_lshlrev_b32_e64 v28, v29, 1
	s_nop 0
	v_cndmask_b32_e64 v28, 0, v28, s[60:61]
	v_cndmask_b32_e64 v30, 0, v28, s[62:63]
	v_sub_u32_e32 v28, v28, v30
	v_add_u32_e32 v24, v24, v30
	v_add_u32_e32 v25, v25, v28
	v_cmp_eq_u32_e64 s[8:9], 0, v141
	v_cmp_eq_u32_e64 s[10:11], 1, v141
	v_cmp_eq_u32_e64 s[12:13], 2, v141
	v_cmp_eq_u32_e64 s[24:25], 3, v141
	v_cmp_eq_u32_e64 s[26:27], 4, v141
	v_cmp_eq_u32_e64 s[28:29], 5, v141
	v_cmp_eq_u32_e64 s[30:31], 6, v141
	v_cmp_eq_u32_e64 s[34:35], 7, v141
	v_cmp_eq_u32_e64 s[36:37], 8, v141
	v_cmp_eq_u32_e64 s[38:39], 9, v141
	v_cmp_eq_u32_e64 s[40:41], 10, v141
	v_cmp_eq_u32_e64 s[42:43], 11, v141
	v_cmp_eq_u32_e64 s[44:45], 12, v141
	v_cmp_eq_u32_e64 s[46:47], 13, v141
	v_cmp_eq_u32_e64 s[60:61], 14, v141
	v_cmp_eq_u32_e64 s[62:63], 15, v141
	s_waitcnt lgkmcnt(0)
; DI void peer_topk_item(const Params& p, int tt128, int head, char* smem) {
;     ...
; #pragma unroll
;     for (int r = 0; r < 16; ++r) {
;       float best = cur[0]; int bi = 0; int bj = pp[0];
; #pragma unroll
;       for (int i = 1; i < 16; ++i) if (cur[i] > best) { best = cur[i]; bi = i; bj = pp[i]; }
;       sel[r] = best;
;       eid[r] = (int)ai[bi] * 128 + (int)bi_[bj];
;       const int nj = bj + 1;
;       const float nv = (nj < 16) ? (av[bi] + bv[nj & 15]) : -INFINITY;
; #pragma unroll
;       for (int i = 0; i < 16; ++i) { cur[i] = (i == bi) ? nv : cur[i]; pp[i] = (i == bi) ? nj : pp[i]; }
;     }
	v_cmp_gt_u32_e64 s[4:5], 16, v53
	v_add_f32_e32 v17, v17, v18
	v_lshl_add_u32 v43, v19, 7, v21
	v_cndmask_b32_e64 v17, v26, v17, s[4:5]
	v_cndmask_b32_e64 v0, v0, v17, s[8:9]
	v_cndmask_b32_e64 v1, v1, v17, s[10:11]
	v_cndmask_b32_e64 v2, v2, v17, s[12:13]
	v_cndmask_b32_e64 v3, v3, v17, s[24:25]
	v_cndmask_b32_e64 v4, v4, v17, s[26:27]
	v_cndmask_b32_e64 v5, v5, v17, s[28:29]
	v_cndmask_b32_e64 v6, v6, v17, s[30:31]
	v_cndmask_b32_e64 v7, v7, v17, s[34:35]
	v_cndmask_b32_e64 v8, v8, v17, s[36:37]
	v_cndmask_b32_e64 v9, v9, v17, s[38:39]
	v_cndmask_b32_e64 v10, v10, v17, s[40:41]
	v_cndmask_b32_e64 v11, v11, v17, s[42:43]
	v_cndmask_b32_e64 v12, v12, v17, s[44:45]
	v_cndmask_b32_e64 v13, v13, v17, s[46:47]
	v_cndmask_b32_e64 v14, v14, v17, s[60:61]
	v_cndmask_b32_e64 v15, v15, v17, s[62:63]
	v_cmp_gt_f32_e64 s[8:9], v1, v0
	v_cmp_gt_f32_e64 s[10:11], v3, v2
	v_cmp_gt_f32_e64 s[12:13], v5, v4
	v_cmp_gt_f32_e64 s[24:25], v7, v6
	v_cmp_gt_f32_e64 s[26:27], v9, v8
	v_cmp_gt_f32_e64 s[28:29], v11, v10
	v_cmp_gt_f32_e64 s[30:31], v13, v12
	v_cmp_gt_f32_e64 s[34:35], v15, v14
	v_cndmask_b32_e64 v16, v0, v1, s[8:9]
	v_cndmask_b32_e64 v141, 0, 1, s[8:9]
	v_cndmask_b32_e64 v17, v2, v3, s[10:11]
	v_cndmask_b32_e64 v142, 2, 3, s[10:11]
	v_cndmask_b32_e64 v18, v4, v5, s[12:13]
	v_cndmask_b32_e64 v143, 4, 5, s[12:13]
	v_cndmask_b32_e64 v19, v6, v7, s[24:25]
	v_cndmask_b32_e64 v144, 6, 7, s[24:25]
	v_cndmask_b32_e64 v20, v8, v9, s[26:27]
	v_cndmask_b32_e64 v145, 8, 9, s[26:27]
	v_cndmask_b32_e64 v21, v10, v11, s[28:29]
	v_cndmask_b32_e64 v146, 10, 11, s[28:29]
	v_cndmask_b32_e64 v22, v12, v13, s[30:31]
	v_cndmask_b32_e64 v147, 12, 13, s[30:31]
	v_cndmask_b32_e64 v23, v14, v15, s[34:35]
	v_cndmask_b32_e64 v148, 14, 15, s[34:35]
	v_cmp_gt_f32_e64 s[8:9], v17, v16
	v_cmp_gt_f32_e64 s[10:11], v19, v18
	v_cmp_gt_f32_e64 s[12:13], v21, v20
	v_cmp_gt_f32_e64 s[24:25], v23, v22
	v_cndmask_b32_e64 v16, v16, v17, s[8:9]
	v_cndmask_b32_e64 v141, v141, v142, s[8:9]
	v_cndmask_b32_e64 v18, v18, v19, s[10:11]
	v_cndmask_b32_e64 v143, v143, v144, s[10:11]
	v_cndmask_b32_e64 v20, v20, v21, s[12:13]
	v_cndmask_b32_e64 v145, v145, v146, s[12:13]
	v_cndmask_b32_e64 v22, v22, v23, s[24:25]
	v_cndmask_b32_e64 v147, v147, v148, s[24:25]
	v_cmp_gt_f32_e64 s[8:9], v18, v16
	v_cmp_gt_f32_e64 s[10:11], v22, v20
	s_nop 0
	v_cndmask_b32_e64 v16, v16, v18, s[8:9]
	v_cndmask_b32_e64 v141, v141, v143, s[8:9]
	v_cndmask_b32_e64 v20, v20, v22, s[10:11]
	v_cndmask_b32_e64 v145, v145, v147, s[10:11]
	v_cmp_gt_f32_e64 s[8:9], v20, v16
	s_nop 1
	v_cndmask_b32_e64 v16, v16, v20, s[8:9]
	v_cndmask_b32_e64 v141, v141, v145, s[8:9]
	v_mov_b32_e32 v136, v16
	v_lshl_add_u32 v28, v141, 8, v150
	ds_read_u8 v19, v28
	v_cmp_gt_u32_e64 s[62:63], 8, v141
	v_and_b32_e32 v29, 7, v141
	v_lshlrev_b32_e32 v29, 2, v29
	v_cndmask_b32_e64 v30, v25, v24, s[62:63]
	v_bfe_u32 v31, v30, v29, 4
	v_lshl_add_u32 v52, v31, 8, v150
	ds_read_u8 v21, v52 offset:128
	v_lshl_add_u32 v27, v141, 10, v149
	ds_read_b32 v17, v27
	v_add_u32_e32 v53, 1, v31
	v_and_b32_e32 v27, 15, v53
	v_lshl_add_u32 v27, v27, 10, v149
	ds_read_b32 v18, v27 offset:512
	v_cmp_gt_u32_e64 s[60:61], 15, v31
	v_lshlrev_b32_e64 v28, v29, 1
	s_nop 0
	v_cndmask_b32_e64 v28, 0, v28, s[60:61]
	v_cndmask_b32_e64 v30, 0, v28, s[62:63]
	v_sub_u32_e32 v28, v28, v30
	v_add_u32_e32 v24, v24, v30
	v_add_u32_e32 v25, v25, v28
	v_cmp_eq_u32_e64 s[8:9], 0, v141
	v_cmp_eq_u32_e64 s[10:11], 1, v141
	v_cmp_eq_u32_e64 s[12:13], 2, v141
	v_cmp_eq_u32_e64 s[24:25], 3, v141
	v_cmp_eq_u32_e64 s[26:27], 4, v141
	v_cmp_eq_u32_e64 s[28:29], 5, v141
	v_cmp_eq_u32_e64 s[30:31], 6, v141
	v_cmp_eq_u32_e64 s[34:35], 7, v141
	v_cmp_eq_u32_e64 s[36:37], 8, v141
	v_cmp_eq_u32_e64 s[38:39], 9, v141
	v_cmp_eq_u32_e64 s[40:41], 10, v141
	v_cmp_eq_u32_e64 s[42:43], 11, v141
	v_cmp_eq_u32_e64 s[44:45], 12, v141
	v_cmp_eq_u32_e64 s[46:47], 13, v141
	v_cmp_eq_u32_e64 s[60:61], 14, v141
	v_cmp_eq_u32_e64 s[62:63], 15, v141
	s_waitcnt lgkmcnt(0)
	v_cmp_gt_u32_e64 s[4:5], 16, v53
	v_add_f32_e32 v17, v17, v18
	v_lshl_add_u32 v44, v19, 7, v21
	v_cndmask_b32_e64 v17, v26, v17, s[4:5]
	v_cndmask_b32_e64 v0, v0, v17, s[8:9]
	v_cndmask_b32_e64 v1, v1, v17, s[10:11]
	v_cndmask_b32_e64 v2, v2, v17, s[12:13]
	v_cndmask_b32_e64 v3, v3, v17, s[24:25]
	v_cndmask_b32_e64 v4, v4, v17, s[26:27]
	v_cndmask_b32_e64 v5, v5, v17, s[28:29]
	v_cndmask_b32_e64 v6, v6, v17, s[30:31]
	v_cndmask_b32_e64 v7, v7, v17, s[34:35]
	v_cndmask_b32_e64 v8, v8, v17, s[36:37]
	v_cndmask_b32_e64 v9, v9, v17, s[38:39]
	v_cndmask_b32_e64 v10, v10, v17, s[40:41]
	v_cndmask_b32_e64 v11, v11, v17, s[42:43]
	v_cndmask_b32_e64 v12, v12, v17, s[44:45]
	v_cndmask_b32_e64 v13, v13, v17, s[46:47]
	v_cndmask_b32_e64 v14, v14, v17, s[60:61]
	v_cndmask_b32_e64 v15, v15, v17, s[62:63]
	v_cmp_gt_f32_e64 s[8:9], v1, v0
	v_cmp_gt_f32_e64 s[10:11], v3, v2
	v_cmp_gt_f32_e64 s[12:13], v5, v4
	v_cmp_gt_f32_e64 s[24:25], v7, v6
	v_cmp_gt_f32_e64 s[26:27], v9, v8
	v_cmp_gt_f32_e64 s[28:29], v11, v10
	v_cmp_gt_f32_e64 s[30:31], v13, v12
	v_cmp_gt_f32_e64 s[34:35], v15, v14
	v_cndmask_b32_e64 v16, v0, v1, s[8:9]
	v_cndmask_b32_e64 v141, 0, 1, s[8:9]
	v_cndmask_b32_e64 v17, v2, v3, s[10:11]
	v_cndmask_b32_e64 v142, 2, 3, s[10:11]
	v_cndmask_b32_e64 v18, v4, v5, s[12:13]
	v_cndmask_b32_e64 v143, 4, 5, s[12:13]
	v_cndmask_b32_e64 v19, v6, v7, s[24:25]
	v_cndmask_b32_e64 v144, 6, 7, s[24:25]
	v_cndmask_b32_e64 v20, v8, v9, s[26:27]
	v_cndmask_b32_e64 v145, 8, 9, s[26:27]
	v_cndmask_b32_e64 v21, v10, v11, s[28:29]
	v_cndmask_b32_e64 v146, 10, 11, s[28:29]
	v_cndmask_b32_e64 v22, v12, v13, s[30:31]
	v_cndmask_b32_e64 v147, 12, 13, s[30:31]
; DI void peer_topk_item(const Params& p, int tt128, int head, char* smem) {
;     ...
; #pragma unroll
;     for (int r = 0; r < 16; ++r) {
;       float best = cur[0]; int bi = 0; int bj = pp[0];
; #pragma unroll
;       for (int i = 1; i < 16; ++i) if (cur[i] > best) { best = cur[i]; bi = i; bj = pp[i]; }
;       sel[r] = best;
;       eid[r] = (int)ai[bi] * 128 + (int)bi_[bj];
;       const int nj = bj + 1;
;       const float nv = (nj < 16) ? (av[bi] + bv[nj & 15]) : -INFINITY;
; #pragma unroll
;       for (int i = 0; i < 16; ++i) { cur[i] = (i == bi) ? nv : cur[i]; pp[i] = (i == bi) ? nj : pp[i]; }
;     }
	v_cndmask_b32_e64 v23, v14, v15, s[34:35]
	v_cndmask_b32_e64 v148, 14, 15, s[34:35]
	v_cmp_gt_f32_e64 s[8:9], v17, v16
	v_cmp_gt_f32_e64 s[10:11], v19, v18
	v_cmp_gt_f32_e64 s[12:13], v21, v20
	v_cmp_gt_f32_e64 s[24:25], v23, v22
	v_cndmask_b32_e64 v16, v16, v17, s[8:9]
	v_cndmask_b32_e64 v141, v141, v142, s[8:9]
	v_cndmask_b32_e64 v18, v18, v19, s[10:11]
	v_cndmask_b32_e64 v143, v143, v144, s[10:11]
	v_cndmask_b32_e64 v20, v20, v21, s[12:13]
	v_cndmask_b32_e64 v145, v145, v146, s[12:13]
	v_cndmask_b32_e64 v22, v22, v23, s[24:25]
	v_cndmask_b32_e64 v147, v147, v148, s[24:25]
	v_cmp_gt_f32_e64 s[8:9], v18, v16
	v_cmp_gt_f32_e64 s[10:11], v22, v20
	s_nop 0
	v_cndmask_b32_e64 v16, v16, v18, s[8:9]
	v_cndmask_b32_e64 v141, v141, v143, s[8:9]
	v_cndmask_b32_e64 v20, v20, v22, s[10:11]
	v_cndmask_b32_e64 v145, v145, v147, s[10:11]
	v_cmp_gt_f32_e64 s[8:9], v20, v16
	s_nop 1
	v_cndmask_b32_e64 v16, v16, v20, s[8:9]
	v_cndmask_b32_e64 v141, v141, v145, s[8:9]
	v_mov_b32_e32 v137, v16
	v_lshl_add_u32 v28, v141, 8, v150
	ds_read_u8 v19, v28
	v_cmp_gt_u32_e64 s[62:63], 8, v141
	v_and_b32_e32 v29, 7, v141
	v_lshlrev_b32_e32 v29, 2, v29
	v_cndmask_b32_e64 v30, v25, v24, s[62:63]
	v_bfe_u32 v31, v30, v29, 4
	v_lshl_add_u32 v52, v31, 8, v150
	ds_read_u8 v21, v52 offset:128
	v_lshl_add_u32 v27, v141, 10, v149
	ds_read_b32 v17, v27
	v_add_u32_e32 v53, 1, v31
	v_and_b32_e32 v27, 15, v53
	v_lshl_add_u32 v27, v27, 10, v149
	ds_read_b32 v18, v27 offset:512
	v_cmp_gt_u32_e64 s[60:61], 15, v31
	v_lshlrev_b32_e64 v28, v29, 1
	s_nop 0
	v_cndmask_b32_e64 v28, 0, v28, s[60:61]
	v_cndmask_b32_e64 v30, 0, v28, s[62:63]
	v_sub_u32_e32 v28, v28, v30
	v_add_u32_e32 v24, v24, v30
	v_add_u32_e32 v25, v25, v28
	v_cmp_eq_u32_e64 s[8:9], 0, v141
	v_cmp_eq_u32_e64 s[10:11], 1, v141
	v_cmp_eq_u32_e64 s[12:13], 2, v141
	v_cmp_eq_u32_e64 s[24:25], 3, v141
	v_cmp_eq_u32_e64 s[26:27], 4, v141
	v_cmp_eq_u32_e64 s[28:29], 5, v141
	v_cmp_eq_u32_e64 s[30:31], 6, v141
	v_cmp_eq_u32_e64 s[34:35], 7, v141
	v_cmp_eq_u32_e64 s[36:37], 8, v141
	v_cmp_eq_u32_e64 s[38:39], 9, v141
	v_cmp_eq_u32_e64 s[40:41], 10, v141
	v_cmp_eq_u32_e64 s[42:43], 11, v141
	v_cmp_eq_u32_e64 s[44:45], 12, v141
	v_cmp_eq_u32_e64 s[46:47], 13, v141
	v_cmp_eq_u32_e64 s[60:61], 14, v141
	v_cmp_eq_u32_e64 s[62:63], 15, v141
	s_waitcnt lgkmcnt(0)
	v_cmp_gt_u32_e64 s[4:5], 16, v53
	v_add_f32_e32 v17, v17, v18
	v_lshl_add_u32 v45, v19, 7, v21
	v_cndmask_b32_e64 v17, v26, v17, s[4:5]
	v_cndmask_b32_e64 v0, v0, v17, s[8:9]
	v_cndmask_b32_e64 v1, v1, v17, s[10:11]
	v_cndmask_b32_e64 v2, v2, v17, s[12:13]
	v_cndmask_b32_e64 v3, v3, v17, s[24:25]
	v_cndmask_b32_e64 v4, v4, v17, s[26:27]
	v_cndmask_b32_e64 v5, v5, v17, s[28:29]
	v_cndmask_b32_e64 v6, v6, v17, s[30:31]
	v_cndmask_b32_e64 v7, v7, v17, s[34:35]
	v_cndmask_b32_e64 v8, v8, v17, s[36:37]
	v_cndmask_b32_e64 v9, v9, v17, s[38:39]
	v_cndmask_b32_e64 v10, v10, v17, s[40:41]
	v_cndmask_b32_e64 v11, v11, v17, s[42:43]
	v_cndmask_b32_e64 v12, v12, v17, s[44:45]
	v_cndmask_b32_e64 v13, v13, v17, s[46:47]
	v_cndmask_b32_e64 v14, v14, v17, s[60:61]
	v_cndmask_b32_e64 v15, v15, v17, s[62:63]
	v_cmp_gt_f32_e64 s[8:9], v1, v0
	v_cmp_gt_f32_e64 s[10:11], v3, v2
	v_cmp_gt_f32_e64 s[12:13], v5, v4
	v_cmp_gt_f32_e64 s[24:25], v7, v6
	v_cmp_gt_f32_e64 s[26:27], v9, v8
	v_cmp_gt_f32_e64 s[28:29], v11, v10
	v_cmp_gt_f32_e64 s[30:31], v13, v12
	v_cmp_gt_f32_e64 s[34:35], v15, v14
	v_cndmask_b32_e64 v16, v0, v1, s[8:9]
	v_cndmask_b32_e64 v141, 0, 1, s[8:9]
	v_cndmask_b32_e64 v17, v2, v3, s[10:11]
	v_cndmask_b32_e64 v142, 2, 3, s[10:11]
	v_cndmask_b32_e64 v18, v4, v5, s[12:13]
	v_cndmask_b32_e64 v143, 4, 5, s[12:13]
	v_cndmask_b32_e64 v19, v6, v7, s[24:25]
	v_cndmask_b32_e64 v144, 6, 7, s[24:25]
	v_cndmask_b32_e64 v20, v8, v9, s[26:27]
	v_cndmask_b32_e64 v145, 8, 9, s[26:27]
	v_cndmask_b32_e64 v21, v10, v11, s[28:29]
	v_cndmask_b32_e64 v146, 10, 11, s[28:29]
	v_cndmask_b32_e64 v22, v12, v13, s[30:31]
	v_cndmask_b32_e64 v147, 12, 13, s[30:31]
	v_cndmask_b32_e64 v23, v14, v15, s[34:35]
	v_cndmask_b32_e64 v148, 14, 15, s[34:35]
	v_cmp_gt_f32_e64 s[8:9], v17, v16
	v_cmp_gt_f32_e64 s[10:11], v19, v18
	v_cmp_gt_f32_e64 s[12:13], v21, v20
	v_cmp_gt_f32_e64 s[24:25], v23, v22
	v_cndmask_b32_e64 v16, v16, v17, s[8:9]
	v_cndmask_b32_e64 v141, v141, v142, s[8:9]
	v_cndmask_b32_e64 v18, v18, v19, s[10:11]
	v_cndmask_b32_e64 v143, v143, v144, s[10:11]
	v_cndmask_b32_e64 v20, v20, v21, s[12:13]
	v_cndmask_b32_e64 v145, v145, v146, s[12:13]
	v_cndmask_b32_e64 v22, v22, v23, s[24:25]
	v_cndmask_b32_e64 v147, v147, v148, s[24:25]
	v_cmp_gt_f32_e64 s[8:9], v18, v16
	v_cmp_gt_f32_e64 s[10:11], v22, v20
	s_nop 0
	v_cndmask_b32_e64 v16, v16, v18, s[8:9]
	v_cndmask_b32_e64 v141, v141, v143, s[8:9]
	v_cndmask_b32_e64 v20, v20, v22, s[10:11]
	v_cndmask_b32_e64 v145, v145, v147, s[10:11]
	v_cmp_gt_f32_e64 s[8:9], v20, v16
	s_nop 1
	v_cndmask_b32_e64 v16, v16, v20, s[8:9]
	v_cndmask_b32_e64 v141, v141, v145, s[8:9]
	v_mov_b32_e32 v138, v16
	v_lshl_add_u32 v28, v141, 8, v150
	ds_read_u8 v19, v28
	v_cmp_gt_u32_e64 s[62:63], 8, v141
	v_and_b32_e32 v29, 7, v141
	v_lshlrev_b32_e32 v29, 2, v29
	v_cndmask_b32_e64 v30, v25, v24, s[62:63]
	v_bfe_u32 v31, v30, v29, 4
	v_lshl_add_u32 v52, v31, 8, v150
	ds_read_u8 v21, v52 offset:128
	v_lshl_add_u32 v27, v141, 10, v149
	ds_read_b32 v17, v27
	v_add_u32_e32 v53, 1, v31
	v_and_b32_e32 v27, 15, v53
	v_lshl_add_u32 v27, v27, 10, v149
	ds_read_b32 v18, v27 offset:512
	v_cmp_gt_u32_e64 s[60:61], 15, v31
	v_lshlrev_b32_e64 v28, v29, 1
	s_nop 0
	v_cndmask_b32_e64 v28, 0, v28, s[60:61]
	v_cndmask_b32_e64 v30, 0, v28, s[62:63]
	v_sub_u32_e32 v28, v28, v30
	v_add_u32_e32 v24, v24, v30
	v_add_u32_e32 v25, v25, v28
	v_cmp_eq_u32_e64 s[8:9], 0, v141
	v_cmp_eq_u32_e64 s[10:11], 1, v141
	v_cmp_eq_u32_e64 s[12:13], 2, v141
	v_cmp_eq_u32_e64 s[24:25], 3, v141
	v_cmp_eq_u32_e64 s[26:27], 4, v141
	v_cmp_eq_u32_e64 s[28:29], 5, v141
	v_cmp_eq_u32_e64 s[30:31], 6, v141
	v_cmp_eq_u32_e64 s[34:35], 7, v141
	v_cmp_eq_u32_e64 s[36:37], 8, v141
	v_cmp_eq_u32_e64 s[38:39], 9, v141
	v_cmp_eq_u32_e64 s[40:41], 10, v141
	v_cmp_eq_u32_e64 s[42:43], 11, v141
	v_cmp_eq_u32_e64 s[44:45], 12, v141
	v_cmp_eq_u32_e64 s[46:47], 13, v141
	v_cmp_eq_u32_e64 s[60:61], 14, v141
	v_cmp_eq_u32_e64 s[62:63], 15, v141
	s_waitcnt lgkmcnt(0)
; DI void peer_topk_item(const Params& p, int tt128, int head, char* smem) {
;     ...
; #pragma unroll
;     for (int r = 0; r < 16; ++r) {
;       float best = cur[0]; int bi = 0; int bj = pp[0];
; #pragma unroll
;       for (int i = 1; i < 16; ++i) if (cur[i] > best) { best = cur[i]; bi = i; bj = pp[i]; }
;       sel[r] = best;
;       eid[r] = (int)ai[bi] * 128 + (int)bi_[bj];
;       const int nj = bj + 1;
;       const float nv = (nj < 16) ? (av[bi] + bv[nj & 15]) : -INFINITY;
; #pragma unroll
;       for (int i = 0; i < 16; ++i) { cur[i] = (i == bi) ? nv : cur[i]; pp[i] = (i == bi) ? nj : pp[i]; }
;     }
;     float sum = 0.f;
;     const float smax = sel[0];
; #pragma unroll
;     for (int r = 0; r < 16; ++r) { sel[r] = __expf(sel[r] - smax); sum += sel[r]; }
;     const float inv = 1.f / sum;
;     int* eo = (int*)(p.ws + OFF_EIDX) + (size_t)(tok0 + tid) * 128 + head * 16;
;     float* go = (float*)(p.ws + OFF_GATE) + (size_t)(tok0 + tid) * 128 + head * 16;
; #pragma unroll
;     for (int r = 0; r < 16; ++r) { eo[r] = eid[r]; go[r] = sel[r] * inv; }
	v_cmp_gt_u32_e64 s[4:5], 16, v53
	v_add_f32_e32 v17, v17, v18
	v_lshl_add_u32 v46, v19, 7, v21
	v_cndmask_b32_e64 v17, v26, v17, s[4:5]
	v_cndmask_b32_e64 v0, v0, v17, s[8:9]
	v_cndmask_b32_e64 v1, v1, v17, s[10:11]
	v_cndmask_b32_e64 v2, v2, v17, s[12:13]
	v_cndmask_b32_e64 v3, v3, v17, s[24:25]
	v_cndmask_b32_e64 v4, v4, v17, s[26:27]
	v_cndmask_b32_e64 v5, v5, v17, s[28:29]
	v_cndmask_b32_e64 v6, v6, v17, s[30:31]
	v_cndmask_b32_e64 v7, v7, v17, s[34:35]
	v_cndmask_b32_e64 v8, v8, v17, s[36:37]
	v_cndmask_b32_e64 v9, v9, v17, s[38:39]
	v_cndmask_b32_e64 v10, v10, v17, s[40:41]
	v_cndmask_b32_e64 v11, v11, v17, s[42:43]
	v_cndmask_b32_e64 v12, v12, v17, s[44:45]
	v_cndmask_b32_e64 v13, v13, v17, s[46:47]
	v_cndmask_b32_e64 v14, v14, v17, s[60:61]
	v_cndmask_b32_e64 v15, v15, v17, s[62:63]
	v_cmp_gt_f32_e64 s[8:9], v1, v0
	v_cmp_gt_f32_e64 s[10:11], v3, v2
	v_cmp_gt_f32_e64 s[12:13], v5, v4
	v_cmp_gt_f32_e64 s[24:25], v7, v6
	v_cmp_gt_f32_e64 s[26:27], v9, v8
	v_cmp_gt_f32_e64 s[28:29], v11, v10
	v_cmp_gt_f32_e64 s[30:31], v13, v12
	v_cmp_gt_f32_e64 s[34:35], v15, v14
	v_cndmask_b32_e64 v16, v0, v1, s[8:9]
	v_cndmask_b32_e64 v141, 0, 1, s[8:9]
	v_cndmask_b32_e64 v17, v2, v3, s[10:11]
	v_cndmask_b32_e64 v142, 2, 3, s[10:11]
	v_cndmask_b32_e64 v18, v4, v5, s[12:13]
	v_cndmask_b32_e64 v143, 4, 5, s[12:13]
	v_cndmask_b32_e64 v19, v6, v7, s[24:25]
	v_cndmask_b32_e64 v144, 6, 7, s[24:25]
	v_cndmask_b32_e64 v20, v8, v9, s[26:27]
	v_cndmask_b32_e64 v145, 8, 9, s[26:27]
	v_cndmask_b32_e64 v21, v10, v11, s[28:29]
	v_cndmask_b32_e64 v146, 10, 11, s[28:29]
	v_cndmask_b32_e64 v22, v12, v13, s[30:31]
	v_cndmask_b32_e64 v147, 12, 13, s[30:31]
	v_cndmask_b32_e64 v23, v14, v15, s[34:35]
	v_cndmask_b32_e64 v148, 14, 15, s[34:35]
	v_cmp_gt_f32_e64 s[8:9], v17, v16
	v_cmp_gt_f32_e64 s[10:11], v19, v18
	v_cmp_gt_f32_e64 s[12:13], v21, v20
	v_cmp_gt_f32_e64 s[24:25], v23, v22
	v_cndmask_b32_e64 v16, v16, v17, s[8:9]
	v_cndmask_b32_e64 v141, v141, v142, s[8:9]
	v_cndmask_b32_e64 v18, v18, v19, s[10:11]
	v_cndmask_b32_e64 v143, v143, v144, s[10:11]
	v_cndmask_b32_e64 v20, v20, v21, s[12:13]
	v_cndmask_b32_e64 v145, v145, v146, s[12:13]
	v_cndmask_b32_e64 v22, v22, v23, s[24:25]
	v_cndmask_b32_e64 v147, v147, v148, s[24:25]
	v_cmp_gt_f32_e64 s[8:9], v18, v16
	v_cmp_gt_f32_e64 s[10:11], v22, v20
	s_nop 0
	v_cndmask_b32_e64 v16, v16, v18, s[8:9]
	v_cndmask_b32_e64 v141, v141, v143, s[8:9]
	v_cndmask_b32_e64 v20, v20, v22, s[10:11]
	v_cndmask_b32_e64 v145, v145, v147, s[10:11]
	v_cmp_gt_f32_e64 s[8:9], v20, v16
	s_nop 1
	v_cndmask_b32_e64 v16, v16, v20, s[8:9]
	v_cndmask_b32_e64 v141, v141, v145, s[8:9]
	v_mov_b32_e32 v139, v16
	v_lshl_add_u32 v28, v141, 8, v150
	ds_read_u8 v19, v28
	v_cmp_gt_u32_e64 s[62:63], 8, v141
	v_and_b32_e32 v29, 7, v141
	v_lshlrev_b32_e32 v29, 2, v29
	v_cndmask_b32_e64 v30, v25, v24, s[62:63]
	v_bfe_u32 v31, v30, v29, 4
	v_lshl_add_u32 v52, v31, 8, v150
	ds_read_u8 v21, v52 offset:128
	s_waitcnt lgkmcnt(0)
	v_lshl_add_u32 v47, v19, 7, v21
	v_sub_f32_e32 v17, v124, v124
	v_sub_f32_e32 v2, v125, v124
	v_sub_f32_e32 v3, v126, v124
	v_sub_f32_e32 v4, v127, v124
	v_sub_f32_e32 v5, v128, v124
	v_sub_f32_e32 v6, v129, v124
	v_sub_f32_e32 v7, v130, v124
	v_sub_f32_e32 v8, v131, v124
	v_sub_f32_e32 v9, v132, v124
	v_sub_f32_e32 v10, v133, v124
	v_sub_f32_e32 v11, v134, v124
	v_sub_f32_e32 v12, v135, v124
	v_sub_f32_e32 v13, v136, v124
	v_sub_f32_e32 v14, v137, v124
	v_sub_f32_e32 v15, v138, v124
	v_sub_f32_e32 v16, v139, v124
	v_mul_f32_e32 v17, 0x3fb8aa3b, v17
	v_mul_f32_e32 v2, 0x3fb8aa3b, v2
	v_mul_f32_e32 v3, 0x3fb8aa3b, v3
	v_mul_f32_e32 v4, 0x3fb8aa3b, v4
	v_mul_f32_e32 v5, 0x3fb8aa3b, v5
	v_mul_f32_e32 v6, 0x3fb8aa3b, v6
	v_mul_f32_e32 v7, 0x3fb8aa3b, v7
	v_mul_f32_e32 v8, 0x3fb8aa3b, v8
	v_mul_f32_e32 v9, 0x3fb8aa3b, v9
	v_mul_f32_e32 v10, 0x3fb8aa3b, v10
	v_mul_f32_e32 v11, 0x3fb8aa3b, v11
	v_mul_f32_e32 v12, 0x3fb8aa3b, v12
	v_mul_f32_e32 v13, 0x3fb8aa3b, v13
	v_mul_f32_e32 v14, 0x3fb8aa3b, v14
	v_mul_f32_e32 v15, 0x3fb8aa3b, v15
	v_mul_f32_e32 v16, 0x3fb8aa3b, v16
	v_exp_f32_e32 v125, v2
	v_exp_f32_e32 v126, v3
	v_exp_f32_e32 v127, v4
	v_exp_f32_e32 v128, v5
	v_exp_f32_e32 v129, v6
	v_exp_f32_e32 v130, v7
	v_exp_f32_e32 v131, v8
	v_exp_f32_e32 v132, v9
	v_exp_f32_e32 v133, v10
	v_exp_f32_e32 v134, v11
	v_exp_f32_e32 v135, v12
	v_exp_f32_e32 v136, v13
	v_exp_f32_e32 v137, v14
	v_exp_f32_e32 v138, v15
	v_exp_f32_e32 v139, v16
	v_exp_f32_e32 v18, v17
	s_nop 0
	v_mov_b32_e32 v124, v18
	v_add_f32_e32 v0, 0, v18
	v_add_f32_e32 v0, v0, v125
	v_add_f32_e32 v0, v0, v126
	v_add_f32_e32 v0, v0, v127
	v_add_f32_e32 v0, v0, v128
	v_add_f32_e32 v0, v0, v129
	v_add_f32_e32 v0, v0, v130
	v_add_f32_e32 v0, v0, v131
	v_add_f32_e32 v0, v0, v132
	v_add_f32_e32 v0, v0, v133
	v_add_f32_e32 v0, v0, v134
	v_add_f32_e32 v0, v0, v135
	v_add_f32_e32 v0, v0, v136
	v_add_f32_e32 v0, v0, v137
	v_add_f32_e32 v0, v0, v138
	v_add_f32_e32 v0, v0, v139
	v_div_scale_f32 v17, s[8:9], v0, v0, 1.0
	v_rcp_f32_e32 v18, v17
	s_and_b32 s4, s2, 7
	s_lshl_b32 s50, s4, 6
	v_fma_f32 v19, -v17, v18, 1.0
	v_fmac_f32_e32 v18, v19, v18
	v_div_scale_f32 v19, vcc, 1.0, v0, 1.0
	v_mul_f32_e32 v20, v19, v18
	v_fma_f32 v21, -v17, v20, v19
	v_fmac_f32_e32 v20, v21, v18
	v_fma_f32 v17, -v17, v20, v19
	v_div_fmas_f32 v17, v17, v18, v20
	v_div_fixup_f32 v22, v17, v0, 1.0
	v_lshl_or_b32 v16, s33, 7, v166
	v_ashrrev_i32_e32 v17, 31, v16
	v_lshlrev_b64 v[16:17], 9, v[16:17]
	v_lshl_add_u64 v[18:19], s[96:97], 0, v[16:17]
	v_lshl_add_u64 v[18:19], v[18:19], 0, s[50:51]
	v_lshl_add_u64 v[16:17], s[48:49], 0, v[16:17]
	v_lshl_add_u64 v[16:17], v[16:17], 0, s[50:51]
	v_mul_f32_e32 v124, v124, v22
	v_mul_f32_e32 v125, v125, v22
	v_mul_f32_e32 v126, v126, v22
	v_mul_f32_e32 v127, v127, v22
	v_mul_f32_e32 v128, v128, v22
	v_mul_f32_e32 v129, v129, v22
	v_mul_f32_e32 v130, v130, v22
	v_mul_f32_e32 v131, v131, v22
	v_mul_f32_e32 v132, v132, v22
	v_mul_f32_e32 v133, v133, v22
	v_mul_f32_e32 v134, v134, v22
	v_mul_f32_e32 v135, v135, v22
	v_mul_f32_e32 v136, v136, v22
	v_mul_f32_e32 v137, v137, v22
	v_mul_f32_e32 v138, v138, v22
	v_mul_f32_e32 v139, v139, v22
	global_store_dwordx4 v[18:19], v[32:35], off
	global_store_dwordx4 v[18:19], v[36:39], off offset:16
	global_store_dwordx4 v[18:19], v[40:43], off offset:32
	global_store_dwordx4 v[18:19], v[44:47], off offset:48
	global_store_dwordx4 v[16:17], v[124:127], off
	global_store_dwordx4 v[16:17], v[128:131], off offset:16
	global_store_dwordx4 v[16:17], v[132:135], off offset:32
	global_store_dwordx4 v[16:17], v[136:139], off offset:48
	s_branch .LBB0_962
